# GEMM K-loops: LDS-DMA loads take the SGPR base + 32-bit lane offset directly (64-bit VALU address adds removed), on top of v019
# speedup vs baseline: 1.0024x; 1.0024x over previous
; #define PG8_STAGE(bufoff, gbase, voff) do { _Pragma("unroll") for (int _i = 0; _i < 2; ++_i) \
;         __builtin_amdgcn_global_load_lds((const unsigned*)((const char*)(gbase) + (voff)[_i]), (PG8_LAS unsigned*)(lds + (bufoff) + ldsw + _i * 8192), 16, 0, 0); } while (0)
; #define PG8_WAIT_V(n) asm volatile("s_waitcnt vmcnt(" #n ")" ::: "memory")
; #define PG8_BAR __builtin_amdgcn_s_barrier()
; template <class Epi, class Sched, bool ALIGN_EPI = false, bool SP2 = false>
; __device__ __forceinline__ void gemm_phase(PG8_LAS unsigned char* lds, const Gemm g, const Sched& S, const Epi& E) {
;     ...
;     const unsigned ldsw = (unsigned)wid * 1024u;
;     const int aoff = lds_byte(wr * 64 + fr, fq * 8), boff = lds_byte(wc * 32 + fr, fq * 8);
;     ...
;         PG8_STAGE(PG8_SB(1, 0), cB + kstep, voffB); PG8_STAGE(PG8_SA(1, 0), cA + kstep, voffA); PG8_STAGE(PG8_SB(1, 1), cB + hstep + kstep, voffB);
;         PG8_WAIT_V(6); PG8_BAR;
.LBB0_345:
	s_lshl_b32 s6, s6, 5
	s_and_b32 s12, s6, 0x60
	s_mov_b64 s[6:7], 0x80
	s_add_i32 m0, s19, 0x18000
	v_lshl_add_u64 v[8:9], v[8:9], 0, s[6:7]
	s_lshl_b32 s9, s1, 13
	s_lshl_b32 s13, s12, 7
	s_waitcnt vmcnt(2)
	s_barrier
	global_load_lds_dwordx4 v[8:9], off
	v_lshl_add_u64 v[6:7], v[6:7], 0, s[6:7]
	s_add_i32 m0, s19, 0x1a000
	s_add_i32 s31, s19, 0x8000
	s_add_i32 s33, s19, 0xa000
	global_load_lds_dwordx4 v[6:7], off
	v_lshl_add_u64 v[2:3], v[2:3], 0, s[6:7]
	s_mov_b32 m0, s31
	s_add_u32 s10, s22, 0x80080
	global_load_lds_dwordx4 v[2:3], off
	v_lshl_add_u64 v[2:3], v[4:5], 0, s[6:7]
	s_mov_b32 m0, s33
	s_addc_u32 s11, s23, 0
	global_load_lds_dwordx4 v[2:3], off
	s_add_i32 m0, s19, 0x1c000
	s_nop 0
	global_load_lds_dwordx4 v134, s[10:11]
	v_lshl_add_u64 v[2:3], s[10:11], 0, v[130:131]
	s_add_i32 m0, s19, 0x1e000
	s_cmpk_lt_u32 s8, 0x100
	global_load_lds_dwordx4 v130, s[10:11]
	v_bfe_u32 v3, v11, 4, 2
	v_and_b32_e32 v2, 15, v11
	v_lshlrev_b32_e32 v4, 4, v3
	v_lshl_or_b32 v2, v2, 6, v4
	v_lshlrev_b32_e32 v4, 2, v11
	v_and_b32_e32 v4, 32, v4
	v_bitop3_b32 v5, v2, s9, v4 bitop3:0xde
	v_bitop3_b32 v150, v2, s13, v4 bitop3:0xde
	v_bfe_u32 v2, v11, 2, 2
	v_lshl_or_b32 v2, v3, 2, v2
	v_and_b32_e32 v3, 3, v11
	v_lshlrev_b32_e32 v4, 6, v3
	v_lshl_or_b32 v151, v2, 2, v4
	v_lshl_or_b32 v152, s1, 6, v2
	v_lshlrev_b32_e32 v2, 15, v15
	v_and_b32_e32 v2, 0xffff0000, v2
	v_lshl_or_b32 v153, v3, 3, s12
	v_lshl_add_u32 v2, v14, 12, v2
	v_and_b32_e32 v3, 1, v15
	v_lshl_or_b32 v2, v3, 6, v2
	v_lshl_add_u32 v138, v16, 1, v2
	v_lshlrev_b32_e32 v2, 15, v10
	v_and_b32_e32 v2, 0xffff0000, v2
	s_waitcnt vmcnt(6)
	v_lshl_add_u32 v2, v12, 12, v2
	v_and_b32_e32 v3, 1, v10
	s_sext_i32_i16 s42, s0
	s_cselect_b64 s[8:9], -1, 0
	v_readlane_b32 s0, v253, 0
	v_lshl_or_b32 v2, v3, 6, v2
	s_add_i32 s35, 0, 0x10000
	s_add_i32 s38, 0, 0x14000
	s_ashr_i32 s34, s0, 31
	v_mov_b32_e32 v139, v135
	v_lshl_add_u32 v140, v13, 1, v2
	v_mov_b32_e32 v141, v135
	v_mov_b64_e32 v[142:143], 0xb00
	v_mov_b64_e32 v[144:145], 0xaff
	v_add_u32_e32 v154, s35, v150
	v_add_u32_e32 v155, s38, v150
	v_add_u32_e32 v156, 0, v5
	s_movk_i32 s39, 0x2c00
	s_barrier
	v_readlane_b32 s1, v253, 1
	s_branch .LBB0_348

; #define PG8_STAGE(bufoff, gbase, voff) do { _Pragma("unroll") for (int _i = 0; _i < 2; ++_i) \
;         __builtin_amdgcn_global_load_lds((const unsigned*)((const char*)(gbase) + (voff)[_i]), (PG8_LAS unsigned*)(lds + (bufoff) + ldsw + _i * 8192), 16, 0, 0); } while (0)
; #define PG8_LDA(dst, b, h) do { _Pragma("unroll") for (int m = 0; m < 4; ++m) _Pragma("unroll") for (int k = 0; k < 2; ++k) dst[m][k] = *(const PG8_LAS bf16x8*)(lds + PG8_SA(b, h) + aoff + m * 2048 + k * 1024); } while (0)
; #define PG8_LDB(dst, b, h) do { _Pragma("unroll") for (int n = 0; n < 2; ++n) _Pragma("unroll") for (int k = 0; k < 2; ++k) dst[n][k] = *(const PG8_LAS bf16x8*)(lds + PG8_SB(b, h) + boff + n * 2048 + k * 1024); } while (0)
; #define PG8_MMA(ai, bj, At, Bt) do { __builtin_amdgcn_s_setprio(1); _Pragma("unroll") for (int m = 0; m < 4; ++m) _Pragma("unroll") for (int n = 0; n < 2; ++n) _Pragma("unroll") for (int k = 0; k < 2; ++k) \
;         acc[ai][bj][m][n] = __builtin_amdgcn_mfma_f32_16x16x32_bf16(Bt[n][k], At[m][k], acc[ai][bj][m][n], 0, 0, 0); __builtin_amdgcn_s_setprio(0); } while (0)
; #define PG8_WAIT_V(n) asm volatile("s_waitcnt vmcnt(" #n ")" ::: "memory")
; #define PG8_WAIT_L(n) asm volatile("s_waitcnt lgkmcnt(" #n ")" ::: "memory")
; #define PG8_BAR __builtin_amdgcn_s_barrier()
; #define PG8_SCHED __builtin_amdgcn_sched_barrier(0)
; template <class Epi, class Sched, bool ALIGN_EPI = false, bool SP2 = false>
; __device__ __forceinline__ void gemm_phase(PG8_LAS unsigned char* lds, const Gemm g, const Sched& S, const Epi& E) {
;     ...
;             PG8_LDB(B0, 0, 0); PG8_LDB(B1, 0, 1); PG8_SCHED; PG8_LDA(At, 0, 0); PG8_STAGE(PG8_SA(1, 1), a1 + hstep, voffA);
;             PG8_WAIT_V(8); PG8_WAIT_L(0); PG8_BAR; PG8_MMA(0, 0, At, B0); PG8_MMA(0, 1, At, B1); PG8_BAR; PG8_SCHED;
;             PG8_LDA(At, 0, 1); PG8_STAGE(PG8_SB(0, 0), b2, voffB); PG8_STAGE(PG8_SB(0, 1), b2 + hstep, voffB); PG8_STAGE(PG8_SA(0, 0), a2, voffA);
.LBB0_351:
	ds_read_b128 v[146:149], v154
	ds_read_b128 v[158:161], v154 offset:1024
	ds_read_b128 v[162:165], v154 offset:2048
	ds_read_b128 v[166:169], v154 offset:3072
	ds_read_b128 v[170:173], v155
	ds_read_b128 v[174:177], v155 offset:1024
	ds_read_b128 v[178:181], v155 offset:2048
	ds_read_b128 v[182:185], v155 offset:3072
	s_add_u32 s22, s20, 0xfff80080
	s_addc_u32 s23, s21, -1
	s_cmp_eq_u32 s53, 28
	s_cselect_b32 s25, s13, s23
	s_cselect_b32 s24, s43, s22
	s_cselect_b32 s23, s11, s52
	s_cselect_b32 s22, s44, s45
	s_add_i32 m0, s19, 0xc000
	ds_read_b128 v[186:189], v156
	ds_read_b128 v[190:193], v156 offset:1024
	ds_read_b128 v[194:197], v156 offset:2048
	ds_read_b128 v[198:201], v156 offset:3072
	ds_read_b128 v[202:205], v156 offset:4096
	ds_read_b128 v[206:209], v156 offset:5120
	ds_read_b128 v[210:213], v156 offset:6144
	ds_read_b128 v[214:217], v156 offset:7168
	global_load_lds_dwordx4 v138, s[20:21]
	s_add_i32 m0, s19, 0xe000
	s_nop 0
	global_load_lds_dwordx4 v140, s[20:21]
	s_waitcnt vmcnt(8)
	s_waitcnt lgkmcnt(0)
	s_barrier
	s_setprio 1
	s_waitcnt lgkmcnt(0)
	v_mfma_f32_16x16x32_bf16 v[126:129], v[146:149], v[186:189], v[126:129]
	v_mfma_f32_16x16x32_bf16 v[122:125], v[162:165], v[186:189], v[122:125]
	v_mfma_f32_16x16x32_bf16 v[110:113], v[146:149], v[194:197], v[110:113]
	v_mfma_f32_16x16x32_bf16 v[106:109], v[162:165], v[194:197], v[106:109]
	v_mfma_f32_16x16x32_bf16 v[94:97], v[146:149], v[202:205], v[94:97]
	v_mfma_f32_16x16x32_bf16 v[90:93], v[162:165], v[202:205], v[90:93]
	v_mfma_f32_16x16x32_bf16 v[78:81], v[146:149], v[210:213], v[78:81]
	v_mfma_f32_16x16x32_bf16 v[74:77], v[162:165], v[210:213], v[74:77]
	v_mfma_f32_16x16x32_bf16 v[126:129], v[158:161], v[190:193], v[126:129]
	v_mfma_f32_16x16x32_bf16 v[122:125], v[166:169], v[190:193], v[122:125]
	v_mfma_f32_16x16x32_bf16 v[110:113], v[158:161], v[198:201], v[110:113]
	v_mfma_f32_16x16x32_bf16 v[106:109], v[166:169], v[198:201], v[106:109]
	v_mfma_f32_16x16x32_bf16 v[94:97], v[158:161], v[206:209], v[94:97]
	v_mfma_f32_16x16x32_bf16 v[90:93], v[166:169], v[206:209], v[90:93]
	v_mfma_f32_16x16x32_bf16 v[78:81], v[158:161], v[214:217], v[78:81]
	v_mfma_f32_16x16x32_bf16 v[74:77], v[166:169], v[214:217], v[74:77]
	s_setprio 0
	s_setprio 1
	v_mfma_f32_16x16x32_bf16 v[118:121], v[170:173], v[186:189], v[118:121]
	v_mfma_f32_16x16x32_bf16 v[114:117], v[178:181], v[186:189], v[114:117]
	v_mfma_f32_16x16x32_bf16 v[102:105], v[170:173], v[194:197], v[102:105]
	v_mfma_f32_16x16x32_bf16 v[98:101], v[178:181], v[194:197], v[98:101]
	v_mfma_f32_16x16x32_bf16 v[86:89], v[170:173], v[202:205], v[86:89]
	v_mfma_f32_16x16x32_bf16 v[82:85], v[178:181], v[202:205], v[82:85]
	v_mfma_f32_16x16x32_bf16 v[70:73], v[170:173], v[210:213], v[70:73]
	v_mfma_f32_16x16x32_bf16 v[66:69], v[178:181], v[210:213], v[66:69]
	v_mfma_f32_16x16x32_bf16 v[118:121], v[174:177], v[190:193], v[118:121]
	v_mfma_f32_16x16x32_bf16 v[114:117], v[182:185], v[190:193], v[114:117]
	v_mfma_f32_16x16x32_bf16 v[102:105], v[174:177], v[198:201], v[102:105]
	v_mfma_f32_16x16x32_bf16 v[98:101], v[182:185], v[198:201], v[98:101]
	v_mfma_f32_16x16x32_bf16 v[86:89], v[174:177], v[206:209], v[86:89]
	v_mfma_f32_16x16x32_bf16 v[82:85], v[182:185], v[206:209], v[82:85]
	v_mfma_f32_16x16x32_bf16 v[70:73], v[174:177], v[214:217], v[70:73]
	v_mfma_f32_16x16x32_bf16 v[66:69], v[182:185], v[214:217], v[66:69]
	s_setprio 0
	s_barrier
	s_add_i32 s54, s35, s2
	v_lshl_add_u64 v[218:219], s[22:23], 0, v[134:135]
	s_mov_b32 m0, s54
	ds_read_b128 v[186:189], v156 offset:16384
	ds_read_b128 v[190:193], v156 offset:17408
	ds_read_b128 v[194:197], v156 offset:18432
	ds_read_b128 v[198:201], v156 offset:19456
	ds_read_b128 v[202:205], v156 offset:20480
	ds_read_b128 v[206:209], v156 offset:21504
	ds_read_b128 v[210:213], v156 offset:22528
	ds_read_b128 v[214:217], v156 offset:23552
	global_load_lds_dwordx4 v134, s[22:23]
	s_add_i32 m0, s54, 0x2000
	s_add_u32 s54, s22, 0x80000
	v_lshl_add_u64 v[220:221], s[22:23], 0, v[130:131]
	s_addc_u32 s55, s23, 0
	s_add_i32 s56, s38, s2
	global_load_lds_dwordx4 v130, s[22:23]
	s_mov_b32 m0, s56
	v_lshl_add_u64 v[224:225], s[24:25], 0, v[132:133]
	global_load_lds_dwordx4 v134, s[54:55]
	s_add_i32 m0, s56, 0x2000
	s_nop 0
	global_load_lds_dwordx4 v130, s[54:55]
	v_lshl_add_u64 v[222:223], s[24:25], 0, v[136:137]
	s_mov_b32 m0, s19
	s_nop 0
	global_load_lds_dwordx4 v136, s[24:25]
	s_mov_b32 m0, s27
	s_nop 0
	global_load_lds_dwordx4 v132, s[24:25]
	s_waitcnt vmcnt(8)
	s_waitcnt lgkmcnt(0)
	s_barrier
; #define PG8_STAGE(bufoff, gbase, voff) do { _Pragma("unroll") for (int _i = 0; _i < 2; ++_i) \
;         __builtin_amdgcn_global_load_lds((const unsigned*)((const char*)(gbase) + (voff)[_i]), (PG8_LAS unsigned*)(lds + (bufoff) + ldsw + _i * 8192), 16, 0, 0); } while (0)
; #define PG8_LDA(dst, b, h) do { _Pragma("unroll") for (int m = 0; m < 4; ++m) _Pragma("unroll") for (int k = 0; k < 2; ++k) dst[m][k] = *(const PG8_LAS bf16x8*)(lds + PG8_SA(b, h) + aoff + m * 2048 + k * 1024); } while (0)
; #define PG8_LDB(dst, b, h) do { _Pragma("unroll") for (int n = 0; n < 2; ++n) _Pragma("unroll") for (int k = 0; k < 2; ++k) dst[n][k] = *(const PG8_LAS bf16x8*)(lds + PG8_SB(b, h) + boff + n * 2048 + k * 1024); } while (0)
; #define PG8_MMA(ai, bj, At, Bt) do { __builtin_amdgcn_s_setprio(1); _Pragma("unroll") for (int m = 0; m < 4; ++m) _Pragma("unroll") for (int n = 0; n < 2; ++n) _Pragma("unroll") for (int k = 0; k < 2; ++k) \
;         acc[ai][bj][m][n] = __builtin_amdgcn_mfma_f32_16x16x32_bf16(Bt[n][k], At[m][k], acc[ai][bj][m][n], 0, 0, 0); __builtin_amdgcn_s_setprio(0); } while (0)
; #define PG8_WAIT_V(n) asm volatile("s_waitcnt vmcnt(" #n ")" ::: "memory")
; #define PG8_WAIT_L(n) asm volatile("s_waitcnt lgkmcnt(" #n ")" ::: "memory")
; #define PG8_BAR __builtin_amdgcn_s_barrier()
; #define PG8_SCHED __builtin_amdgcn_sched_barrier(0)
; template <class Epi, class Sched, bool ALIGN_EPI = false, bool SP2 = false>
; __device__ __forceinline__ void gemm_phase(PG8_LAS unsigned char* lds, const Gemm g, const Sched& S, const Epi& E) {
;     ...
;             PG8_WAIT_V(8); PG8_WAIT_L(0); PG8_BAR; PG8_MMA(1, 0, At, B0); PG8_MMA(1, 1, At, B1); PG8_BAR; PG8_SCHED;
;             PG8_LDB(B0, 1, 0); PG8_LDB(B1, 1, 1); PG8_SCHED; PG8_LDA(At, 1, 0); PG8_STAGE(PG8_SA(0, 1), a2 + hstep, voffA);
;             PG8_WAIT_V(8); PG8_WAIT_L(0); PG8_BAR; PG8_MMA(0, 0, At, B0); PG8_MMA(0, 1, At, B1); PG8_BAR; PG8_SCHED;
	s_setprio 1
	s_waitcnt lgkmcnt(0)
	v_mfma_f32_16x16x32_bf16 v[62:65], v[146:149], v[186:189], v[62:65]
	v_mfma_f32_16x16x32_bf16 v[58:61], v[162:165], v[186:189], v[58:61]
	v_mfma_f32_16x16x32_bf16 v[46:49], v[146:149], v[194:197], v[46:49]
	v_mfma_f32_16x16x32_bf16 v[42:45], v[162:165], v[194:197], v[42:45]
	v_mfma_f32_16x16x32_bf16 v[30:33], v[146:149], v[202:205], v[30:33]
	v_mfma_f32_16x16x32_bf16 v[26:29], v[162:165], v[202:205], v[26:29]
	v_mfma_f32_16x16x32_bf16 v[14:17], v[146:149], v[210:213], v[14:17]
	v_mfma_f32_16x16x32_bf16 v[10:13], v[162:165], v[210:213], v[10:13]
	v_mfma_f32_16x16x32_bf16 v[62:65], v[158:161], v[190:193], v[62:65]
	v_mfma_f32_16x16x32_bf16 v[58:61], v[166:169], v[190:193], v[58:61]
	v_mfma_f32_16x16x32_bf16 v[46:49], v[158:161], v[198:201], v[46:49]
	v_mfma_f32_16x16x32_bf16 v[42:45], v[166:169], v[198:201], v[42:45]
	v_mfma_f32_16x16x32_bf16 v[30:33], v[158:161], v[206:209], v[30:33]
	v_mfma_f32_16x16x32_bf16 v[26:29], v[166:169], v[206:209], v[26:29]
	v_mfma_f32_16x16x32_bf16 v[14:17], v[158:161], v[214:217], v[14:17]
	v_mfma_f32_16x16x32_bf16 v[10:13], v[166:169], v[214:217], v[10:13]
	s_setprio 0
	s_setprio 1
	v_mfma_f32_16x16x32_bf16 v[54:57], v[170:173], v[186:189], v[54:57]
	v_mfma_f32_16x16x32_bf16 v[50:53], v[178:181], v[186:189], v[50:53]
	v_mfma_f32_16x16x32_bf16 v[38:41], v[170:173], v[194:197], v[38:41]
	v_mfma_f32_16x16x32_bf16 v[34:37], v[178:181], v[194:197], v[34:37]
	v_mfma_f32_16x16x32_bf16 v[22:25], v[170:173], v[202:205], v[22:25]
	v_mfma_f32_16x16x32_bf16 v[18:21], v[178:181], v[202:205], v[18:21]
	v_mfma_f32_16x16x32_bf16 v[6:9], v[170:173], v[210:213], v[6:9]
	v_mfma_f32_16x16x32_bf16 v[2:5], v[178:181], v[210:213], v[2:5]
	v_mfma_f32_16x16x32_bf16 v[54:57], v[174:177], v[190:193], v[54:57]
	v_mfma_f32_16x16x32_bf16 v[50:53], v[182:185], v[190:193], v[50:53]
	v_mfma_f32_16x16x32_bf16 v[38:41], v[174:177], v[198:201], v[38:41]
	v_mfma_f32_16x16x32_bf16 v[34:37], v[182:185], v[198:201], v[34:37]
	v_mfma_f32_16x16x32_bf16 v[22:25], v[174:177], v[206:209], v[22:25]
	v_mfma_f32_16x16x32_bf16 v[18:21], v[182:185], v[206:209], v[18:21]
	v_mfma_f32_16x16x32_bf16 v[6:9], v[174:177], v[214:217], v[6:9]
	v_mfma_f32_16x16x32_bf16 v[2:5], v[182:185], v[214:217], v[2:5]
	s_setprio 0
	s_barrier
	s_add_i32 s54, 0, 0x18000
	v_add_u32_e32 v157, s54, v150
	s_add_i32 s55, 0, 0x1c000
	ds_read_b128 v[146:149], v157
	ds_read_b128 v[158:161], v157 offset:1024
	ds_read_b128 v[162:165], v157 offset:2048
	ds_read_b128 v[166:169], v157 offset:3072
	v_add_u32_e32 v157, s55, v150
	ds_read_b128 v[170:173], v157
	ds_read_b128 v[174:177], v157 offset:1024
	ds_read_b128 v[178:181], v157 offset:2048
	ds_read_b128 v[182:185], v157 offset:3072
	s_add_u32 s24, s24, 0x80000
	s_addc_u32 s25, s25, 0
	s_mov_b32 m0, s28
	ds_read_b128 v[186:189], v156 offset:32768
	ds_read_b128 v[190:193], v156 offset:33792
	ds_read_b128 v[194:197], v156 offset:34816
	ds_read_b128 v[198:201], v156 offset:35840
	ds_read_b128 v[202:205], v156 offset:36864
	ds_read_b128 v[206:209], v156 offset:37888
	ds_read_b128 v[210:213], v156 offset:38912
	ds_read_b128 v[214:217], v156 offset:39936
	global_load_lds_dwordx4 v136, s[24:25]
	v_lshl_add_u64 v[226:227], s[24:25], 0, v[132:133]
	s_mov_b32 m0, s29
	s_nop 0
	global_load_lds_dwordx4 v132, s[24:25]
	s_waitcnt vmcnt(8)
	s_waitcnt lgkmcnt(0)
	s_barrier
	s_setprio 1
	s_waitcnt lgkmcnt(0)
	v_mfma_f32_16x16x32_bf16 v[126:129], v[146:149], v[186:189], v[126:129]
	v_mfma_f32_16x16x32_bf16 v[122:125], v[162:165], v[186:189], v[122:125]
	v_mfma_f32_16x16x32_bf16 v[110:113], v[146:149], v[194:197], v[110:113]
	v_mfma_f32_16x16x32_bf16 v[106:109], v[162:165], v[194:197], v[106:109]
	v_mfma_f32_16x16x32_bf16 v[94:97], v[146:149], v[202:205], v[94:97]
	v_mfma_f32_16x16x32_bf16 v[90:93], v[162:165], v[202:205], v[90:93]
	v_mfma_f32_16x16x32_bf16 v[78:81], v[146:149], v[210:213], v[78:81]
	v_mfma_f32_16x16x32_bf16 v[74:77], v[162:165], v[210:213], v[74:77]
	v_mfma_f32_16x16x32_bf16 v[126:129], v[158:161], v[190:193], v[126:129]
	v_mfma_f32_16x16x32_bf16 v[122:125], v[166:169], v[190:193], v[122:125]
	v_mfma_f32_16x16x32_bf16 v[110:113], v[158:161], v[198:201], v[110:113]
	v_mfma_f32_16x16x32_bf16 v[106:109], v[166:169], v[198:201], v[106:109]
	v_mfma_f32_16x16x32_bf16 v[94:97], v[158:161], v[206:209], v[94:97]
	v_mfma_f32_16x16x32_bf16 v[90:93], v[166:169], v[206:209], v[90:93]
	v_mfma_f32_16x16x32_bf16 v[78:81], v[158:161], v[214:217], v[78:81]
	v_mfma_f32_16x16x32_bf16 v[74:77], v[166:169], v[214:217], v[74:77]
	s_setprio 0
	s_setprio 1
	v_mfma_f32_16x16x32_bf16 v[118:121], v[170:173], v[186:189], v[118:121]
	v_mfma_f32_16x16x32_bf16 v[114:117], v[178:181], v[186:189], v[114:117]
	v_mfma_f32_16x16x32_bf16 v[102:105], v[170:173], v[194:197], v[102:105]
	v_mfma_f32_16x16x32_bf16 v[98:101], v[178:181], v[194:197], v[98:101]
	v_mfma_f32_16x16x32_bf16 v[86:89], v[170:173], v[202:205], v[86:89]
	v_mfma_f32_16x16x32_bf16 v[82:85], v[178:181], v[202:205], v[82:85]
	v_mfma_f32_16x16x32_bf16 v[70:73], v[170:173], v[210:213], v[70:73]
	v_mfma_f32_16x16x32_bf16 v[66:69], v[178:181], v[210:213], v[66:69]
	v_mfma_f32_16x16x32_bf16 v[118:121], v[174:177], v[190:193], v[118:121]
	v_mfma_f32_16x16x32_bf16 v[114:117], v[182:185], v[190:193], v[114:117]
	v_mfma_f32_16x16x32_bf16 v[102:105], v[174:177], v[198:201], v[102:105]
	v_mfma_f32_16x16x32_bf16 v[98:101], v[182:185], v[198:201], v[98:101]
	v_mfma_f32_16x16x32_bf16 v[86:89], v[174:177], v[206:209], v[86:89]
	v_mfma_f32_16x16x32_bf16 v[82:85], v[182:185], v[206:209], v[82:85]
	v_mfma_f32_16x16x32_bf16 v[70:73], v[174:177], v[214:217], v[70:73]
	v_mfma_f32_16x16x32_bf16 v[66:69], v[182:185], v[214:217], v[66:69]
	s_setprio 0
	s_barrier
; #define PG8_STAGE(bufoff, gbase, voff) do { _Pragma("unroll") for (int _i = 0; _i < 2; ++_i) \
;         __builtin_amdgcn_global_load_lds((const unsigned*)((const char*)(gbase) + (voff)[_i]), (PG8_LAS unsigned*)(lds + (bufoff) + ldsw + _i * 8192), 16, 0, 0); } while (0)
; #define PG8_LDA(dst, b, h) do { _Pragma("unroll") for (int m = 0; m < 4; ++m) _Pragma("unroll") for (int k = 0; k < 2; ++k) dst[m][k] = *(const PG8_LAS bf16x8*)(lds + PG8_SA(b, h) + aoff + m * 2048 + k * 1024); } while (0)
; #define PG8_MMA(ai, bj, At, Bt) do { __builtin_amdgcn_s_setprio(1); _Pragma("unroll") for (int m = 0; m < 4; ++m) _Pragma("unroll") for (int n = 0; n < 2; ++n) _Pragma("unroll") for (int k = 0; k < 2; ++k) \
;         acc[ai][bj][m][n] = __builtin_amdgcn_mfma_f32_16x16x32_bf16(Bt[n][k], At[m][k], acc[ai][bj][m][n], 0, 0, 0); __builtin_amdgcn_s_setprio(0); } while (0)
; #define PG8_WAIT_V(n) asm volatile("s_waitcnt vmcnt(" #n ")" ::: "memory")
; #define PG8_WAIT_L(n) asm volatile("s_waitcnt lgkmcnt(" #n ")" ::: "memory")
; #define PG8_BAR __builtin_amdgcn_s_barrier()
; #define PG8_SCHED __builtin_amdgcn_sched_barrier(0)
; template <class Epi, class Sched, bool ALIGN_EPI = false, bool SP2 = false>
; __device__ __forceinline__ void gemm_phase(PG8_LAS unsigned char* lds, const Gemm g, const Sched& S, const Epi& E) {
;     ...
;         for (int t = 0; t < nt; t += 2) {
;             const bool last = (t == nt - 2);
;             const char* a1 = cA + (size_t)(t + 1) * kstep;
;             const char* a2 = last ? nA : cA + (size_t)(t + 2) * kstep; const char* b2 = last ? nB : cB + (size_t)(t + 2) * kstep;
;     ...
;             PG8_LDA(At, 1, 1); PG8_STAGE(PG8_SB(1, 0), b3, voffB); PG8_STAGE(PG8_SB(1, 1), b3 + hstep, voffB); PG8_STAGE(PG8_SA(1, 0), a3, voffA);
;             PG8_WAIT_V(8); PG8_WAIT_L(0); PG8_BAR; PG8_MMA(1, 0, At, B0); PG8_MMA(1, 1, At, B1); PG8_BAR; PG8_SCHED;
	s_add_i32 s24, s54, s2
	v_lshl_add_u64 v[218:219], v[218:219], 0, s[6:7]
	s_mov_b32 m0, s24
	ds_read_b128 v[186:189], v156 offset:49152
	ds_read_b128 v[190:193], v156 offset:50176
	ds_read_b128 v[194:197], v156 offset:51200
	ds_read_b128 v[198:201], v156 offset:52224
	ds_read_b128 v[202:205], v156 offset:53248
	ds_read_b128 v[206:209], v156 offset:54272
	ds_read_b128 v[210:213], v156 offset:55296
	ds_read_b128 v[214:217], v156 offset:56320
	global_load_lds_dwordx4 v[218:219], off
	s_add_i32 m0, s24, 0x2000
	s_add_u32 s22, s22, 0x80080
	v_lshl_add_u64 v[218:219], v[220:221], 0, s[6:7]
	s_addc_u32 s23, s23, 0
	s_add_i32 s24, s55, s2
	global_load_lds_dwordx4 v[218:219], off
	s_mov_b32 m0, s24
	s_nop 0
	global_load_lds_dwordx4 v134, s[22:23]
	s_add_i32 m0, s24, 0x2000
	s_nop 0
	global_load_lds_dwordx4 v130, s[22:23]
	v_lshl_add_u64 v[218:219], v[222:223], 0, s[6:7]
	s_mov_b32 m0, s31
	s_nop 0
	global_load_lds_dwordx4 v[218:219], off
	v_lshl_add_u64 v[218:219], v[224:225], 0, s[6:7]
	s_mov_b32 m0, s33
	s_nop 0
	global_load_lds_dwordx4 v[218:219], off
	s_waitcnt vmcnt(8)
	s_waitcnt lgkmcnt(0)
	s_barrier
	s_setprio 1
	s_waitcnt lgkmcnt(0)
	v_mfma_f32_16x16x32_bf16 v[62:65], v[146:149], v[186:189], v[62:65]
	v_mfma_f32_16x16x32_bf16 v[58:61], v[162:165], v[186:189], v[58:61]
	v_mfma_f32_16x16x32_bf16 v[46:49], v[146:149], v[194:197], v[46:49]
	v_mfma_f32_16x16x32_bf16 v[42:45], v[162:165], v[194:197], v[42:45]
	v_mfma_f32_16x16x32_bf16 v[30:33], v[146:149], v[202:205], v[30:33]
	v_mfma_f32_16x16x32_bf16 v[26:29], v[162:165], v[202:205], v[26:29]
	v_mfma_f32_16x16x32_bf16 v[14:17], v[146:149], v[210:213], v[14:17]
	v_mfma_f32_16x16x32_bf16 v[10:13], v[162:165], v[210:213], v[10:13]
	v_mfma_f32_16x16x32_bf16 v[62:65], v[158:161], v[190:193], v[62:65]
	v_mfma_f32_16x16x32_bf16 v[58:61], v[166:169], v[190:193], v[58:61]
	v_mfma_f32_16x16x32_bf16 v[46:49], v[158:161], v[198:201], v[46:49]
	v_mfma_f32_16x16x32_bf16 v[42:45], v[166:169], v[198:201], v[42:45]
	v_mfma_f32_16x16x32_bf16 v[30:33], v[158:161], v[206:209], v[30:33]
	v_mfma_f32_16x16x32_bf16 v[26:29], v[166:169], v[206:209], v[26:29]
	v_mfma_f32_16x16x32_bf16 v[14:17], v[158:161], v[214:217], v[14:17]
	v_mfma_f32_16x16x32_bf16 v[10:13], v[166:169], v[214:217], v[10:13]
	s_setprio 0
	s_setprio 1
	v_mfma_f32_16x16x32_bf16 v[54:57], v[170:173], v[186:189], v[54:57]
	v_mfma_f32_16x16x32_bf16 v[50:53], v[178:181], v[186:189], v[50:53]
	v_mfma_f32_16x16x32_bf16 v[38:41], v[170:173], v[194:197], v[38:41]
	v_mfma_f32_16x16x32_bf16 v[34:37], v[178:181], v[194:197], v[34:37]
	v_mfma_f32_16x16x32_bf16 v[22:25], v[170:173], v[202:205], v[22:25]
	v_mfma_f32_16x16x32_bf16 v[18:21], v[178:181], v[202:205], v[18:21]
	v_mfma_f32_16x16x32_bf16 v[6:9], v[170:173], v[210:213], v[6:9]
	v_mfma_f32_16x16x32_bf16 v[2:5], v[178:181], v[210:213], v[2:5]
	v_mfma_f32_16x16x32_bf16 v[54:57], v[174:177], v[190:193], v[54:57]
	v_mfma_f32_16x16x32_bf16 v[50:53], v[182:185], v[190:193], v[50:53]
	v_mfma_f32_16x16x32_bf16 v[38:41], v[174:177], v[198:201], v[38:41]
	v_mfma_f32_16x16x32_bf16 v[34:37], v[182:185], v[198:201], v[34:37]
	v_mfma_f32_16x16x32_bf16 v[22:25], v[174:177], v[206:209], v[22:25]
	v_mfma_f32_16x16x32_bf16 v[18:21], v[182:185], v[206:209], v[18:21]
	v_mfma_f32_16x16x32_bf16 v[6:9], v[174:177], v[214:217], v[6:9]
	v_mfma_f32_16x16x32_bf16 v[2:5], v[182:185], v[214:217], v[2:5]
	s_setprio 0
	s_barrier
	s_add_i32 s53, s53, 2
	s_add_u32 s20, s20, 0x100
	s_addc_u32 s21, s21, 0
	s_add_u32 s45, s45, 0x100
	s_addc_u32 s52, s52, 0
	s_cmp_gt_u32 s53, 29
	s_cbranch_scc0 .LBB0_351
	s_and_b64 vcc, exec, s[8:9]
	s_cbranch_vccz .LBB0_354
	s_barrier

; #define PG8_STAGE(bufoff, gbase, voff) do { _Pragma("unroll") for (int _i = 0; _i < 2; ++_i) \
;         __builtin_amdgcn_global_load_lds((const unsigned*)((const char*)(gbase) + (voff)[_i]), (PG8_LAS unsigned*)(lds + (bufoff) + ldsw + _i * 8192), 16, 0, 0); } while (0)
; #define PG8_WAIT_V(n) asm volatile("s_waitcnt vmcnt(" #n ")" ::: "memory")
; #define PG8_BAR __builtin_amdgcn_s_barrier()
; template <class Epi, class Sched, bool ALIGN_EPI = false, bool SP2 = false>
; __device__ __forceinline__ void gemm_phase(PG8_LAS unsigned char* lds, const Gemm g, const Sched& S, const Epi& E) {
;     ...
;     const unsigned ldsw = (unsigned)wid * 1024u;
;     const int aoff = lds_byte(wr * 64 + fr, fq * 8), boff = lds_byte(wc * 32 + fr, fq * 8);
;     ...
;         PG8_STAGE(PG8_SB(1, 0), cB + kstep, voffB); PG8_STAGE(PG8_SA(1, 0), cA + kstep, voffA); PG8_STAGE(PG8_SB(1, 1), cB + hstep + kstep, voffB);
;         PG8_WAIT_V(6); PG8_BAR;
.LBB0_434:
	v_bfe_u32 v19, v10, 4, 2
	v_and_b32_e32 v20, 15, v10
	v_lshlrev_b32_e32 v21, 4, v19
	s_lshl_b32 s8, s8, 5
	v_lshl_or_b32 v20, v20, 6, v21
	v_lshlrev_b32_e32 v21, 2, v10
	s_and_b32 s18, s8, 0x60
	s_sext_i32_i8 s38, s9
	s_lshl_b32 s9, s0, 13
	v_and_b32_e32 v21, 32, v21
	s_lshl_b32 s8, s18, 7
	v_bitop3_b32 v22, v20, s9, v21 bitop3:0xde
	v_bitop3_b32 v146, v20, s8, v21 bitop3:0xde
	s_mov_b64 s[8:9], 0x80
	s_add_i32 m0, s22, 0x18000
	v_lshl_add_u64 v[8:9], v[8:9], 0, s[8:9]
	s_waitcnt vmcnt(2)
	s_barrier
	global_load_lds_dwordx4 v[8:9], off
	v_lshl_add_u64 v[4:5], v[4:5], 0, s[8:9]
	s_add_i32 m0, s22, 0x1a000
	s_add_i32 s27, s22, 0x8000
	s_add_i32 s28, s22, 0xa000
	global_load_lds_dwordx4 v[4:5], off
	v_lshl_add_u64 v[2:3], v[2:3], 0, s[8:9]
	s_mov_b32 m0, s27
	s_add_u32 s10, s16, 0x160080
	global_load_lds_dwordx4 v[2:3], off
	v_lshl_add_u64 v[2:3], v[6:7], 0, s[8:9]
	s_mov_b32 m0, s28
	s_addc_u32 s11, s17, 0
	global_load_lds_dwordx4 v[2:3], off
	s_add_i32 m0, s22, 0x1c000
	s_nop 0
	global_load_lds_dwordx4 v132, s[10:11]
	v_lshl_add_u64 v[2:3], s[10:11], 0, v[136:137]
	s_add_i32 m0, s22, 0x1e000
	s_mov_b64 s[12:13], 0x160080
	global_load_lds_dwordx4 v136, s[10:11]
	v_bfe_u32 v2, v10, 2, 2
	v_and_b32_e32 v3, 3, v10
	v_lshl_or_b32 v2, v19, 2, v2
	v_lshlrev_b32_e32 v4, 6, v3
	v_lshl_or_b32 v147, v2, 2, v4
	v_lshl_or_b32 v148, s0, 6, v2
	v_lshl_or_b32 v149, v3, 3, s18
	v_lshrrev_b32_e32 v3, 1, v11
	v_mul_lo_u32 v2, v12, s1
	v_mad_u64_u32 v[2:3], s[18:19], v3, s5, v[2:3]
	v_or_b32_e32 v2, v2, v13
	v_add_lshl_u32 v2, v2, v14, 1
	v_mov_b32_e32 v3, v133
	v_lshl_add_u64 v[138:139], v[2:3], 0, s[12:13]
	v_lshrrev_b32_e32 v3, 1, v15
	v_mul_lo_u32 v2, v16, s1
	v_mad_u64_u32 v[2:3], s[0:1], v3, s5, v[2:3]
	s_waitcnt vmcnt(6)
	s_cmpk_lt_u32 s4, 0x100
	v_or_b32_e32 v2, v2, v17
	s_cselect_b64 s[10:11], -1, 0
	v_readlane_b32 s20, v253, 0
	v_add_lshl_u32 v2, v2, v18, 1
	v_mov_b32_e32 v3, v133
	s_add_i32 s30, 0, 0x10000
	s_add_i32 s31, 0, 0x14000
	s_ashr_i32 s29, s20, 31
	v_lshl_add_u64 v[140:141], v[2:3], 0, s[12:13]
	v_mov_b64_e32 v[142:143], 0x200
	v_mov_b64_e32 v[144:145], 0x1ff
	v_add_u32_e32 v150, s30, v146
	v_add_u32_e32 v151, s31, v146
	v_add_u32_e32 v152, 0, v22
	s_barrier
	v_readlane_b32 s21, v253, 1
	s_waitcnt vmcnt(0)
	s_branch .LBB0_437

; #define PG8_STAGE(bufoff, gbase, voff) do { _Pragma("unroll") for (int _i = 0; _i < 2; ++_i) \
;         __builtin_amdgcn_global_load_lds((const unsigned*)((const char*)(gbase) + (voff)[_i]), (PG8_LAS unsigned*)(lds + (bufoff) + ldsw + _i * 8192), 16, 0, 0); } while (0)
; #define PG8_LDA(dst, b, h) do { _Pragma("unroll") for (int m = 0; m < 4; ++m) _Pragma("unroll") for (int k = 0; k < 2; ++k) dst[m][k] = *(const PG8_LAS bf16x8*)(lds + PG8_SA(b, h) + aoff + m * 2048 + k * 1024); } while (0)
; #define PG8_LDB(dst, b, h) do { _Pragma("unroll") for (int n = 0; n < 2; ++n) _Pragma("unroll") for (int k = 0; k < 2; ++k) dst[n][k] = *(const PG8_LAS bf16x8*)(lds + PG8_SB(b, h) + boff + n * 2048 + k * 1024); } while (0)
; #define PG8_MMA(ai, bj, At, Bt) do { __builtin_amdgcn_s_setprio(1); _Pragma("unroll") for (int m = 0; m < 4; ++m) _Pragma("unroll") for (int n = 0; n < 2; ++n) _Pragma("unroll") for (int k = 0; k < 2; ++k) \
;         acc[ai][bj][m][n] = __builtin_amdgcn_mfma_f32_16x16x32_bf16(Bt[n][k], At[m][k], acc[ai][bj][m][n], 0, 0, 0); __builtin_amdgcn_s_setprio(0); } while (0)
; #define PG8_WAIT_V(n) asm volatile("s_waitcnt vmcnt(" #n ")" ::: "memory")
; #define PG8_WAIT_L(n) asm volatile("s_waitcnt lgkmcnt(" #n ")" ::: "memory")
; #define PG8_BAR __builtin_amdgcn_s_barrier()
; #define PG8_SCHED __builtin_amdgcn_sched_barrier(0)
; template <class Epi, class Sched, bool ALIGN_EPI = false, bool SP2 = false>
; __device__ __forceinline__ void gemm_phase(PG8_LAS unsigned char* lds, const Gemm g, const Sched& S, const Epi& E) {
;     ...
;             PG8_LDB(B0, 0, 0); PG8_LDB(B1, 0, 1); PG8_SCHED; PG8_LDA(At, 0, 0); PG8_STAGE(PG8_SA(1, 1), a1 + hstep, voffA);
;             PG8_WAIT_V(8); PG8_WAIT_L(0); PG8_BAR; PG8_MMA(0, 0, At, B0); PG8_MMA(0, 1, At, B1); PG8_BAR; PG8_SCHED;
;             PG8_LDA(At, 0, 1); PG8_STAGE(PG8_SB(0, 0), b2, voffB); PG8_STAGE(PG8_SB(0, 1), b2 + hstep, voffB); PG8_STAGE(PG8_SA(0, 0), a2, voffA);
.LBB0_448:
	ds_read_b128 v[154:157], v150
	ds_read_b128 v[158:161], v150 offset:1024
	ds_read_b128 v[162:165], v150 offset:2048
	ds_read_b128 v[166:169], v150 offset:3072
	ds_read_b128 v[170:173], v151
	ds_read_b128 v[174:177], v151 offset:1024
	ds_read_b128 v[178:181], v151 offset:2048
	ds_read_b128 v[182:185], v151 offset:3072
	s_add_u32 s16, s14, 0x100
	s_addc_u32 s17, s15, 0
	s_cmpk_eq_i32 s43, 0x54
	s_cselect_b32 s21, s5, s17
	s_cselect_b32 s20, s4, s16
	s_cselect_b32 s19, s13, s42
	s_cselect_b32 s18, s12, s39
	s_add_i32 m0, s22, 0xc000
	ds_read_b128 v[186:189], v152
	ds_read_b128 v[190:193], v152 offset:1024
	ds_read_b128 v[194:197], v152 offset:2048
	ds_read_b128 v[198:201], v152 offset:3072
	ds_read_b128 v[202:205], v152 offset:4096
	ds_read_b128 v[206:209], v152 offset:5120
	ds_read_b128 v[210:213], v152 offset:6144
	ds_read_b128 v[214:217], v152 offset:7168
	global_load_lds_dwordx4 v138, s[14:15]
	s_add_i32 m0, s22, 0xe000
	s_nop 0
	global_load_lds_dwordx4 v140, s[14:15]
	s_waitcnt vmcnt(8)
	s_waitcnt lgkmcnt(0)
	s_barrier
	s_setprio 1
	s_waitcnt lgkmcnt(0)
	v_mfma_f32_16x16x32_bf16 v[126:129], v[154:157], v[186:189], v[126:129]
	v_mfma_f32_16x16x32_bf16 v[122:125], v[162:165], v[186:189], v[122:125]
	v_mfma_f32_16x16x32_bf16 v[114:117], v[154:157], v[194:197], v[114:117]
	v_mfma_f32_16x16x32_bf16 v[106:109], v[162:165], v[194:197], v[106:109]
	v_mfma_f32_16x16x32_bf16 v[102:105], v[154:157], v[202:205], v[102:105]
	v_mfma_f32_16x16x32_bf16 v[94:97], v[162:165], v[202:205], v[94:97]
	v_mfma_f32_16x16x32_bf16 v[86:89], v[154:157], v[210:213], v[86:89]
	v_mfma_f32_16x16x32_bf16 v[78:81], v[162:165], v[210:213], v[78:81]
	v_mfma_f32_16x16x32_bf16 v[126:129], v[158:161], v[190:193], v[126:129]
	v_mfma_f32_16x16x32_bf16 v[122:125], v[166:169], v[190:193], v[122:125]
	v_mfma_f32_16x16x32_bf16 v[114:117], v[158:161], v[198:201], v[114:117]
	v_mfma_f32_16x16x32_bf16 v[106:109], v[166:169], v[198:201], v[106:109]
	v_mfma_f32_16x16x32_bf16 v[102:105], v[158:161], v[206:209], v[102:105]
	v_mfma_f32_16x16x32_bf16 v[94:97], v[166:169], v[206:209], v[94:97]
	v_mfma_f32_16x16x32_bf16 v[86:89], v[158:161], v[214:217], v[86:89]
	v_mfma_f32_16x16x32_bf16 v[78:81], v[166:169], v[214:217], v[78:81]
	s_setprio 0
	s_setprio 1
	v_mfma_f32_16x16x32_bf16 v[118:121], v[170:173], v[186:189], v[118:121]
	v_mfma_f32_16x16x32_bf16 v[110:113], v[178:181], v[186:189], v[110:113]
	v_mfma_f32_16x16x32_bf16 v[98:101], v[170:173], v[194:197], v[98:101]
	v_mfma_f32_16x16x32_bf16 v[90:93], v[178:181], v[194:197], v[90:93]
	v_mfma_f32_16x16x32_bf16 v[82:85], v[170:173], v[202:205], v[82:85]
	v_mfma_f32_16x16x32_bf16 v[74:77], v[178:181], v[202:205], v[74:77]
	v_mfma_f32_16x16x32_bf16 v[70:73], v[170:173], v[210:213], v[70:73]
	v_mfma_f32_16x16x32_bf16 v[66:69], v[178:181], v[210:213], v[66:69]
	v_mfma_f32_16x16x32_bf16 v[118:121], v[174:177], v[190:193], v[118:121]
	v_mfma_f32_16x16x32_bf16 v[110:113], v[182:185], v[190:193], v[110:113]
	v_mfma_f32_16x16x32_bf16 v[98:101], v[174:177], v[198:201], v[98:101]
	v_mfma_f32_16x16x32_bf16 v[90:93], v[182:185], v[198:201], v[90:93]
	v_mfma_f32_16x16x32_bf16 v[82:85], v[174:177], v[206:209], v[82:85]
	v_mfma_f32_16x16x32_bf16 v[74:77], v[182:185], v[206:209], v[74:77]
	v_mfma_f32_16x16x32_bf16 v[70:73], v[174:177], v[214:217], v[70:73]
	v_mfma_f32_16x16x32_bf16 v[66:69], v[182:185], v[214:217], v[66:69]
	s_setprio 0
	s_barrier
	s_add_i32 s14, s30, s3
	v_lshl_add_u64 v[218:219], s[18:19], 0, v[132:133]
	s_mov_b32 m0, s14
	ds_read_b128 v[186:189], v152 offset:16384
	ds_read_b128 v[190:193], v152 offset:17408
	ds_read_b128 v[194:197], v152 offset:18432
	ds_read_b128 v[198:201], v152 offset:19456
	ds_read_b128 v[202:205], v152 offset:20480
	ds_read_b128 v[206:209], v152 offset:21504
	ds_read_b128 v[210:213], v152 offset:22528
	ds_read_b128 v[214:217], v152 offset:23552
	global_load_lds_dwordx4 v132, s[18:19]
	s_add_i32 m0, s14, 0x2000
	s_add_u32 s14, s18, 0x160000
	v_lshl_add_u64 v[220:221], s[18:19], 0, v[136:137]
	s_addc_u32 s15, s19, 0
	s_add_i32 s44, s31, s3
	global_load_lds_dwordx4 v136, s[18:19]
	s_mov_b32 m0, s44
	v_lshl_add_u64 v[224:225], s[20:21], 0, v[134:135]
	global_load_lds_dwordx4 v132, s[14:15]
	s_add_i32 m0, s44, 0x2000
	s_nop 0
	global_load_lds_dwordx4 v136, s[14:15]
	v_lshl_add_u64 v[222:223], s[20:21], 0, v[130:131]
	s_mov_b32 m0, s22
	s_nop 0
	global_load_lds_dwordx4 v130, s[20:21]
	s_mov_b32 m0, s23
	s_nop 0
	global_load_lds_dwordx4 v134, s[20:21]
	s_waitcnt vmcnt(8)
	s_waitcnt lgkmcnt(0)
	s_barrier
; #define PG8_STAGE(bufoff, gbase, voff) do { _Pragma("unroll") for (int _i = 0; _i < 2; ++_i) \
;         __builtin_amdgcn_global_load_lds((const unsigned*)((const char*)(gbase) + (voff)[_i]), (PG8_LAS unsigned*)(lds + (bufoff) + ldsw + _i * 8192), 16, 0, 0); } while (0)
; #define PG8_LDA(dst, b, h) do { _Pragma("unroll") for (int m = 0; m < 4; ++m) _Pragma("unroll") for (int k = 0; k < 2; ++k) dst[m][k] = *(const PG8_LAS bf16x8*)(lds + PG8_SA(b, h) + aoff + m * 2048 + k * 1024); } while (0)
; #define PG8_LDB(dst, b, h) do { _Pragma("unroll") for (int n = 0; n < 2; ++n) _Pragma("unroll") for (int k = 0; k < 2; ++k) dst[n][k] = *(const PG8_LAS bf16x8*)(lds + PG8_SB(b, h) + boff + n * 2048 + k * 1024); } while (0)
; #define PG8_MMA(ai, bj, At, Bt) do { __builtin_amdgcn_s_setprio(1); _Pragma("unroll") for (int m = 0; m < 4; ++m) _Pragma("unroll") for (int n = 0; n < 2; ++n) _Pragma("unroll") for (int k = 0; k < 2; ++k) \
;         acc[ai][bj][m][n] = __builtin_amdgcn_mfma_f32_16x16x32_bf16(Bt[n][k], At[m][k], acc[ai][bj][m][n], 0, 0, 0); __builtin_amdgcn_s_setprio(0); } while (0)
; #define PG8_WAIT_V(n) asm volatile("s_waitcnt vmcnt(" #n ")" ::: "memory")
; #define PG8_WAIT_L(n) asm volatile("s_waitcnt lgkmcnt(" #n ")" ::: "memory")
; #define PG8_BAR __builtin_amdgcn_s_barrier()
; #define PG8_SCHED __builtin_amdgcn_sched_barrier(0)
; template <class Epi, class Sched, bool ALIGN_EPI = false, bool SP2 = false>
; __device__ __forceinline__ void gemm_phase(PG8_LAS unsigned char* lds, const Gemm g, const Sched& S, const Epi& E) {
;     ...
;             PG8_WAIT_V(8); PG8_WAIT_L(0); PG8_BAR; PG8_MMA(1, 0, At, B0); PG8_MMA(1, 1, At, B1); PG8_BAR; PG8_SCHED;
;             PG8_LDB(B0, 1, 0); PG8_LDB(B1, 1, 1); PG8_SCHED; PG8_LDA(At, 1, 0); PG8_STAGE(PG8_SA(0, 1), a2 + hstep, voffA);
;             PG8_WAIT_V(8); PG8_WAIT_L(0); PG8_BAR; PG8_MMA(0, 0, At, B0); PG8_MMA(0, 1, At, B1); PG8_BAR; PG8_SCHED;
	s_setprio 1
	s_waitcnt lgkmcnt(0)
	v_mfma_f32_16x16x32_bf16 v[62:65], v[154:157], v[186:189], v[62:65]
	v_mfma_f32_16x16x32_bf16 v[58:61], v[162:165], v[186:189], v[58:61]
	v_mfma_f32_16x16x32_bf16 v[54:57], v[154:157], v[194:197], v[54:57]
	v_mfma_f32_16x16x32_bf16 v[46:49], v[162:165], v[194:197], v[46:49]
	v_mfma_f32_16x16x32_bf16 v[38:41], v[154:157], v[202:205], v[38:41]
	v_mfma_f32_16x16x32_bf16 v[30:33], v[162:165], v[202:205], v[30:33]
	v_mfma_f32_16x16x32_bf16 v[22:25], v[154:157], v[210:213], v[22:25]
	v_mfma_f32_16x16x32_bf16 v[14:17], v[162:165], v[210:213], v[14:17]
	v_mfma_f32_16x16x32_bf16 v[62:65], v[158:161], v[190:193], v[62:65]
	v_mfma_f32_16x16x32_bf16 v[58:61], v[166:169], v[190:193], v[58:61]
	v_mfma_f32_16x16x32_bf16 v[54:57], v[158:161], v[198:201], v[54:57]
	v_mfma_f32_16x16x32_bf16 v[46:49], v[166:169], v[198:201], v[46:49]
	v_mfma_f32_16x16x32_bf16 v[38:41], v[158:161], v[206:209], v[38:41]
	v_mfma_f32_16x16x32_bf16 v[30:33], v[166:169], v[206:209], v[30:33]
	v_mfma_f32_16x16x32_bf16 v[22:25], v[158:161], v[214:217], v[22:25]
	v_mfma_f32_16x16x32_bf16 v[14:17], v[166:169], v[214:217], v[14:17]
	s_setprio 0
	s_setprio 1
	v_mfma_f32_16x16x32_bf16 v[50:53], v[170:173], v[186:189], v[50:53]
	v_mfma_f32_16x16x32_bf16 v[42:45], v[178:181], v[186:189], v[42:45]
	v_mfma_f32_16x16x32_bf16 v[34:37], v[170:173], v[194:197], v[34:37]
	v_mfma_f32_16x16x32_bf16 v[26:29], v[178:181], v[194:197], v[26:29]
	v_mfma_f32_16x16x32_bf16 v[18:21], v[170:173], v[202:205], v[18:21]
	v_mfma_f32_16x16x32_bf16 v[10:13], v[178:181], v[202:205], v[10:13]
	v_mfma_f32_16x16x32_bf16 v[6:9], v[170:173], v[210:213], v[6:9]
	v_mfma_f32_16x16x32_bf16 v[2:5], v[178:181], v[210:213], v[2:5]
	v_mfma_f32_16x16x32_bf16 v[50:53], v[174:177], v[190:193], v[50:53]
	v_mfma_f32_16x16x32_bf16 v[42:45], v[182:185], v[190:193], v[42:45]
	v_mfma_f32_16x16x32_bf16 v[34:37], v[174:177], v[198:201], v[34:37]
	v_mfma_f32_16x16x32_bf16 v[26:29], v[182:185], v[198:201], v[26:29]
	v_mfma_f32_16x16x32_bf16 v[18:21], v[174:177], v[206:209], v[18:21]
	v_mfma_f32_16x16x32_bf16 v[10:13], v[182:185], v[206:209], v[10:13]
	v_mfma_f32_16x16x32_bf16 v[6:9], v[174:177], v[214:217], v[6:9]
	v_mfma_f32_16x16x32_bf16 v[2:5], v[182:185], v[214:217], v[2:5]
	s_setprio 0
	s_barrier
	s_add_i32 s44, 0, 0x18000
	v_add_u32_e32 v153, s44, v146
	s_add_i32 s45, 0, 0x1c000
	ds_read_b128 v[154:157], v153
	ds_read_b128 v[158:161], v153 offset:1024
	ds_read_b128 v[162:165], v153 offset:2048
	ds_read_b128 v[166:169], v153 offset:3072
	v_add_u32_e32 v153, s45, v146
	ds_read_b128 v[170:173], v153
	ds_read_b128 v[174:177], v153 offset:1024
	ds_read_b128 v[178:181], v153 offset:2048
	ds_read_b128 v[182:185], v153 offset:3072
	s_add_u32 s14, s20, 0x160000
	s_addc_u32 s15, s21, 0
	s_mov_b32 m0, s24
	ds_read_b128 v[186:189], v152 offset:32768
	ds_read_b128 v[190:193], v152 offset:33792
	ds_read_b128 v[194:197], v152 offset:34816
	ds_read_b128 v[198:201], v152 offset:35840
	ds_read_b128 v[202:205], v152 offset:36864
	ds_read_b128 v[206:209], v152 offset:37888
	ds_read_b128 v[210:213], v152 offset:38912
	ds_read_b128 v[214:217], v152 offset:39936
	global_load_lds_dwordx4 v130, s[14:15]
	v_lshl_add_u64 v[226:227], s[14:15], 0, v[134:135]
	s_mov_b32 m0, s25
	s_nop 0
	global_load_lds_dwordx4 v134, s[14:15]
	s_waitcnt vmcnt(8)
	s_waitcnt lgkmcnt(0)
	s_barrier
	s_setprio 1
	s_waitcnt lgkmcnt(0)
	v_mfma_f32_16x16x32_bf16 v[126:129], v[154:157], v[186:189], v[126:129]
	v_mfma_f32_16x16x32_bf16 v[122:125], v[162:165], v[186:189], v[122:125]
	v_mfma_f32_16x16x32_bf16 v[114:117], v[154:157], v[194:197], v[114:117]
	v_mfma_f32_16x16x32_bf16 v[106:109], v[162:165], v[194:197], v[106:109]
	v_mfma_f32_16x16x32_bf16 v[102:105], v[154:157], v[202:205], v[102:105]
	v_mfma_f32_16x16x32_bf16 v[94:97], v[162:165], v[202:205], v[94:97]
	v_mfma_f32_16x16x32_bf16 v[86:89], v[154:157], v[210:213], v[86:89]
	v_mfma_f32_16x16x32_bf16 v[78:81], v[162:165], v[210:213], v[78:81]
	v_mfma_f32_16x16x32_bf16 v[126:129], v[158:161], v[190:193], v[126:129]
	v_mfma_f32_16x16x32_bf16 v[122:125], v[166:169], v[190:193], v[122:125]
	v_mfma_f32_16x16x32_bf16 v[114:117], v[158:161], v[198:201], v[114:117]
	v_mfma_f32_16x16x32_bf16 v[106:109], v[166:169], v[198:201], v[106:109]
	v_mfma_f32_16x16x32_bf16 v[102:105], v[158:161], v[206:209], v[102:105]
	v_mfma_f32_16x16x32_bf16 v[94:97], v[166:169], v[206:209], v[94:97]
	v_mfma_f32_16x16x32_bf16 v[86:89], v[158:161], v[214:217], v[86:89]
	v_mfma_f32_16x16x32_bf16 v[78:81], v[166:169], v[214:217], v[78:81]
	s_setprio 0
	s_setprio 1
	v_mfma_f32_16x16x32_bf16 v[118:121], v[170:173], v[186:189], v[118:121]
	v_mfma_f32_16x16x32_bf16 v[110:113], v[178:181], v[186:189], v[110:113]
	v_mfma_f32_16x16x32_bf16 v[98:101], v[170:173], v[194:197], v[98:101]
	v_mfma_f32_16x16x32_bf16 v[90:93], v[178:181], v[194:197], v[90:93]
	v_mfma_f32_16x16x32_bf16 v[82:85], v[170:173], v[202:205], v[82:85]
	v_mfma_f32_16x16x32_bf16 v[74:77], v[178:181], v[202:205], v[74:77]
	v_mfma_f32_16x16x32_bf16 v[70:73], v[170:173], v[210:213], v[70:73]
	v_mfma_f32_16x16x32_bf16 v[66:69], v[178:181], v[210:213], v[66:69]
	v_mfma_f32_16x16x32_bf16 v[118:121], v[174:177], v[190:193], v[118:121]
	v_mfma_f32_16x16x32_bf16 v[110:113], v[182:185], v[190:193], v[110:113]
	v_mfma_f32_16x16x32_bf16 v[98:101], v[174:177], v[198:201], v[98:101]
	v_mfma_f32_16x16x32_bf16 v[90:93], v[182:185], v[198:201], v[90:93]
	v_mfma_f32_16x16x32_bf16 v[82:85], v[174:177], v[206:209], v[82:85]
	v_mfma_f32_16x16x32_bf16 v[74:77], v[182:185], v[206:209], v[74:77]
	v_mfma_f32_16x16x32_bf16 v[70:73], v[174:177], v[214:217], v[70:73]
	v_mfma_f32_16x16x32_bf16 v[66:69], v[182:185], v[214:217], v[66:69]
	s_setprio 0
	s_barrier
; #define PG8_STAGE(bufoff, gbase, voff) do { _Pragma("unroll") for (int _i = 0; _i < 2; ++_i) \
;         __builtin_amdgcn_global_load_lds((const unsigned*)((const char*)(gbase) + (voff)[_i]), (PG8_LAS unsigned*)(lds + (bufoff) + ldsw + _i * 8192), 16, 0, 0); } while (0)
; #define PG8_LDA(dst, b, h) do { _Pragma("unroll") for (int m = 0; m < 4; ++m) _Pragma("unroll") for (int k = 0; k < 2; ++k) dst[m][k] = *(const PG8_LAS bf16x8*)(lds + PG8_SA(b, h) + aoff + m * 2048 + k * 1024); } while (0)
; #define PG8_MMA(ai, bj, At, Bt) do { __builtin_amdgcn_s_setprio(1); _Pragma("unroll") for (int m = 0; m < 4; ++m) _Pragma("unroll") for (int n = 0; n < 2; ++n) _Pragma("unroll") for (int k = 0; k < 2; ++k) \
;         acc[ai][bj][m][n] = __builtin_amdgcn_mfma_f32_16x16x32_bf16(Bt[n][k], At[m][k], acc[ai][bj][m][n], 0, 0, 0); __builtin_amdgcn_s_setprio(0); } while (0)
; #define PG8_WAIT_V(n) asm volatile("s_waitcnt vmcnt(" #n ")" ::: "memory")
; #define PG8_WAIT_L(n) asm volatile("s_waitcnt lgkmcnt(" #n ")" ::: "memory")
; #define PG8_BAR __builtin_amdgcn_s_barrier()
; #define PG8_SCHED __builtin_amdgcn_sched_barrier(0)
; template <class Epi, class Sched, bool ALIGN_EPI = false, bool SP2 = false>
; __device__ __forceinline__ void gemm_phase(PG8_LAS unsigned char* lds, const Gemm g, const Sched& S, const Epi& E) {
;     ...
;         for (int t = 0; t < nt; t += 2) {
;             const bool last = (t == nt - 2);
;             const char* a1 = cA + (size_t)(t + 1) * kstep;
;             const char* a2 = last ? nA : cA + (size_t)(t + 2) * kstep; const char* b2 = last ? nB : cB + (size_t)(t + 2) * kstep;
;     ...
;             PG8_LDA(At, 1, 1); PG8_STAGE(PG8_SB(1, 0), b3, voffB); PG8_STAGE(PG8_SB(1, 1), b3 + hstep, voffB); PG8_STAGE(PG8_SA(1, 0), a3, voffA);
;             PG8_WAIT_V(8); PG8_WAIT_L(0); PG8_BAR; PG8_MMA(1, 0, At, B0); PG8_MMA(1, 1, At, B1); PG8_BAR; PG8_SCHED;
	s_add_i32 s14, s44, s3
	v_lshl_add_u64 v[218:219], v[218:219], 0, s[8:9]
	s_mov_b32 m0, s14
	ds_read_b128 v[186:189], v152 offset:49152
	ds_read_b128 v[190:193], v152 offset:50176
	ds_read_b128 v[194:197], v152 offset:51200
	ds_read_b128 v[198:201], v152 offset:52224
	ds_read_b128 v[202:205], v152 offset:53248
	ds_read_b128 v[206:209], v152 offset:54272
	ds_read_b128 v[210:213], v152 offset:55296
	ds_read_b128 v[214:217], v152 offset:56320
	global_load_lds_dwordx4 v[218:219], off
	s_add_i32 m0, s14, 0x2000
	s_add_u32 s14, s18, 0x160080
	v_lshl_add_u64 v[218:219], v[220:221], 0, s[8:9]
	s_addc_u32 s15, s19, 0
	s_add_i32 s18, s45, s3
	global_load_lds_dwordx4 v[218:219], off
	s_mov_b32 m0, s18
	s_nop 0
	global_load_lds_dwordx4 v132, s[14:15]
	s_add_i32 m0, s18, 0x2000
	s_nop 0
	global_load_lds_dwordx4 v136, s[14:15]
	v_lshl_add_u64 v[218:219], v[222:223], 0, s[8:9]
	s_mov_b32 m0, s27
	s_nop 0
	global_load_lds_dwordx4 v[218:219], off
	v_lshl_add_u64 v[218:219], v[224:225], 0, s[8:9]
	s_mov_b32 m0, s28
	s_nop 0
	global_load_lds_dwordx4 v[218:219], off
	s_waitcnt vmcnt(8)
	s_waitcnt lgkmcnt(0)
	s_barrier
	s_setprio 1
	s_waitcnt lgkmcnt(0)
	v_mfma_f32_16x16x32_bf16 v[62:65], v[154:157], v[186:189], v[62:65]
	v_mfma_f32_16x16x32_bf16 v[58:61], v[162:165], v[186:189], v[58:61]
	v_mfma_f32_16x16x32_bf16 v[54:57], v[154:157], v[194:197], v[54:57]
	v_mfma_f32_16x16x32_bf16 v[46:49], v[162:165], v[194:197], v[46:49]
	v_mfma_f32_16x16x32_bf16 v[38:41], v[154:157], v[202:205], v[38:41]
	v_mfma_f32_16x16x32_bf16 v[30:33], v[162:165], v[202:205], v[30:33]
	v_mfma_f32_16x16x32_bf16 v[22:25], v[154:157], v[210:213], v[22:25]
	v_mfma_f32_16x16x32_bf16 v[14:17], v[162:165], v[210:213], v[14:17]
	v_mfma_f32_16x16x32_bf16 v[62:65], v[158:161], v[190:193], v[62:65]
	v_mfma_f32_16x16x32_bf16 v[58:61], v[166:169], v[190:193], v[58:61]
	v_mfma_f32_16x16x32_bf16 v[54:57], v[158:161], v[198:201], v[54:57]
	v_mfma_f32_16x16x32_bf16 v[46:49], v[166:169], v[198:201], v[46:49]
	v_mfma_f32_16x16x32_bf16 v[38:41], v[158:161], v[206:209], v[38:41]
	v_mfma_f32_16x16x32_bf16 v[30:33], v[166:169], v[206:209], v[30:33]
	v_mfma_f32_16x16x32_bf16 v[22:25], v[158:161], v[214:217], v[22:25]
	v_mfma_f32_16x16x32_bf16 v[14:17], v[166:169], v[214:217], v[14:17]
	s_setprio 0
	s_setprio 1
	v_mfma_f32_16x16x32_bf16 v[50:53], v[170:173], v[186:189], v[50:53]
	v_mfma_f32_16x16x32_bf16 v[42:45], v[178:181], v[186:189], v[42:45]
	v_mfma_f32_16x16x32_bf16 v[34:37], v[170:173], v[194:197], v[34:37]
	v_mfma_f32_16x16x32_bf16 v[26:29], v[178:181], v[194:197], v[26:29]
	v_mfma_f32_16x16x32_bf16 v[18:21], v[170:173], v[202:205], v[18:21]
	v_mfma_f32_16x16x32_bf16 v[10:13], v[178:181], v[202:205], v[10:13]
	v_mfma_f32_16x16x32_bf16 v[6:9], v[170:173], v[210:213], v[6:9]
	v_mfma_f32_16x16x32_bf16 v[2:5], v[178:181], v[210:213], v[2:5]
	v_mfma_f32_16x16x32_bf16 v[50:53], v[174:177], v[190:193], v[50:53]
	v_mfma_f32_16x16x32_bf16 v[42:45], v[182:185], v[190:193], v[42:45]
	v_mfma_f32_16x16x32_bf16 v[34:37], v[174:177], v[198:201], v[34:37]
	v_mfma_f32_16x16x32_bf16 v[26:29], v[182:185], v[198:201], v[26:29]
	v_mfma_f32_16x16x32_bf16 v[18:21], v[174:177], v[206:209], v[18:21]
	v_mfma_f32_16x16x32_bf16 v[10:13], v[182:185], v[206:209], v[10:13]
	v_mfma_f32_16x16x32_bf16 v[6:9], v[174:177], v[214:217], v[6:9]
	v_mfma_f32_16x16x32_bf16 v[2:5], v[182:185], v[214:217], v[2:5]
	s_setprio 0
	s_barrier
	s_add_i32 s43, s43, 2
	s_add_u32 s39, s39, 0x100
	s_addc_u32 s42, s42, 0
	s_cmpk_gt_u32 s43, 0x55
	s_mov_b64 s[14:15], s[16:17]
	s_cbranch_scc0 .LBB0_448
	s_and_b64 vcc, exec, s[10:11]
	s_cbranch_vccz .LBB0_451
	s_barrier

; #define PG8_STAGE(bufoff, gbase, voff) do { _Pragma("unroll") for (int _i = 0; _i < 2; ++_i) \
;         __builtin_amdgcn_global_load_lds((const unsigned*)((const char*)(gbase) + (voff)[_i]), (PG8_LAS unsigned*)(lds + (bufoff) + ldsw + _i * 8192), 16, 0, 0); } while (0)
; #define PG8_WAIT_V(n) asm volatile("s_waitcnt vmcnt(" #n ")" ::: "memory")
; #define PG8_BAR __builtin_amdgcn_s_barrier()
; template <class Epi, class Sched, bool ALIGN_EPI = false, bool SP2 = false>
; __device__ __forceinline__ void gemm_phase(PG8_LAS unsigned char* lds, const Gemm g, const Sched& S, const Epi& E) {
;     ...
;     const int K = g.K, nt = K / BK;
;     unsigned voffA[2], voffB[2];
; #pragma unroll
;     for (int i = 0; i < 2; ++i) { int R, C; stage_rc(tid * 16 + i * 8192, R, C); const int Rb = Epi::PERM ? ((R & ~31) + perm32(R & 31)) : R;
;         voffA[i] = (unsigned)(R * K + C) * 2u; voffB[i] = (unsigned)(Rb * K + C) * 2u; }
;     const size_t kstep = (size_t)(BK * 2);
;     const size_t hstep = (size_t)HALF * K * 2;
;     const size_t tstep = 2 * hstep;
;     const unsigned ldsw = (unsigned)wid * 1024u;
;     const int aoff = lds_byte(wr * 64 + fr, fq * 8), boff = lds_byte(wc * 32 + fr, fq * 8);
;     ...
;         PG8_STAGE(PG8_SB(1, 0), cB + kstep, voffB); PG8_STAGE(PG8_SA(1, 0), cA + kstep, voffA); PG8_STAGE(PG8_SB(1, 1), cB + hstep + kstep, voffB);
;         PG8_WAIT_V(6); PG8_BAR;
.LBB0_576:
	s_mov_b64 s[42:43], 0x80
	s_and_b32 s8, s3, 3
	s_add_i32 m0, s33, 0x18000
	v_lshl_add_u64 v[8:9], v[8:9], 0, s[42:43]
	s_lshl_b32 s79, s5, 6
	s_lshl_b32 s9, s5, 13
	s_lshl_b32 s11, s8, 12
	s_waitcnt vmcnt(2)
	s_barrier
	global_load_lds_dwordx4 v[8:9], off
	v_lshl_add_u64 v[6:7], v[6:7], 0, s[42:43]
	s_add_i32 m0, s33, 0x1a000
	s_add_i32 s3, s33, 0x8000
	s_add_i32 s82, s33, 0xa000
	global_load_lds_dwordx4 v[6:7], off
	v_lshl_add_u64 v[4:5], v[4:5], 0, s[42:43]
	s_mov_b32 m0, s3
	s_add_u32 s6, s16, 0x80080
	global_load_lds_dwordx4 v[4:5], off
	v_lshl_add_u64 v[2:3], v[2:3], 0, s[42:43]
	s_mov_b32 m0, s82
	s_addc_u32 s7, s17, 0
	global_load_lds_dwordx4 v[2:3], off
	s_add_i32 m0, s33, 0x1c000
	s_nop 0
	global_load_lds_dwordx4 v132, s[6:7]
	v_lshl_add_u64 v[2:3], s[6:7], 0, v[136:137]
	s_add_i32 m0, s33, 0x1e000
	s_cmpk_lt_u32 s4, 0x100
	global_load_lds_dwordx4 v136, s[6:7]
	v_and_b32_e32 v3, 3, v10
	v_lshlrev_b32_e32 v5, 6, v3
	v_lshlrev_b32_e32 v3, 3, v3
	v_lshl_or_b32 v140, s8, 5, v3
	v_cmp_gt_u32_e64 s[6:7], 24, v140
	s_cselect_b64 s[84:85], -1, 0
	v_and_b32_e32 v17, 15, v10
	v_writelane_b32 v254, s6, 51
	v_lshlrev_b32_e32 v138, 2, v140
	v_bfe_u32 v18, v10, 4, 2
	v_writelane_b32 v254, s7, 52
	v_readlane_b32 s6, v253, 0
	v_readlane_b32 s7, v253, 1
	s_ashr_i32 s90, s6, 31
	v_readlane_b32 s6, v253, 4
	v_readlane_b32 s7, v253, 5
	s_ashr_i32 s91, s6, 31
	v_readlane_b32 s6, v254, 27
	v_readlane_b32 s7, v254, 28
	v_lshlrev_b32_e32 v3, 4, v17
	v_bfe_u32 v2, v10, 2, 2
	v_lshl_add_u64 v[142:143], s[6:7], 0, v[138:139]
	v_readlane_b32 s6, v254, 25
	v_lshl_or_b32 v138, v18, 8, v3
	v_readlane_b32 s7, v254, 26
	s_lshl_b32 s4, s5, 2
	v_readlane_b32 s44, v253, 32
	v_lshl_add_u64 v[144:145], s[6:7], 0, v[138:139]
	v_readlane_b32 s6, v254, 23
	v_readlane_b32 s7, v254, 24
	s_or_b32 s4, s4, s8
	v_readlane_b32 s56, v253, 44
	v_lshl_add_u64 v[146:147], s[6:7], 0, v[138:139]
	v_lshlrev_b32_e32 v138, 11, v2
	v_readlane_b32 s57, v253, 45
	v_lshl_or_b32 v175, v18, 2, v2
	s_add_i32 s86, s4, 0xffffff08
	s_add_i32 s87, s4, 0xffffff48
	v_cmp_eq_u32_e64 s[4:5], 3, v2
	v_readlane_b32 s50, v253, 38
	v_lshl_add_u64 v[2:3], s[56:57], 0, v[138:139]
	s_mov_b64 s[6:7], 0xca7e000
	v_readlane_b32 s51, v253, 39
	v_lshl_add_u64 v[148:149], v[2:3], 0, s[6:7]
	s_add_u32 s50, s56, 0xc180000
	v_lshlrev_b32_e32 v2, 15, v11
	v_readlane_b32 s58, v253, 46
	s_addc_u32 s51, s57, 0
	v_and_b32_e32 v2, 0xffff0000, v2
	v_readlane_b32 s59, v253, 47
	s_add_u32 s58, s56, 0x8100000
	v_lshl_add_u32 v2, v12, 12, v2
	v_and_b32_e32 v3, 1, v11
	s_addc_u32 s59, s57, 0
	v_lshl_or_b32 v2, v3, 6, v2
	s_add_u32 s40, s56, 0xf39a000
	v_lshl_add_u32 v150, v13, 1, v2
	v_lshlrev_b32_e32 v2, 15, v14
	v_lshlrev_b32_e32 v19, 4, v18
	v_lshlrev_b32_e32 v20, 2, v10
	v_readlane_b32 s46, v253, 34
	v_readlane_b32 s47, v253, 35
	v_readlane_b32 s48, v253, 36
	v_readlane_b32 s49, v253, 37
	v_readlane_b32 s52, v253, 40
	s_addc_u32 s41, s57, 0
	v_and_b32_e32 v2, 0xffff0000, v2
	v_lshl_or_b32 v19, v17, 6, v19
	v_and_b32_e32 v20, 32, v20
	s_waitcnt vmcnt(6)
	v_readlane_b32 s53, v253, 41
	s_add_u32 s52, s56, 0xf380000
	v_lshl_add_u32 v2, v15, 12, v2
	v_and_b32_e32 v3, 1, v14
	v_readlane_b32 s46, v254, 19
	v_readlane_b32 s48, v254, 21
	v_bitop3_b32 v4, v19, s9, v20 bitop3:0xde
	v_bitop3_b32 v174, v19, s11, v20 bitop3:0xde
	s_addc_u32 s53, s57, 0
	v_lshl_or_b32 v2, v3, 6, v2
	s_add_i32 s83, 0, 0x10000
	s_add_i32 s28, 0, 0x14000
	v_readlane_b32 s47, v254, 20
	v_readlane_b32 s49, v254, 22
	v_writelane_b32 v254, s18, 53
	v_lshl_or_b32 v176, v175, 2, v5
	v_mov_b32_e32 v141, v139
	v_mov_b32_e32 v151, v139
	v_lshl_add_u32 v152, v16, 1, v2
	v_mov_b32_e32 v153, v139
	v_mov_b64_e32 v[154:155], 0xa00
	v_mov_b64_e32 v[156:157], 0x9ff
	v_add_u32_e32 v177, s83, v174
	v_add_u32_e32 v178, s28, v174
	v_add_u32_e32 v179, 0, v4
	s_movk_i32 s93, 0x4080
	s_movk_i32 s75, 0x1a00
	s_movk_i32 s29, 0x3400
	v_mov_b32_e32 v180, 0x7cf
	v_writelane_b32 v254, s19, 54
	s_movk_i32 s78, 0x7ff
	s_barrier
	v_readlane_b32 s45, v253, 33
	v_readlane_b32 s54, v253, 42
	v_readlane_b32 s55, v253, 43
	s_branch .LBB0_579

; #define PG8_STAGE(bufoff, gbase, voff) do { _Pragma("unroll") for (int _i = 0; _i < 2; ++_i) \
;         __builtin_amdgcn_global_load_lds((const unsigned*)((const char*)(gbase) + (voff)[_i]), (PG8_LAS unsigned*)(lds + (bufoff) + ldsw + _i * 8192), 16, 0, 0); } while (0)
; #define PG8_LDA(dst, b, h) do { _Pragma("unroll") for (int m = 0; m < 4; ++m) _Pragma("unroll") for (int k = 0; k < 2; ++k) dst[m][k] = *(const PG8_LAS bf16x8*)(lds + PG8_SA(b, h) + aoff + m * 2048 + k * 1024); } while (0)
; #define PG8_LDB(dst, b, h) do { _Pragma("unroll") for (int n = 0; n < 2; ++n) _Pragma("unroll") for (int k = 0; k < 2; ++k) dst[n][k] = *(const PG8_LAS bf16x8*)(lds + PG8_SB(b, h) + boff + n * 2048 + k * 1024); } while (0)
; #define PG8_MMA(ai, bj, At, Bt) do { __builtin_amdgcn_s_setprio(1); _Pragma("unroll") for (int m = 0; m < 4; ++m) _Pragma("unroll") for (int n = 0; n < 2; ++n) _Pragma("unroll") for (int k = 0; k < 2; ++k) \
;         acc[ai][bj][m][n] = __builtin_amdgcn_mfma_f32_16x16x32_bf16(Bt[n][k], At[m][k], acc[ai][bj][m][n], 0, 0, 0); __builtin_amdgcn_s_setprio(0); } while (0)
; #define PG8_WAIT_V(n) asm volatile("s_waitcnt vmcnt(" #n ")" ::: "memory")
; #define PG8_WAIT_L(n) asm volatile("s_waitcnt lgkmcnt(" #n ")" ::: "memory")
; #define PG8_BAR __builtin_amdgcn_s_barrier()
; #define PG8_SCHED __builtin_amdgcn_sched_barrier(0)
; template <class Epi, class Sched, bool ALIGN_EPI = false, bool SP2 = false>
; __device__ __forceinline__ void gemm_phase(PG8_LAS unsigned char* lds, const Gemm g, const Sched& S, const Epi& E) {
;     ...
;             PG8_LDB(B0, 0, 0); PG8_LDB(B1, 0, 1); PG8_SCHED; PG8_LDA(At, 0, 0); PG8_STAGE(PG8_SA(1, 1), a1 + hstep, voffA);
;             PG8_WAIT_V(8); PG8_WAIT_L(0); PG8_BAR; PG8_MMA(0, 0, At, B0); PG8_MMA(0, 1, At, B1); PG8_BAR; PG8_SCHED;
;             PG8_LDA(At, 0, 1); PG8_STAGE(PG8_SB(0, 0), b2, voffB); PG8_STAGE(PG8_SB(0, 1), b2 + hstep, voffB); PG8_STAGE(PG8_SA(0, 0), a2, voffA);
.LBB0_582:
	ds_read_b128 v[158:161], v177
	ds_read_b128 v[162:165], v177 offset:1024
	ds_read_b128 v[166:169], v177 offset:2048
	ds_read_b128 v[170:173], v177 offset:3072
	ds_read_b128 v[182:185], v178
	ds_read_b128 v[186:189], v178 offset:1024
	ds_read_b128 v[190:193], v178 offset:2048
	ds_read_b128 v[194:197], v178 offset:3072
	s_add_u32 s16, s0, 0xfff80080
	s_addc_u32 s17, s1, -1
	s_cmp_eq_u32 s23, 28
	s_cselect_b32 s19, s7, s17
	s_cselect_b32 s18, s11, s16
	s_cselect_b32 s17, s15, s22
	s_cselect_b32 s16, s20, s21
	v_lshl_add_u64 v[230:231], s[0:1], 0, v[150:151]
	s_add_i32 m0, s33, 0xc000
	ds_read_b128 v[198:201], v179
	ds_read_b128 v[202:205], v179 offset:1024
	ds_read_b128 v[206:209], v179 offset:2048
	ds_read_b128 v[210:213], v179 offset:3072
	ds_read_b128 v[214:217], v179 offset:4096
	ds_read_b128 v[218:221], v179 offset:5120
	ds_read_b128 v[222:225], v179 offset:6144
	ds_read_b128 v[226:229], v179 offset:7168
	global_load_lds_dwordx4 v[230:231], off
	v_lshl_add_u64 v[230:231], s[0:1], 0, v[152:153]
	s_add_i32 m0, s33, 0xe000
	s_nop 0
	global_load_lds_dwordx4 v[230:231], off
	s_waitcnt vmcnt(8)
	s_waitcnt lgkmcnt(0)
	s_barrier
	s_setprio 1
	s_waitcnt lgkmcnt(0)
	v_mfma_f32_16x16x32_bf16 v[126:129], v[158:161], v[198:201], v[126:129]
	v_mfma_f32_16x16x32_bf16 v[122:125], v[166:169], v[198:201], v[122:125]
	v_mfma_f32_16x16x32_bf16 v[110:113], v[158:161], v[206:209], v[110:113]
	v_mfma_f32_16x16x32_bf16 v[106:109], v[166:169], v[206:209], v[106:109]
	v_mfma_f32_16x16x32_bf16 v[94:97], v[158:161], v[214:217], v[94:97]
	v_mfma_f32_16x16x32_bf16 v[90:93], v[166:169], v[214:217], v[90:93]
	v_mfma_f32_16x16x32_bf16 v[78:81], v[158:161], v[222:225], v[78:81]
	v_mfma_f32_16x16x32_bf16 v[74:77], v[166:169], v[222:225], v[74:77]
	v_mfma_f32_16x16x32_bf16 v[126:129], v[162:165], v[202:205], v[126:129]
	v_mfma_f32_16x16x32_bf16 v[122:125], v[170:173], v[202:205], v[122:125]
	v_mfma_f32_16x16x32_bf16 v[110:113], v[162:165], v[210:213], v[110:113]
	v_mfma_f32_16x16x32_bf16 v[106:109], v[170:173], v[210:213], v[106:109]
	v_mfma_f32_16x16x32_bf16 v[94:97], v[162:165], v[218:221], v[94:97]
	v_mfma_f32_16x16x32_bf16 v[90:93], v[170:173], v[218:221], v[90:93]
	v_mfma_f32_16x16x32_bf16 v[78:81], v[162:165], v[226:229], v[78:81]
	v_mfma_f32_16x16x32_bf16 v[74:77], v[170:173], v[226:229], v[74:77]
	s_setprio 0
	s_setprio 1
	v_mfma_f32_16x16x32_bf16 v[118:121], v[182:185], v[198:201], v[118:121]
	v_mfma_f32_16x16x32_bf16 v[114:117], v[190:193], v[198:201], v[114:117]
	v_mfma_f32_16x16x32_bf16 v[102:105], v[182:185], v[206:209], v[102:105]
	v_mfma_f32_16x16x32_bf16 v[98:101], v[190:193], v[206:209], v[98:101]
	v_mfma_f32_16x16x32_bf16 v[86:89], v[182:185], v[214:217], v[86:89]
	v_mfma_f32_16x16x32_bf16 v[82:85], v[190:193], v[214:217], v[82:85]
	v_mfma_f32_16x16x32_bf16 v[70:73], v[182:185], v[222:225], v[70:73]
	v_mfma_f32_16x16x32_bf16 v[66:69], v[190:193], v[222:225], v[66:69]
	v_mfma_f32_16x16x32_bf16 v[118:121], v[186:189], v[202:205], v[118:121]
	v_mfma_f32_16x16x32_bf16 v[114:117], v[194:197], v[202:205], v[114:117]
	v_mfma_f32_16x16x32_bf16 v[102:105], v[186:189], v[210:213], v[102:105]
	v_mfma_f32_16x16x32_bf16 v[98:101], v[194:197], v[210:213], v[98:101]
	v_mfma_f32_16x16x32_bf16 v[86:89], v[186:189], v[218:221], v[86:89]
	v_mfma_f32_16x16x32_bf16 v[82:85], v[194:197], v[218:221], v[82:85]
	v_mfma_f32_16x16x32_bf16 v[70:73], v[186:189], v[226:229], v[70:73]
	v_mfma_f32_16x16x32_bf16 v[66:69], v[194:197], v[226:229], v[66:69]
	s_setprio 0
	s_barrier
	s_add_i32 s24, s83, s2
	v_lshl_add_u64 v[230:231], s[16:17], 0, v[132:133]
	s_mov_b32 m0, s24
	ds_read_b128 v[198:201], v179 offset:16384
	ds_read_b128 v[202:205], v179 offset:17408
	ds_read_b128 v[206:209], v179 offset:18432
	ds_read_b128 v[210:213], v179 offset:19456
	ds_read_b128 v[214:217], v179 offset:20480
	ds_read_b128 v[218:221], v179 offset:21504
	ds_read_b128 v[222:225], v179 offset:22528
	ds_read_b128 v[226:229], v179 offset:23552
	global_load_lds_dwordx4 v132, s[16:17]
	s_add_i32 m0, s24, 0x2000
	s_add_u32 s24, s16, 0x80000
	v_lshl_add_u64 v[232:233], s[16:17], 0, v[136:137]
	s_addc_u32 s25, s17, 0
	s_add_i32 s26, s28, s2
	global_load_lds_dwordx4 v136, s[16:17]
	s_mov_b32 m0, s26
	v_lshl_add_u64 v[236:237], s[18:19], 0, v[134:135]
	global_load_lds_dwordx4 v132, s[24:25]
	s_add_i32 m0, s26, 0x2000
	s_nop 0
	global_load_lds_dwordx4 v136, s[24:25]
	v_lshl_add_u64 v[234:235], s[18:19], 0, v[130:131]
	s_mov_b32 m0, s33
	s_nop 0
	global_load_lds_dwordx4 v130, s[18:19]
	s_mov_b32 m0, s34
	s_nop 0
	global_load_lds_dwordx4 v134, s[18:19]
	s_waitcnt vmcnt(8)
	s_waitcnt lgkmcnt(0)
	s_barrier
; #define PG8_STAGE(bufoff, gbase, voff) do { _Pragma("unroll") for (int _i = 0; _i < 2; ++_i) \
;         __builtin_amdgcn_global_load_lds((const unsigned*)((const char*)(gbase) + (voff)[_i]), (PG8_LAS unsigned*)(lds + (bufoff) + ldsw + _i * 8192), 16, 0, 0); } while (0)
; #define PG8_LDA(dst, b, h) do { _Pragma("unroll") for (int m = 0; m < 4; ++m) _Pragma("unroll") for (int k = 0; k < 2; ++k) dst[m][k] = *(const PG8_LAS bf16x8*)(lds + PG8_SA(b, h) + aoff + m * 2048 + k * 1024); } while (0)
; #define PG8_LDB(dst, b, h) do { _Pragma("unroll") for (int n = 0; n < 2; ++n) _Pragma("unroll") for (int k = 0; k < 2; ++k) dst[n][k] = *(const PG8_LAS bf16x8*)(lds + PG8_SB(b, h) + boff + n * 2048 + k * 1024); } while (0)
; #define PG8_MMA(ai, bj, At, Bt) do { __builtin_amdgcn_s_setprio(1); _Pragma("unroll") for (int m = 0; m < 4; ++m) _Pragma("unroll") for (int n = 0; n < 2; ++n) _Pragma("unroll") for (int k = 0; k < 2; ++k) \
;         acc[ai][bj][m][n] = __builtin_amdgcn_mfma_f32_16x16x32_bf16(Bt[n][k], At[m][k], acc[ai][bj][m][n], 0, 0, 0); __builtin_amdgcn_s_setprio(0); } while (0)
; #define PG8_WAIT_V(n) asm volatile("s_waitcnt vmcnt(" #n ")" ::: "memory")
; #define PG8_WAIT_L(n) asm volatile("s_waitcnt lgkmcnt(" #n ")" ::: "memory")
; #define PG8_BAR __builtin_amdgcn_s_barrier()
; #define PG8_SCHED __builtin_amdgcn_sched_barrier(0)
; template <class Epi, class Sched, bool ALIGN_EPI = false, bool SP2 = false>
; __device__ __forceinline__ void gemm_phase(PG8_LAS unsigned char* lds, const Gemm g, const Sched& S, const Epi& E) {
;     ...
;             PG8_WAIT_V(8); PG8_WAIT_L(0); PG8_BAR; PG8_MMA(1, 0, At, B0); PG8_MMA(1, 1, At, B1); PG8_BAR; PG8_SCHED;
;             PG8_LDB(B0, 1, 0); PG8_LDB(B1, 1, 1); PG8_SCHED; PG8_LDA(At, 1, 0); PG8_STAGE(PG8_SA(0, 1), a2 + hstep, voffA);
;             PG8_WAIT_V(8); PG8_WAIT_L(0); PG8_BAR; PG8_MMA(0, 0, At, B0); PG8_MMA(0, 1, At, B1); PG8_BAR; PG8_SCHED;
	s_setprio 1
	s_waitcnt lgkmcnt(0)
	v_mfma_f32_16x16x32_bf16 v[62:65], v[158:161], v[198:201], v[62:65]
	v_mfma_f32_16x16x32_bf16 v[58:61], v[166:169], v[198:201], v[58:61]
	v_mfma_f32_16x16x32_bf16 v[46:49], v[158:161], v[206:209], v[46:49]
	v_mfma_f32_16x16x32_bf16 v[42:45], v[166:169], v[206:209], v[42:45]
	v_mfma_f32_16x16x32_bf16 v[30:33], v[158:161], v[214:217], v[30:33]
	v_mfma_f32_16x16x32_bf16 v[26:29], v[166:169], v[214:217], v[26:29]
	v_mfma_f32_16x16x32_bf16 v[14:17], v[158:161], v[222:225], v[14:17]
	v_mfma_f32_16x16x32_bf16 v[10:13], v[166:169], v[222:225], v[10:13]
	v_mfma_f32_16x16x32_bf16 v[62:65], v[162:165], v[202:205], v[62:65]
	v_mfma_f32_16x16x32_bf16 v[58:61], v[170:173], v[202:205], v[58:61]
	v_mfma_f32_16x16x32_bf16 v[46:49], v[162:165], v[210:213], v[46:49]
	v_mfma_f32_16x16x32_bf16 v[42:45], v[170:173], v[210:213], v[42:45]
	v_mfma_f32_16x16x32_bf16 v[30:33], v[162:165], v[218:221], v[30:33]
	v_mfma_f32_16x16x32_bf16 v[26:29], v[170:173], v[218:221], v[26:29]
	v_mfma_f32_16x16x32_bf16 v[14:17], v[162:165], v[226:229], v[14:17]
	v_mfma_f32_16x16x32_bf16 v[10:13], v[170:173], v[226:229], v[10:13]
	s_setprio 0
	s_setprio 1
	v_mfma_f32_16x16x32_bf16 v[54:57], v[182:185], v[198:201], v[54:57]
	v_mfma_f32_16x16x32_bf16 v[50:53], v[190:193], v[198:201], v[50:53]
	v_mfma_f32_16x16x32_bf16 v[38:41], v[182:185], v[206:209], v[38:41]
	v_mfma_f32_16x16x32_bf16 v[34:37], v[190:193], v[206:209], v[34:37]
	v_mfma_f32_16x16x32_bf16 v[22:25], v[182:185], v[214:217], v[22:25]
	v_mfma_f32_16x16x32_bf16 v[18:21], v[190:193], v[214:217], v[18:21]
	v_mfma_f32_16x16x32_bf16 v[6:9], v[182:185], v[222:225], v[6:9]
	v_mfma_f32_16x16x32_bf16 v[2:5], v[190:193], v[222:225], v[2:5]
	v_mfma_f32_16x16x32_bf16 v[54:57], v[186:189], v[202:205], v[54:57]
	v_mfma_f32_16x16x32_bf16 v[50:53], v[194:197], v[202:205], v[50:53]
	v_mfma_f32_16x16x32_bf16 v[38:41], v[186:189], v[210:213], v[38:41]
	v_mfma_f32_16x16x32_bf16 v[34:37], v[194:197], v[210:213], v[34:37]
	v_mfma_f32_16x16x32_bf16 v[22:25], v[186:189], v[218:221], v[22:25]
	v_mfma_f32_16x16x32_bf16 v[18:21], v[194:197], v[218:221], v[18:21]
	v_mfma_f32_16x16x32_bf16 v[6:9], v[186:189], v[226:229], v[6:9]
	v_mfma_f32_16x16x32_bf16 v[2:5], v[194:197], v[226:229], v[2:5]
	s_setprio 0
	s_barrier
	s_add_i32 s24, 0, 0x18000
	v_add_u32_e32 v138, s24, v174
	s_add_i32 s25, 0, 0x1c000
	ds_read_b128 v[158:161], v138
	ds_read_b128 v[162:165], v138 offset:1024
	ds_read_b128 v[166:169], v138 offset:2048
	ds_read_b128 v[170:173], v138 offset:3072
	v_add_u32_e32 v138, s25, v174
	ds_read_b128 v[182:185], v138
	ds_read_b128 v[186:189], v138 offset:1024
	ds_read_b128 v[190:193], v138 offset:2048
	ds_read_b128 v[194:197], v138 offset:3072
	s_add_u32 s18, s18, 0x80000
	s_addc_u32 s19, s19, 0
	s_mov_b32 m0, s35
	ds_read_b128 v[198:201], v179 offset:32768
	ds_read_b128 v[202:205], v179 offset:33792
	ds_read_b128 v[206:209], v179 offset:34816
	ds_read_b128 v[210:213], v179 offset:35840
	ds_read_b128 v[214:217], v179 offset:36864
	ds_read_b128 v[218:221], v179 offset:37888
	ds_read_b128 v[222:225], v179 offset:38912
	ds_read_b128 v[226:229], v179 offset:39936
	global_load_lds_dwordx4 v130, s[18:19]
	v_lshl_add_u64 v[238:239], s[18:19], 0, v[134:135]
	s_mov_b32 m0, s36
	s_nop 0
	global_load_lds_dwordx4 v134, s[18:19]
	s_waitcnt vmcnt(8)
	s_waitcnt lgkmcnt(0)
	s_barrier
	s_setprio 1
	s_waitcnt lgkmcnt(0)
	v_mfma_f32_16x16x32_bf16 v[126:129], v[158:161], v[198:201], v[126:129]
	v_mfma_f32_16x16x32_bf16 v[122:125], v[166:169], v[198:201], v[122:125]
	v_mfma_f32_16x16x32_bf16 v[110:113], v[158:161], v[206:209], v[110:113]
	v_mfma_f32_16x16x32_bf16 v[106:109], v[166:169], v[206:209], v[106:109]
	v_mfma_f32_16x16x32_bf16 v[94:97], v[158:161], v[214:217], v[94:97]
	v_mfma_f32_16x16x32_bf16 v[90:93], v[166:169], v[214:217], v[90:93]
	v_mfma_f32_16x16x32_bf16 v[78:81], v[158:161], v[222:225], v[78:81]
	v_mfma_f32_16x16x32_bf16 v[74:77], v[166:169], v[222:225], v[74:77]
	v_mfma_f32_16x16x32_bf16 v[126:129], v[162:165], v[202:205], v[126:129]
	v_mfma_f32_16x16x32_bf16 v[122:125], v[170:173], v[202:205], v[122:125]
	v_mfma_f32_16x16x32_bf16 v[110:113], v[162:165], v[210:213], v[110:113]
	v_mfma_f32_16x16x32_bf16 v[106:109], v[170:173], v[210:213], v[106:109]
	v_mfma_f32_16x16x32_bf16 v[94:97], v[162:165], v[218:221], v[94:97]
	v_mfma_f32_16x16x32_bf16 v[90:93], v[170:173], v[218:221], v[90:93]
	v_mfma_f32_16x16x32_bf16 v[78:81], v[162:165], v[226:229], v[78:81]
	v_mfma_f32_16x16x32_bf16 v[74:77], v[170:173], v[226:229], v[74:77]
	s_setprio 0
	s_setprio 1
	v_mfma_f32_16x16x32_bf16 v[118:121], v[182:185], v[198:201], v[118:121]
	v_mfma_f32_16x16x32_bf16 v[114:117], v[190:193], v[198:201], v[114:117]
	v_mfma_f32_16x16x32_bf16 v[102:105], v[182:185], v[206:209], v[102:105]
	v_mfma_f32_16x16x32_bf16 v[98:101], v[190:193], v[206:209], v[98:101]
	v_mfma_f32_16x16x32_bf16 v[86:89], v[182:185], v[214:217], v[86:89]
	v_mfma_f32_16x16x32_bf16 v[82:85], v[190:193], v[214:217], v[82:85]
	v_mfma_f32_16x16x32_bf16 v[70:73], v[182:185], v[222:225], v[70:73]
	v_mfma_f32_16x16x32_bf16 v[66:69], v[190:193], v[222:225], v[66:69]
	v_mfma_f32_16x16x32_bf16 v[118:121], v[186:189], v[202:205], v[118:121]
	v_mfma_f32_16x16x32_bf16 v[114:117], v[194:197], v[202:205], v[114:117]
	v_mfma_f32_16x16x32_bf16 v[102:105], v[186:189], v[210:213], v[102:105]
	v_mfma_f32_16x16x32_bf16 v[98:101], v[194:197], v[210:213], v[98:101]
	v_mfma_f32_16x16x32_bf16 v[86:89], v[186:189], v[218:221], v[86:89]
	v_mfma_f32_16x16x32_bf16 v[82:85], v[194:197], v[218:221], v[82:85]
	v_mfma_f32_16x16x32_bf16 v[70:73], v[186:189], v[226:229], v[70:73]
	v_mfma_f32_16x16x32_bf16 v[66:69], v[194:197], v[226:229], v[66:69]
	s_setprio 0
	s_barrier
; #define PG8_STAGE(bufoff, gbase, voff) do { _Pragma("unroll") for (int _i = 0; _i < 2; ++_i) \
;         __builtin_amdgcn_global_load_lds((const unsigned*)((const char*)(gbase) + (voff)[_i]), (PG8_LAS unsigned*)(lds + (bufoff) + ldsw + _i * 8192), 16, 0, 0); } while (0)
; #define PG8_LDA(dst, b, h) do { _Pragma("unroll") for (int m = 0; m < 4; ++m) _Pragma("unroll") for (int k = 0; k < 2; ++k) dst[m][k] = *(const PG8_LAS bf16x8*)(lds + PG8_SA(b, h) + aoff + m * 2048 + k * 1024); } while (0)
; #define PG8_MMA(ai, bj, At, Bt) do { __builtin_amdgcn_s_setprio(1); _Pragma("unroll") for (int m = 0; m < 4; ++m) _Pragma("unroll") for (int n = 0; n < 2; ++n) _Pragma("unroll") for (int k = 0; k < 2; ++k) \
;         acc[ai][bj][m][n] = __builtin_amdgcn_mfma_f32_16x16x32_bf16(Bt[n][k], At[m][k], acc[ai][bj][m][n], 0, 0, 0); __builtin_amdgcn_s_setprio(0); } while (0)
; #define PG8_WAIT_V(n) asm volatile("s_waitcnt vmcnt(" #n ")" ::: "memory")
; #define PG8_WAIT_L(n) asm volatile("s_waitcnt lgkmcnt(" #n ")" ::: "memory")
; #define PG8_BAR __builtin_amdgcn_s_barrier()
; #define PG8_SCHED __builtin_amdgcn_sched_barrier(0)
; template <class Epi, class Sched, bool ALIGN_EPI = false, bool SP2 = false>
; __device__ __forceinline__ void gemm_phase(PG8_LAS unsigned char* lds, const Gemm g, const Sched& S, const Epi& E) {
;     ...
;         for (int t = 0; t < nt; t += 2) {
;             const bool last = (t == nt - 2);
;             const char* a1 = cA + (size_t)(t + 1) * kstep;
;             const char* a2 = last ? nA : cA + (size_t)(t + 2) * kstep; const char* b2 = last ? nB : cB + (size_t)(t + 2) * kstep;
;     ...
;             PG8_LDA(At, 1, 1); PG8_STAGE(PG8_SB(1, 0), b3, voffB); PG8_STAGE(PG8_SB(1, 1), b3 + hstep, voffB); PG8_STAGE(PG8_SA(1, 0), a3, voffA);
;             PG8_WAIT_V(8); PG8_WAIT_L(0); PG8_BAR; PG8_MMA(1, 0, At, B0); PG8_MMA(1, 1, At, B1); PG8_BAR; PG8_SCHED;
	s_add_i32 s18, s24, s2
	v_lshl_add_u64 v[230:231], v[230:231], 0, s[42:43]
	s_mov_b32 m0, s18
	ds_read_b128 v[198:201], v179 offset:49152
	ds_read_b128 v[202:205], v179 offset:50176
	ds_read_b128 v[206:209], v179 offset:51200
	ds_read_b128 v[210:213], v179 offset:52224
	ds_read_b128 v[214:217], v179 offset:53248
	ds_read_b128 v[218:221], v179 offset:54272
	ds_read_b128 v[222:225], v179 offset:55296
	ds_read_b128 v[226:229], v179 offset:56320
	global_load_lds_dwordx4 v[230:231], off
	s_add_i32 m0, s18, 0x2000
	s_add_u32 s16, s16, 0x80080
	v_lshl_add_u64 v[230:231], v[232:233], 0, s[42:43]
	s_addc_u32 s17, s17, 0
	s_add_i32 s18, s25, s2
	global_load_lds_dwordx4 v[230:231], off
	s_mov_b32 m0, s18
	s_nop 0
	global_load_lds_dwordx4 v132, s[16:17]
	s_add_i32 m0, s18, 0x2000
	s_nop 0
	global_load_lds_dwordx4 v136, s[16:17]
	v_lshl_add_u64 v[230:231], v[234:235], 0, s[42:43]
	s_mov_b32 m0, s3
	s_nop 0
	global_load_lds_dwordx4 v[230:231], off
	v_lshl_add_u64 v[230:231], v[236:237], 0, s[42:43]
	s_mov_b32 m0, s82
	s_nop 0
	global_load_lds_dwordx4 v[230:231], off
	s_waitcnt vmcnt(8)
	s_waitcnt lgkmcnt(0)
	s_barrier
	s_setprio 1
	s_waitcnt lgkmcnt(0)
	v_mfma_f32_16x16x32_bf16 v[62:65], v[158:161], v[198:201], v[62:65]
	v_mfma_f32_16x16x32_bf16 v[58:61], v[166:169], v[198:201], v[58:61]
	v_mfma_f32_16x16x32_bf16 v[46:49], v[158:161], v[206:209], v[46:49]
	v_mfma_f32_16x16x32_bf16 v[42:45], v[166:169], v[206:209], v[42:45]
	v_mfma_f32_16x16x32_bf16 v[30:33], v[158:161], v[214:217], v[30:33]
	v_mfma_f32_16x16x32_bf16 v[26:29], v[166:169], v[214:217], v[26:29]
	v_mfma_f32_16x16x32_bf16 v[14:17], v[158:161], v[222:225], v[14:17]
	v_mfma_f32_16x16x32_bf16 v[10:13], v[166:169], v[222:225], v[10:13]
	v_mfma_f32_16x16x32_bf16 v[62:65], v[162:165], v[202:205], v[62:65]
	v_mfma_f32_16x16x32_bf16 v[58:61], v[170:173], v[202:205], v[58:61]
	v_mfma_f32_16x16x32_bf16 v[46:49], v[162:165], v[210:213], v[46:49]
	v_mfma_f32_16x16x32_bf16 v[42:45], v[170:173], v[210:213], v[42:45]
	v_mfma_f32_16x16x32_bf16 v[30:33], v[162:165], v[218:221], v[30:33]
	v_mfma_f32_16x16x32_bf16 v[26:29], v[170:173], v[218:221], v[26:29]
	v_mfma_f32_16x16x32_bf16 v[14:17], v[162:165], v[226:229], v[14:17]
	v_mfma_f32_16x16x32_bf16 v[10:13], v[170:173], v[226:229], v[10:13]
	s_setprio 0
	s_setprio 1
	v_mfma_f32_16x16x32_bf16 v[54:57], v[182:185], v[198:201], v[54:57]
	v_mfma_f32_16x16x32_bf16 v[50:53], v[190:193], v[198:201], v[50:53]
	v_mfma_f32_16x16x32_bf16 v[38:41], v[182:185], v[206:209], v[38:41]
	v_mfma_f32_16x16x32_bf16 v[34:37], v[190:193], v[206:209], v[34:37]
	v_mfma_f32_16x16x32_bf16 v[22:25], v[182:185], v[214:217], v[22:25]
	v_mfma_f32_16x16x32_bf16 v[18:21], v[190:193], v[214:217], v[18:21]
	v_mfma_f32_16x16x32_bf16 v[6:9], v[182:185], v[222:225], v[6:9]
	v_mfma_f32_16x16x32_bf16 v[2:5], v[190:193], v[222:225], v[2:5]
	v_mfma_f32_16x16x32_bf16 v[54:57], v[186:189], v[202:205], v[54:57]
	v_mfma_f32_16x16x32_bf16 v[50:53], v[194:197], v[202:205], v[50:53]
	v_mfma_f32_16x16x32_bf16 v[38:41], v[186:189], v[210:213], v[38:41]
	v_mfma_f32_16x16x32_bf16 v[34:37], v[194:197], v[210:213], v[34:37]
	v_mfma_f32_16x16x32_bf16 v[22:25], v[186:189], v[218:221], v[22:25]
	v_mfma_f32_16x16x32_bf16 v[18:21], v[194:197], v[218:221], v[18:21]
	v_mfma_f32_16x16x32_bf16 v[6:9], v[186:189], v[226:229], v[6:9]
	v_mfma_f32_16x16x32_bf16 v[2:5], v[194:197], v[226:229], v[2:5]
	s_setprio 0
	s_barrier
	s_add_i32 s23, s23, 2
	s_add_u32 s0, s0, 0x100
	s_addc_u32 s1, s1, 0
	s_add_u32 s21, s21, 0x100
	s_addc_u32 s22, s22, 0
	s_cmp_gt_u32 s23, 29
	s_cbranch_scc0 .LBB0_582
	s_and_b64 vcc, exec, s[84:85]
	s_cbranch_vccz .LBB0_585
	s_barrier

; #define PG8_STAGE(bufoff, gbase, voff) do { _Pragma("unroll") for (int _i = 0; _i < 2; ++_i) \
;         __builtin_amdgcn_global_load_lds((const unsigned*)((const char*)(gbase) + (voff)[_i]), (PG8_LAS unsigned*)(lds + (bufoff) + ldsw + _i * 8192), 16, 0, 0); } while (0)
; #define PG8_LDA(dst, b, h) do { _Pragma("unroll") for (int m = 0; m < 4; ++m) _Pragma("unroll") for (int k = 0; k < 2; ++k) dst[m][k] = *(const PG8_LAS bf16x8*)(lds + PG8_SA(b, h) + aoff + m * 2048 + k * 1024); } while (0)
; #define PG8_LDB(dst, b, h) do { _Pragma("unroll") for (int n = 0; n < 2; ++n) _Pragma("unroll") for (int k = 0; k < 2; ++k) dst[n][k] = *(const PG8_LAS bf16x8*)(lds + PG8_SB(b, h) + boff + n * 2048 + k * 1024); } while (0)
; #define PG8_MMA(ai, bj, At, Bt) do { __builtin_amdgcn_s_setprio(1); _Pragma("unroll") for (int m = 0; m < 4; ++m) _Pragma("unroll") for (int n = 0; n < 2; ++n) _Pragma("unroll") for (int k = 0; k < 2; ++k) \
;         acc[ai][bj][m][n] = __builtin_amdgcn_mfma_f32_16x16x32_bf16(Bt[n][k], At[m][k], acc[ai][bj][m][n], 0, 0, 0); __builtin_amdgcn_s_setprio(0); } while (0)
; #define PG8_WAIT_V(n) asm volatile("s_waitcnt vmcnt(" #n ")" ::: "memory")
; #define PG8_WAIT_L(n) asm volatile("s_waitcnt lgkmcnt(" #n ")" ::: "memory")
; #define PG8_BAR __builtin_amdgcn_s_barrier()
; #define PG8_SCHED __builtin_amdgcn_sched_barrier(0)
; template <class Epi, class Sched, bool ALIGN_EPI = false, bool SP2 = false>
; __device__ __forceinline__ void gemm_phase(PG8_LAS unsigned char* lds, const Gemm g, const Sched& S, const Epi& E) {
;     ...
;             PG8_LDB(B0, 0, 0); PG8_LDB(B1, 0, 1); PG8_SCHED; PG8_LDA(At, 0, 0); PG8_STAGE(PG8_SA(1, 1), a1 + hstep, voffA);
;             PG8_WAIT_V(8); PG8_WAIT_L(0); PG8_BAR; PG8_MMA(0, 0, At, B0); PG8_MMA(0, 1, At, B1); PG8_BAR; PG8_SCHED;
;             PG8_LDA(At, 0, 1); PG8_STAGE(PG8_SB(0, 0), b2, voffB); PG8_STAGE(PG8_SB(0, 1), b2 + hstep, voffB); PG8_STAGE(PG8_SA(0, 0), a2, voffA);
.LBB0_1465:
	s_add_i32 s85, s84, 2
	s_add_u32 s94, s60, 0x80
	s_addc_u32 s95, s61, 0
	s_add_i32 s54, 0, 0x10000
	s_cmp_eq_u32 s52, s84
	s_cselect_b32 s95, s1, s95
	s_cselect_b32 s94, s0, s94
	s_cselect_b32 vcc_hi, s75, s63
	s_cselect_b32 vcc_lo, s74, s62
	s_add_i32 s55, 0, 0x14000
	v_add_u32_e32 v154, s54, v173
	v_add_u32_e32 v170, s55, v173
	ds_read_b128 v[130:133], v154
	ds_read_b128 v[134:137], v154 offset:1024
	ds_read_b128 v[150:153], v154 offset:2048
	ds_read_b128 v[154:157], v154 offset:3072
	ds_read_b128 v[158:161], v170
	ds_read_b128 v[162:165], v170 offset:1024
	ds_read_b128 v[166:169], v170 offset:2048
	ds_read_b128 v[188:191], v170 offset:3072
	v_lshl_add_u64 v[170:171], s[60:61], 0, v[146:147]
	s_add_i32 m0, s3, 0xc000
	ds_read_b128 v[192:195], v175
	ds_read_b128 v[196:199], v175 offset:1024
	ds_read_b128 v[200:203], v175 offset:2048
	ds_read_b128 v[204:207], v175 offset:3072
	ds_read_b128 v[208:211], v175 offset:4096
	ds_read_b128 v[212:215], v175 offset:5120
	ds_read_b128 v[216:219], v175 offset:6144
	ds_read_b128 v[220:223], v175 offset:7168
	global_load_lds_dwordx4 v[170:171], off
	v_lshl_add_u64 v[170:171], s[60:61], 0, v[148:149]
	s_add_i32 m0, s3, 0xe000
	s_nop 0
	global_load_lds_dwordx4 v[170:171], off
	s_waitcnt vmcnt(8)
	s_waitcnt lgkmcnt(0)
	s_barrier
	s_setprio 1
	s_waitcnt lgkmcnt(0)
	v_mfma_f32_16x16x32_bf16 v[126:129], v[130:133], v[192:195], v[126:129]
	v_mfma_f32_16x16x32_bf16 v[94:97], v[150:153], v[192:195], v[94:97]
	v_mfma_f32_16x16x32_bf16 v[122:125], v[130:133], v[200:203], v[122:125]
	v_mfma_f32_16x16x32_bf16 v[90:93], v[150:153], v[200:203], v[90:93]
	v_mfma_f32_16x16x32_bf16 v[118:121], v[130:133], v[208:211], v[118:121]
	v_mfma_f32_16x16x32_bf16 v[86:89], v[150:153], v[208:211], v[86:89]
	v_mfma_f32_16x16x32_bf16 v[114:117], v[130:133], v[216:219], v[114:117]
	v_mfma_f32_16x16x32_bf16 v[82:85], v[150:153], v[216:219], v[82:85]
	v_mfma_f32_16x16x32_bf16 v[126:129], v[134:137], v[196:199], v[126:129]
	v_mfma_f32_16x16x32_bf16 v[94:97], v[154:157], v[196:199], v[94:97]
	v_mfma_f32_16x16x32_bf16 v[122:125], v[134:137], v[204:207], v[122:125]
	v_mfma_f32_16x16x32_bf16 v[90:93], v[154:157], v[204:207], v[90:93]
	v_mfma_f32_16x16x32_bf16 v[118:121], v[134:137], v[212:215], v[118:121]
	v_mfma_f32_16x16x32_bf16 v[86:89], v[154:157], v[212:215], v[86:89]
	v_mfma_f32_16x16x32_bf16 v[114:117], v[134:137], v[220:223], v[114:117]
	v_mfma_f32_16x16x32_bf16 v[82:85], v[154:157], v[220:223], v[82:85]
	s_setprio 0
	s_setprio 1
	v_mfma_f32_16x16x32_bf16 v[62:65], v[158:161], v[192:195], v[62:65]
	v_mfma_f32_16x16x32_bf16 v[30:33], v[166:169], v[192:195], v[30:33]
	v_mfma_f32_16x16x32_bf16 v[58:61], v[158:161], v[200:203], v[58:61]
	v_mfma_f32_16x16x32_bf16 v[26:29], v[166:169], v[200:203], v[26:29]
	v_mfma_f32_16x16x32_bf16 v[54:57], v[158:161], v[208:211], v[54:57]
	v_mfma_f32_16x16x32_bf16 v[22:25], v[166:169], v[208:211], v[22:25]
	v_mfma_f32_16x16x32_bf16 v[50:53], v[158:161], v[216:219], v[50:53]
	v_mfma_f32_16x16x32_bf16 v[18:21], v[166:169], v[216:219], v[18:21]
	v_mfma_f32_16x16x32_bf16 v[62:65], v[162:165], v[196:199], v[62:65]
	v_mfma_f32_16x16x32_bf16 v[30:33], v[188:191], v[196:199], v[30:33]
	v_mfma_f32_16x16x32_bf16 v[58:61], v[162:165], v[204:207], v[58:61]
	v_mfma_f32_16x16x32_bf16 v[26:29], v[188:191], v[204:207], v[26:29]
	v_mfma_f32_16x16x32_bf16 v[54:57], v[162:165], v[212:215], v[54:57]
	v_mfma_f32_16x16x32_bf16 v[22:25], v[188:191], v[212:215], v[22:25]
	v_mfma_f32_16x16x32_bf16 v[50:53], v[162:165], v[220:223], v[50:53]
	v_mfma_f32_16x16x32_bf16 v[18:21], v[188:191], v[220:223], v[18:21]
	s_setprio 0
	s_barrier
	s_add_i32 s54, s54, s2
	v_lshl_add_u64 v[170:171], vcc, 0, v[142:143]
	s_mov_b32 m0, s54
	ds_read_b128 v[192:195], v175 offset:16384
	ds_read_b128 v[196:199], v175 offset:17408
	ds_read_b128 v[200:203], v175 offset:18432
	ds_read_b128 v[204:207], v175 offset:19456
	ds_read_b128 v[208:211], v175 offset:20480
	ds_read_b128 v[212:215], v175 offset:21504
	ds_read_b128 v[216:219], v175 offset:22528
	ds_read_b128 v[220:223], v175 offset:23552
	global_load_lds_dwordx4 v[170:171], off
	s_add_i32 m0, s54, 0x2000
	v_lshl_add_u64 v[176:177], vcc, 0, v[138:139]
	s_add_u32 vcc_lo, vcc_lo, s10
	s_addc_u32 vcc_hi, vcc_hi, s11
	s_add_i32 s54, s55, s2
	global_load_lds_dwordx4 v[176:177], off
	v_lshl_add_u64 v[224:225], vcc, 0, v[142:143]
	s_mov_b32 m0, s54
	v_lshl_add_u64 v[226:227], vcc, 0, v[138:139]
	global_load_lds_dwordx4 v[224:225], off
	s_add_i32 m0, s54, 0x2000
	v_lshl_add_u64 v[228:229], s[94:95], 0, v[144:145]
	global_load_lds_dwordx4 v[226:227], off
	s_mov_b32 m0, s3
	v_lshl_add_u64 v[230:231], s[94:95], 0, v[140:141]
	global_load_lds_dwordx4 v[228:229], off
	s_mov_b32 m0, s4
	s_nop 0
	global_load_lds_dwordx4 v140, s[94:95]
	s_waitcnt vmcnt(8)
	s_waitcnt lgkmcnt(0)
	s_barrier
; #define PG8_STAGE(bufoff, gbase, voff) do { _Pragma("unroll") for (int _i = 0; _i < 2; ++_i) \
;         __builtin_amdgcn_global_load_lds((const unsigned*)((const char*)(gbase) + (voff)[_i]), (PG8_LAS unsigned*)(lds + (bufoff) + ldsw + _i * 8192), 16, 0, 0); } while (0)
; #define PG8_LDA(dst, b, h) do { _Pragma("unroll") for (int m = 0; m < 4; ++m) _Pragma("unroll") for (int k = 0; k < 2; ++k) dst[m][k] = *(const PG8_LAS bf16x8*)(lds + PG8_SA(b, h) + aoff + m * 2048 + k * 1024); } while (0)
; #define PG8_LDB(dst, b, h) do { _Pragma("unroll") for (int n = 0; n < 2; ++n) _Pragma("unroll") for (int k = 0; k < 2; ++k) dst[n][k] = *(const PG8_LAS bf16x8*)(lds + PG8_SB(b, h) + boff + n * 2048 + k * 1024); } while (0)
; #define PG8_MMA(ai, bj, At, Bt) do { __builtin_amdgcn_s_setprio(1); _Pragma("unroll") for (int m = 0; m < 4; ++m) _Pragma("unroll") for (int n = 0; n < 2; ++n) _Pragma("unroll") for (int k = 0; k < 2; ++k) \
;         acc[ai][bj][m][n] = __builtin_amdgcn_mfma_f32_16x16x32_bf16(Bt[n][k], At[m][k], acc[ai][bj][m][n], 0, 0, 0); __builtin_amdgcn_s_setprio(0); } while (0)
; #define PG8_WAIT_V(n) asm volatile("s_waitcnt vmcnt(" #n ")" ::: "memory")
; #define PG8_WAIT_L(n) asm volatile("s_waitcnt lgkmcnt(" #n ")" ::: "memory")
; #define PG8_BAR __builtin_amdgcn_s_barrier()
; #define PG8_SCHED __builtin_amdgcn_sched_barrier(0)
; template <class Epi, class Sched, bool ALIGN_EPI = false, bool SP2 = false>
; __device__ __forceinline__ void gemm_phase(PG8_LAS unsigned char* lds, const Gemm g, const Sched& S, const Epi& E) {
;     ...
;             PG8_WAIT_V(8); PG8_WAIT_L(0); PG8_BAR; PG8_MMA(1, 0, At, B0); PG8_MMA(1, 1, At, B1); PG8_BAR; PG8_SCHED;
;             PG8_LDB(B0, 1, 0); PG8_LDB(B1, 1, 1); PG8_SCHED; PG8_LDA(At, 1, 0); PG8_STAGE(PG8_SA(0, 1), a2 + hstep, voffA);
;             PG8_WAIT_V(8); PG8_WAIT_L(0); PG8_BAR; PG8_MMA(0, 0, At, B0); PG8_MMA(0, 1, At, B1); PG8_BAR; PG8_SCHED;
	s_setprio 1
	s_waitcnt lgkmcnt(0)
	v_mfma_f32_16x16x32_bf16 v[110:113], v[130:133], v[192:195], v[110:113]
	v_mfma_f32_16x16x32_bf16 v[78:81], v[150:153], v[192:195], v[78:81]
	v_mfma_f32_16x16x32_bf16 v[106:109], v[130:133], v[200:203], v[106:109]
	v_mfma_f32_16x16x32_bf16 v[74:77], v[150:153], v[200:203], v[74:77]
	v_mfma_f32_16x16x32_bf16 v[102:105], v[130:133], v[208:211], v[102:105]
	v_mfma_f32_16x16x32_bf16 v[70:73], v[150:153], v[208:211], v[70:73]
	v_mfma_f32_16x16x32_bf16 v[98:101], v[130:133], v[216:219], v[98:101]
	v_mfma_f32_16x16x32_bf16 v[66:69], v[150:153], v[216:219], v[66:69]
	v_mfma_f32_16x16x32_bf16 v[110:113], v[134:137], v[196:199], v[110:113]
	v_mfma_f32_16x16x32_bf16 v[78:81], v[154:157], v[196:199], v[78:81]
	v_mfma_f32_16x16x32_bf16 v[106:109], v[134:137], v[204:207], v[106:109]
	v_mfma_f32_16x16x32_bf16 v[74:77], v[154:157], v[204:207], v[74:77]
	v_mfma_f32_16x16x32_bf16 v[102:105], v[134:137], v[212:215], v[102:105]
	v_mfma_f32_16x16x32_bf16 v[70:73], v[154:157], v[212:215], v[70:73]
	v_mfma_f32_16x16x32_bf16 v[98:101], v[134:137], v[220:223], v[98:101]
	v_mfma_f32_16x16x32_bf16 v[66:69], v[154:157], v[220:223], v[66:69]
	s_setprio 0
	s_setprio 1
	v_mfma_f32_16x16x32_bf16 v[46:49], v[158:161], v[192:195], v[46:49]
	v_mfma_f32_16x16x32_bf16 v[14:17], v[166:169], v[192:195], v[14:17]
	v_mfma_f32_16x16x32_bf16 v[42:45], v[158:161], v[200:203], v[42:45]
	v_mfma_f32_16x16x32_bf16 v[10:13], v[166:169], v[200:203], v[10:13]
	v_mfma_f32_16x16x32_bf16 v[38:41], v[158:161], v[208:211], v[38:41]
	v_mfma_f32_16x16x32_bf16 v[6:9], v[166:169], v[208:211], v[6:9]
	v_mfma_f32_16x16x32_bf16 v[34:37], v[158:161], v[216:219], v[34:37]
	v_mfma_f32_16x16x32_bf16 v[2:5], v[166:169], v[216:219], v[2:5]
	v_mfma_f32_16x16x32_bf16 v[46:49], v[162:165], v[196:199], v[46:49]
	v_mfma_f32_16x16x32_bf16 v[14:17], v[188:191], v[196:199], v[14:17]
	v_mfma_f32_16x16x32_bf16 v[42:45], v[162:165], v[204:207], v[42:45]
	v_mfma_f32_16x16x32_bf16 v[10:13], v[188:191], v[204:207], v[10:13]
	v_mfma_f32_16x16x32_bf16 v[38:41], v[162:165], v[212:215], v[38:41]
	v_mfma_f32_16x16x32_bf16 v[6:9], v[188:191], v[212:215], v[6:9]
	v_mfma_f32_16x16x32_bf16 v[34:37], v[162:165], v[220:223], v[34:37]
	v_mfma_f32_16x16x32_bf16 v[2:5], v[188:191], v[220:223], v[2:5]
	s_setprio 0
	s_barrier
	s_add_i32 s54, 0, 0x18000
	s_add_i32 s55, 0, 0x1c000
	v_add_u32_e32 v154, s54, v173
	v_add_u32_e32 v180, s55, v173
	ds_read_b128 v[130:133], v154
	ds_read_b128 v[134:137], v154 offset:1024
	ds_read_b128 v[150:153], v154 offset:2048
	ds_read_b128 v[154:157], v154 offset:3072
	ds_read_b128 v[158:161], v180
	ds_read_b128 v[162:165], v180 offset:1024
	ds_read_b128 v[166:169], v180 offset:2048
	ds_read_b128 v[188:191], v180 offset:3072
	s_add_u32 s94, s94, s10
	s_addc_u32 s95, s95, s11
	s_mov_b32 m0, s5
	v_lshl_add_u64 v[232:233], s[94:95], 0, v[144:145]
	ds_read_b128 v[192:195], v175 offset:32768
	ds_read_b128 v[196:199], v175 offset:33792
	ds_read_b128 v[200:203], v175 offset:34816
	ds_read_b128 v[204:207], v175 offset:35840
	ds_read_b128 v[208:211], v175 offset:36864
	ds_read_b128 v[212:215], v175 offset:37888
	ds_read_b128 v[216:219], v175 offset:38912
	ds_read_b128 v[220:223], v175 offset:39936
	global_load_lds_dwordx4 v[232:233], off
	v_lshl_add_u64 v[232:233], s[94:95], 0, v[140:141]
	s_mov_b32 m0, s19
	s_nop 0
	global_load_lds_dwordx4 v140, s[94:95]
	s_waitcnt vmcnt(8)
	s_waitcnt lgkmcnt(0)
	s_barrier
	s_setprio 1
	s_waitcnt lgkmcnt(0)
	v_mfma_f32_16x16x32_bf16 v[126:129], v[130:133], v[192:195], v[126:129]
	v_mfma_f32_16x16x32_bf16 v[94:97], v[150:153], v[192:195], v[94:97]
	v_mfma_f32_16x16x32_bf16 v[122:125], v[130:133], v[200:203], v[122:125]
	v_mfma_f32_16x16x32_bf16 v[90:93], v[150:153], v[200:203], v[90:93]
	v_mfma_f32_16x16x32_bf16 v[118:121], v[130:133], v[208:211], v[118:121]
	v_mfma_f32_16x16x32_bf16 v[86:89], v[150:153], v[208:211], v[86:89]
	v_mfma_f32_16x16x32_bf16 v[114:117], v[130:133], v[216:219], v[114:117]
	v_mfma_f32_16x16x32_bf16 v[82:85], v[150:153], v[216:219], v[82:85]
	v_mfma_f32_16x16x32_bf16 v[126:129], v[134:137], v[196:199], v[126:129]
	v_mfma_f32_16x16x32_bf16 v[94:97], v[154:157], v[196:199], v[94:97]
	v_mfma_f32_16x16x32_bf16 v[122:125], v[134:137], v[204:207], v[122:125]
	v_mfma_f32_16x16x32_bf16 v[90:93], v[154:157], v[204:207], v[90:93]
	v_mfma_f32_16x16x32_bf16 v[118:121], v[134:137], v[212:215], v[118:121]
	v_mfma_f32_16x16x32_bf16 v[86:89], v[154:157], v[212:215], v[86:89]
	v_mfma_f32_16x16x32_bf16 v[114:117], v[134:137], v[220:223], v[114:117]
	v_mfma_f32_16x16x32_bf16 v[82:85], v[154:157], v[220:223], v[82:85]
	s_setprio 0
	s_setprio 1
	v_mfma_f32_16x16x32_bf16 v[62:65], v[158:161], v[192:195], v[62:65]
	v_mfma_f32_16x16x32_bf16 v[30:33], v[166:169], v[192:195], v[30:33]
	v_mfma_f32_16x16x32_bf16 v[58:61], v[158:161], v[200:203], v[58:61]
	v_mfma_f32_16x16x32_bf16 v[26:29], v[166:169], v[200:203], v[26:29]
	v_mfma_f32_16x16x32_bf16 v[54:57], v[158:161], v[208:211], v[54:57]
	v_mfma_f32_16x16x32_bf16 v[22:25], v[166:169], v[208:211], v[22:25]
	v_mfma_f32_16x16x32_bf16 v[50:53], v[158:161], v[216:219], v[50:53]
	v_mfma_f32_16x16x32_bf16 v[18:21], v[166:169], v[216:219], v[18:21]
	v_mfma_f32_16x16x32_bf16 v[62:65], v[162:165], v[196:199], v[62:65]
	v_mfma_f32_16x16x32_bf16 v[30:33], v[188:191], v[196:199], v[30:33]
	v_mfma_f32_16x16x32_bf16 v[58:61], v[162:165], v[204:207], v[58:61]
	v_mfma_f32_16x16x32_bf16 v[26:29], v[188:191], v[204:207], v[26:29]
	v_mfma_f32_16x16x32_bf16 v[54:57], v[162:165], v[212:215], v[54:57]
	v_mfma_f32_16x16x32_bf16 v[22:25], v[188:191], v[212:215], v[22:25]
	v_mfma_f32_16x16x32_bf16 v[50:53], v[162:165], v[220:223], v[50:53]
	v_mfma_f32_16x16x32_bf16 v[18:21], v[188:191], v[220:223], v[18:21]
	s_setprio 0
	s_barrier
; #define PG8_STAGE(bufoff, gbase, voff) do { _Pragma("unroll") for (int _i = 0; _i < 2; ++_i) \
;         __builtin_amdgcn_global_load_lds((const unsigned*)((const char*)(gbase) + (voff)[_i]), (PG8_LAS unsigned*)(lds + (bufoff) + ldsw + _i * 8192), 16, 0, 0); } while (0)
; #define PG8_LDA(dst, b, h) do { _Pragma("unroll") for (int m = 0; m < 4; ++m) _Pragma("unroll") for (int k = 0; k < 2; ++k) dst[m][k] = *(const PG8_LAS bf16x8*)(lds + PG8_SA(b, h) + aoff + m * 2048 + k * 1024); } while (0)
; #define PG8_MMA(ai, bj, At, Bt) do { __builtin_amdgcn_s_setprio(1); _Pragma("unroll") for (int m = 0; m < 4; ++m) _Pragma("unroll") for (int n = 0; n < 2; ++n) _Pragma("unroll") for (int k = 0; k < 2; ++k) \
;         acc[ai][bj][m][n] = __builtin_amdgcn_mfma_f32_16x16x32_bf16(Bt[n][k], At[m][k], acc[ai][bj][m][n], 0, 0, 0); __builtin_amdgcn_s_setprio(0); } while (0)
; #define PG8_WAIT_V(n) asm volatile("s_waitcnt vmcnt(" #n ")" ::: "memory")
; #define PG8_WAIT_L(n) asm volatile("s_waitcnt lgkmcnt(" #n ")" ::: "memory")
; #define PG8_BAR __builtin_amdgcn_s_barrier()
; #define PG8_SCHED __builtin_amdgcn_sched_barrier(0)
; template <class Epi, class Sched, bool ALIGN_EPI = false, bool SP2 = false>
; __device__ __forceinline__ void gemm_phase(PG8_LAS unsigned char* lds, const Gemm g, const Sched& S, const Epi& E) {
;     ...
;         for (int t = 0; t < nt; t += 2) {
;     ...
;             PG8_LDA(At, 1, 1); PG8_STAGE(PG8_SB(1, 0), b3, voffB); PG8_STAGE(PG8_SB(1, 1), b3 + hstep, voffB); PG8_STAGE(PG8_SA(1, 0), a3, voffA);
;             PG8_WAIT_V(8); PG8_WAIT_L(0); PG8_BAR; PG8_MMA(1, 0, At, B0); PG8_MMA(1, 1, At, B1); PG8_BAR; PG8_SCHED;
	s_add_i32 s54, s54, s2
	v_lshl_add_u64 v[170:171], v[170:171], 0, s[42:43]
	s_mov_b32 m0, s54
	ds_read_b128 v[192:195], v175 offset:49152
	ds_read_b128 v[196:199], v175 offset:50176
	ds_read_b128 v[200:203], v175 offset:51200
	ds_read_b128 v[204:207], v175 offset:52224
	ds_read_b128 v[208:211], v175 offset:53248
	ds_read_b128 v[212:215], v175 offset:54272
	ds_read_b128 v[216:219], v175 offset:55296
	ds_read_b128 v[220:223], v175 offset:56320
	global_load_lds_dwordx4 v[170:171], off
	v_lshl_add_u64 v[170:171], v[176:177], 0, s[42:43]
	s_add_i32 m0, s54, 0x2000
	s_add_i32 s54, s55, s2
	global_load_lds_dwordx4 v[170:171], off
	v_lshl_add_u64 v[170:171], v[224:225], 0, s[42:43]
	s_mov_b32 m0, s54
	s_nop 0
	global_load_lds_dwordx4 v[170:171], off
	v_lshl_add_u64 v[170:171], v[226:227], 0, s[42:43]
	s_add_i32 m0, s54, 0x2000
	s_nop 0
	global_load_lds_dwordx4 v[170:171], off
	v_lshl_add_u64 v[170:171], v[228:229], 0, s[42:43]
	s_mov_b32 m0, s26
	s_nop 0
	global_load_lds_dwordx4 v[170:171], off
	v_lshl_add_u64 v[170:171], v[230:231], 0, s[42:43]
	s_mov_b32 m0, s45
	s_nop 0
	global_load_lds_dwordx4 v[170:171], off
	s_waitcnt vmcnt(8)
	s_waitcnt lgkmcnt(0)
	s_barrier
	s_setprio 1
	s_waitcnt lgkmcnt(0)
	v_mfma_f32_16x16x32_bf16 v[110:113], v[130:133], v[192:195], v[110:113]
	v_mfma_f32_16x16x32_bf16 v[78:81], v[150:153], v[192:195], v[78:81]
	v_mfma_f32_16x16x32_bf16 v[106:109], v[130:133], v[200:203], v[106:109]
	v_mfma_f32_16x16x32_bf16 v[74:77], v[150:153], v[200:203], v[74:77]
	v_mfma_f32_16x16x32_bf16 v[102:105], v[130:133], v[208:211], v[102:105]
	v_mfma_f32_16x16x32_bf16 v[70:73], v[150:153], v[208:211], v[70:73]
	v_mfma_f32_16x16x32_bf16 v[98:101], v[130:133], v[216:219], v[98:101]
	v_mfma_f32_16x16x32_bf16 v[66:69], v[150:153], v[216:219], v[66:69]
	v_mfma_f32_16x16x32_bf16 v[110:113], v[134:137], v[196:199], v[110:113]
	v_mfma_f32_16x16x32_bf16 v[78:81], v[154:157], v[196:199], v[78:81]
	v_mfma_f32_16x16x32_bf16 v[106:109], v[134:137], v[204:207], v[106:109]
	v_mfma_f32_16x16x32_bf16 v[74:77], v[154:157], v[204:207], v[74:77]
	v_mfma_f32_16x16x32_bf16 v[102:105], v[134:137], v[212:215], v[102:105]
	v_mfma_f32_16x16x32_bf16 v[70:73], v[154:157], v[212:215], v[70:73]
	v_mfma_f32_16x16x32_bf16 v[98:101], v[134:137], v[220:223], v[98:101]
	v_mfma_f32_16x16x32_bf16 v[66:69], v[154:157], v[220:223], v[66:69]
	s_setprio 0
	s_setprio 1
	v_mfma_f32_16x16x32_bf16 v[46:49], v[158:161], v[192:195], v[46:49]
	v_mfma_f32_16x16x32_bf16 v[14:17], v[166:169], v[192:195], v[14:17]
	v_mfma_f32_16x16x32_bf16 v[42:45], v[158:161], v[200:203], v[42:45]
	v_mfma_f32_16x16x32_bf16 v[10:13], v[166:169], v[200:203], v[10:13]
	v_mfma_f32_16x16x32_bf16 v[38:41], v[158:161], v[208:211], v[38:41]
	v_mfma_f32_16x16x32_bf16 v[6:9], v[166:169], v[208:211], v[6:9]
	v_mfma_f32_16x16x32_bf16 v[34:37], v[158:161], v[216:219], v[34:37]
	v_mfma_f32_16x16x32_bf16 v[2:5], v[166:169], v[216:219], v[2:5]
	v_mfma_f32_16x16x32_bf16 v[46:49], v[162:165], v[196:199], v[46:49]
	v_mfma_f32_16x16x32_bf16 v[14:17], v[188:191], v[196:199], v[14:17]
	v_mfma_f32_16x16x32_bf16 v[42:45], v[162:165], v[204:207], v[42:45]
	v_mfma_f32_16x16x32_bf16 v[10:13], v[188:191], v[204:207], v[10:13]
	v_mfma_f32_16x16x32_bf16 v[38:41], v[162:165], v[212:215], v[38:41]
	v_mfma_f32_16x16x32_bf16 v[6:9], v[188:191], v[212:215], v[6:9]
	v_mfma_f32_16x16x32_bf16 v[34:37], v[162:165], v[220:223], v[34:37]
	v_mfma_f32_16x16x32_bf16 v[2:5], v[188:191], v[220:223], v[2:5]
	s_setprio 0
	s_barrier
	s_add_u32 s60, s60, 0x100
	s_addc_u32 s61, s61, 0
	s_add_u32 s62, s62, 0x100
	s_addc_u32 s63, s63, 0
	s_cmp_ge_i32 s85, s9
	s_mov_b32 s84, s85
	s_cbranch_scc0 .LBB0_1465

; #define PG8_STAGE(bufoff, gbase, voff) do { _Pragma("unroll") for (int _i = 0; _i < 2; ++_i) \
;         __builtin_amdgcn_global_load_lds((const unsigned*)((const char*)(gbase) + (voff)[_i]), (PG8_LAS unsigned*)(lds + (bufoff) + ldsw + _i * 8192), 16, 0, 0); } while (0)
; #define PG8_WAIT_V(n) asm volatile("s_waitcnt vmcnt(" #n ")" ::: "memory")
; #define PG8_BAR __builtin_amdgcn_s_barrier()
; template <class Epi, class Sched, bool ALIGN_EPI = false, bool SP2 = false>
; __device__ __forceinline__ void gemm_phase(PG8_LAS unsigned char* lds, const Gemm g, const Sched& S, const Epi& E) {
;     ...
;     const int K = g.K, nt = K / BK;
;     unsigned voffA[2], voffB[2];
; #pragma unroll
;     for (int i = 0; i < 2; ++i) { int R, C; stage_rc(tid * 16 + i * 8192, R, C); const int Rb = Epi::PERM ? ((R & ~31) + perm32(R & 31)) : R;
;         voffA[i] = (unsigned)(R * K + C) * 2u; voffB[i] = (unsigned)(Rb * K + C) * 2u; }
;     const size_t kstep = (size_t)(BK * 2);
;     const size_t hstep = (size_t)HALF * K * 2;
;     const size_t tstep = 2 * hstep;
;     const unsigned ldsw = (unsigned)wid * 1024u;
;     const int aoff = lds_byte(wr * 64 + fr, fq * 8), boff = lds_byte(wc * 32 + fr, fq * 8);
;     ...
;         PG8_STAGE(PG8_SB(1, 0), cB + kstep, voffB); PG8_STAGE(PG8_SA(1, 0), cA + kstep, voffA); PG8_STAGE(PG8_SB(1, 1), cB + hstep + kstep, voffB);
;         PG8_WAIT_V(6); PG8_BAR;
.LBB0_2518:
	s_mov_b64 s[8:9], 0x80
	s_and_b32 s1, s1, 3
	s_add_i32 m0, s21, 0x18000
	v_lshl_add_u64 v[8:9], v[8:9], 0, s[8:9]
	s_lshl_b32 s11, s12, 13
	s_lshl_b32 s13, s1, 12
	s_waitcnt vmcnt(2)
	s_barrier
	global_load_lds_dwordx4 v[8:9], off
	v_lshl_add_u64 v[6:7], v[6:7], 0, s[8:9]
	s_add_i32 m0, s21, 0x1a000
	s_add_i32 s34, s21, 0x8000
	s_add_i32 s35, s21, 0xa000
	global_load_lds_dwordx4 v[6:7], off
	v_lshl_add_u64 v[2:3], v[2:3], 0, s[8:9]
	s_mov_b32 m0, s34
	s_add_u32 s14, s24, 0x40080
	global_load_lds_dwordx4 v[2:3], off
	v_lshl_add_u64 v[2:3], v[4:5], 0, s[8:9]
	s_mov_b32 m0, s35
	s_addc_u32 s15, s25, 0
	global_load_lds_dwordx4 v[2:3], off
	s_add_i32 m0, s21, 0x1c000
	s_nop 0
	global_load_lds_dwordx4 v140, s[14:15]
	v_lshl_add_u64 v[2:3], s[14:15], 0, v[144:145]
	s_add_i32 m0, s21, 0x1e000
	s_cmpk_lt_u32 s10, 0x100
	global_load_lds_dwordx4 v[2:3], off
	v_and_b32_e32 v2, 15, v1
	v_bfe_u32 v3, v1, 4, 2
	v_lshlrev_b32_e32 v4, 6, v2
	v_lshlrev_b32_e32 v2, 3, v2
	v_lshl_or_b32 v146, v3, 7, v2
	v_lshlrev_b32_e32 v2, 14, v10
	v_and_b32_e32 v2, 0xffff8000, v2
	v_lshl_or_b32 v4, v3, 4, v4
	v_lshl_add_u32 v2, v11, 11, v2
	v_and_b32_e32 v3, 1, v10
	v_lshl_or_b32 v2, v3, 6, v2
	v_lshl_add_u32 v148, v12, 1, v2
	v_lshlrev_b32_e32 v2, 14, v13
	v_lshlrev_b32_e32 v1, 2, v1
	v_and_b32_e32 v2, 0xffff8000, v2
	v_and_b32_e32 v1, 32, v1
	s_waitcnt vmcnt(6)
	v_lshl_add_u32 v2, v14, 11, v2
	v_and_b32_e32 v3, 1, v13
	s_sext_i32_i8 s39, s0
	v_bitop3_b32 v5, v4, s11, v1 bitop3:0xde
	v_bitop3_b32 v1, v4, s13, v1 bitop3:0xde
	s_cselect_b64 s[10:11], -1, 0
	s_lshl_b32 s0, s12, 2
	v_lshl_or_b32 v2, v3, 6, v2
	s_add_i32 s37, 0, 0x10000
	s_add_i32 s38, 0, 0x14000
	s_or_b32 s36, s1, s0
	v_mov_b32_e32 v149, v141
	v_lshl_add_u32 v150, v15, 1, v2
	v_mov_b32_e32 v151, v141
	v_mov_b64_e32 v[152:153], 0x200
	v_mov_b64_e32 v[154:155], 0x1ff
	v_add_u32_e32 v147, s37, v1
	v_add_u32_e32 v162, s38, v1
	v_add_u32_e32 v163, 0, v5
	s_barrier
	s_branch .LBB0_2521

; #define PG8_STAGE(bufoff, gbase, voff) do { _Pragma("unroll") for (int _i = 0; _i < 2; ++_i) \
;         __builtin_amdgcn_global_load_lds((const unsigned*)((const char*)(gbase) + (voff)[_i]), (PG8_LAS unsigned*)(lds + (bufoff) + ldsw + _i * 8192), 16, 0, 0); } while (0)
; #define PG8_LDA(dst, b, h) do { _Pragma("unroll") for (int m = 0; m < 4; ++m) _Pragma("unroll") for (int k = 0; k < 2; ++k) dst[m][k] = *(const PG8_LAS bf16x8*)(lds + PG8_SA(b, h) + aoff + m * 2048 + k * 1024); } while (0)
; #define PG8_LDB(dst, b, h) do { _Pragma("unroll") for (int n = 0; n < 2; ++n) _Pragma("unroll") for (int k = 0; k < 2; ++k) dst[n][k] = *(const PG8_LAS bf16x8*)(lds + PG8_SB(b, h) + boff + n * 2048 + k * 1024); } while (0)
; #define PG8_MMA(ai, bj, At, Bt) do { __builtin_amdgcn_s_setprio(1); _Pragma("unroll") for (int m = 0; m < 4; ++m) _Pragma("unroll") for (int n = 0; n < 2; ++n) _Pragma("unroll") for (int k = 0; k < 2; ++k) \
;         acc[ai][bj][m][n] = __builtin_amdgcn_mfma_f32_16x16x32_bf16(Bt[n][k], At[m][k], acc[ai][bj][m][n], 0, 0, 0); __builtin_amdgcn_s_setprio(0); } while (0)
; #define PG8_WAIT_V(n) asm volatile("s_waitcnt vmcnt(" #n ")" ::: "memory")
; #define PG8_WAIT_L(n) asm volatile("s_waitcnt lgkmcnt(" #n ")" ::: "memory")
; #define PG8_BAR __builtin_amdgcn_s_barrier()
; #define PG8_SCHED __builtin_amdgcn_sched_barrier(0)
; template <class Epi, class Sched, bool ALIGN_EPI = false, bool SP2 = false>
; __device__ __forceinline__ void gemm_phase(PG8_LAS unsigned char* lds, const Gemm g, const Sched& S, const Epi& E) {
;     ...
;             PG8_LDB(B0, 0, 0); PG8_LDB(B1, 0, 1); PG8_SCHED; PG8_LDA(At, 0, 0); PG8_STAGE(PG8_SA(1, 1), a1 + hstep, voffA);
;             PG8_WAIT_V(8); PG8_WAIT_L(0); PG8_BAR; PG8_MMA(0, 0, At, B0); PG8_MMA(0, 1, At, B1); PG8_BAR; PG8_SCHED;
;             PG8_LDA(At, 0, 1); PG8_STAGE(PG8_SB(0, 0), b2, voffB); PG8_STAGE(PG8_SB(0, 1), b2 + hstep, voffB); PG8_STAGE(PG8_SA(0, 0), a2, voffA);
.LBB0_2528:
	ds_read_b128 v[130:133], v147
	ds_read_b128 v[134:137], v147 offset:1024
	ds_read_b128 v[156:159], v147 offset:2048
	ds_read_b128 v[164:167], v147 offset:3072
	ds_read_b128 v[168:171], v162
	ds_read_b128 v[172:175], v162 offset:1024
	ds_read_b128 v[176:179], v162 offset:2048
	ds_read_b128 v[180:183], v162 offset:3072
	s_add_u32 s24, s22, 0xfffc0080
	s_addc_u32 s25, s23, -1
	s_cmp_eq_u32 s44, 12
	s_cselect_b32 s27, s15, s25
	s_cselect_b32 s26, s40, s24
	s_cselect_b32 s25, s13, s43
	s_cselect_b32 s24, s41, s42
	v_lshl_add_u64 v[160:161], s[22:23], 0, v[148:149]
	s_add_i32 m0, s21, 0xc000
	ds_read_b128 v[184:187], v163
	ds_read_b128 v[188:191], v163 offset:1024
	ds_read_b128 v[192:195], v163 offset:2048
	ds_read_b128 v[196:199], v163 offset:3072
	ds_read_b128 v[200:203], v163 offset:4096
	ds_read_b128 v[204:207], v163 offset:5120
	ds_read_b128 v[208:211], v163 offset:6144
	ds_read_b128 v[212:215], v163 offset:7168
	global_load_lds_dwordx4 v[160:161], off
	v_lshl_add_u64 v[160:161], s[22:23], 0, v[150:151]
	s_add_i32 m0, s21, 0xe000
	s_nop 0
	global_load_lds_dwordx4 v[160:161], off
	s_waitcnt vmcnt(8)
	s_waitcnt lgkmcnt(0)
	s_barrier
	s_setprio 1
	s_waitcnt lgkmcnt(0)
	v_mfma_f32_16x16x32_bf16 v[126:129], v[130:133], v[184:187], v[126:129]
	v_mfma_f32_16x16x32_bf16 v[122:125], v[156:159], v[184:187], v[122:125]
	v_mfma_f32_16x16x32_bf16 v[118:121], v[130:133], v[192:195], v[118:121]
	v_mfma_f32_16x16x32_bf16 v[114:117], v[156:159], v[192:195], v[114:117]
	v_mfma_f32_16x16x32_bf16 v[94:97], v[130:133], v[200:203], v[94:97]
	v_mfma_f32_16x16x32_bf16 v[90:93], v[156:159], v[200:203], v[90:93]
	v_mfma_f32_16x16x32_bf16 v[82:85], v[130:133], v[208:211], v[82:85]
	v_mfma_f32_16x16x32_bf16 v[74:77], v[156:159], v[208:211], v[74:77]
	v_mfma_f32_16x16x32_bf16 v[126:129], v[134:137], v[188:191], v[126:129]
	v_mfma_f32_16x16x32_bf16 v[122:125], v[164:167], v[188:191], v[122:125]
	v_mfma_f32_16x16x32_bf16 v[118:121], v[134:137], v[196:199], v[118:121]
	v_mfma_f32_16x16x32_bf16 v[114:117], v[164:167], v[196:199], v[114:117]
	v_mfma_f32_16x16x32_bf16 v[94:97], v[134:137], v[204:207], v[94:97]
	v_mfma_f32_16x16x32_bf16 v[90:93], v[164:167], v[204:207], v[90:93]
	v_mfma_f32_16x16x32_bf16 v[82:85], v[134:137], v[212:215], v[82:85]
	v_mfma_f32_16x16x32_bf16 v[74:77], v[164:167], v[212:215], v[74:77]
	s_setprio 0
	s_setprio 1
	v_mfma_f32_16x16x32_bf16 v[110:113], v[168:171], v[184:187], v[110:113]
	v_mfma_f32_16x16x32_bf16 v[106:109], v[176:179], v[184:187], v[106:109]
	v_mfma_f32_16x16x32_bf16 v[102:105], v[168:171], v[192:195], v[102:105]
	v_mfma_f32_16x16x32_bf16 v[98:101], v[176:179], v[192:195], v[98:101]
	v_mfma_f32_16x16x32_bf16 v[86:89], v[168:171], v[200:203], v[86:89]
	v_mfma_f32_16x16x32_bf16 v[78:81], v[176:179], v[200:203], v[78:81]
	v_mfma_f32_16x16x32_bf16 v[70:73], v[168:171], v[208:211], v[70:73]
	v_mfma_f32_16x16x32_bf16 v[66:69], v[176:179], v[208:211], v[66:69]
	v_mfma_f32_16x16x32_bf16 v[110:113], v[172:175], v[188:191], v[110:113]
	v_mfma_f32_16x16x32_bf16 v[106:109], v[180:183], v[188:191], v[106:109]
	v_mfma_f32_16x16x32_bf16 v[102:105], v[172:175], v[196:199], v[102:105]
	v_mfma_f32_16x16x32_bf16 v[98:101], v[180:183], v[196:199], v[98:101]
	v_mfma_f32_16x16x32_bf16 v[86:89], v[172:175], v[204:207], v[86:89]
	v_mfma_f32_16x16x32_bf16 v[78:81], v[180:183], v[204:207], v[78:81]
	v_mfma_f32_16x16x32_bf16 v[70:73], v[172:175], v[212:215], v[70:73]
	v_mfma_f32_16x16x32_bf16 v[66:69], v[180:183], v[212:215], v[66:69]
	s_setprio 0
	s_barrier
	s_add_i32 s45, s37, s28
	v_lshl_add_u64 v[160:161], s[24:25], 0, v[140:141]
	s_mov_b32 m0, s45
	ds_read_b128 v[184:187], v163 offset:16384
	ds_read_b128 v[188:191], v163 offset:17408
	ds_read_b128 v[192:195], v163 offset:18432
	ds_read_b128 v[196:199], v163 offset:19456
	ds_read_b128 v[200:203], v163 offset:20480
	ds_read_b128 v[204:207], v163 offset:21504
	ds_read_b128 v[208:211], v163 offset:22528
	ds_read_b128 v[212:215], v163 offset:23552
	global_load_lds_dwordx4 v140, s[24:25]
	s_add_i32 m0, s45, 0x2000
	s_add_u32 s46, s24, 0x40000
	v_lshl_add_u64 v[216:217], s[24:25], 0, v[144:145]
	s_addc_u32 s47, s25, 0
	s_add_i32 s45, s38, s28
	global_load_lds_dwordx4 v[216:217], off
	s_mov_b32 m0, s45
	v_lshl_add_u64 v[220:221], s[26:27], 0, v[142:143]
	global_load_lds_dwordx4 v140, s[46:47]
	v_lshl_add_u64 v[218:219], s[46:47], 0, v[144:145]
	s_add_i32 m0, s45, 0x2000
	s_nop 0
	global_load_lds_dwordx4 v[218:219], off
	v_lshl_add_u64 v[218:219], s[26:27], 0, v[138:139]
	s_mov_b32 m0, s21
	s_nop 0
	global_load_lds_dwordx4 v138, s[26:27]
	s_mov_b32 m0, s29
	s_nop 0
	global_load_lds_dwordx4 v[220:221], off
	s_waitcnt vmcnt(8)
	s_waitcnt lgkmcnt(0)
	s_barrier
; #define PG8_STAGE(bufoff, gbase, voff) do { _Pragma("unroll") for (int _i = 0; _i < 2; ++_i) \
;         __builtin_amdgcn_global_load_lds((const unsigned*)((const char*)(gbase) + (voff)[_i]), (PG8_LAS unsigned*)(lds + (bufoff) + ldsw + _i * 8192), 16, 0, 0); } while (0)
; #define PG8_LDA(dst, b, h) do { _Pragma("unroll") for (int m = 0; m < 4; ++m) _Pragma("unroll") for (int k = 0; k < 2; ++k) dst[m][k] = *(const PG8_LAS bf16x8*)(lds + PG8_SA(b, h) + aoff + m * 2048 + k * 1024); } while (0)
; #define PG8_LDB(dst, b, h) do { _Pragma("unroll") for (int n = 0; n < 2; ++n) _Pragma("unroll") for (int k = 0; k < 2; ++k) dst[n][k] = *(const PG8_LAS bf16x8*)(lds + PG8_SB(b, h) + boff + n * 2048 + k * 1024); } while (0)
; #define PG8_MMA(ai, bj, At, Bt) do { __builtin_amdgcn_s_setprio(1); _Pragma("unroll") for (int m = 0; m < 4; ++m) _Pragma("unroll") for (int n = 0; n < 2; ++n) _Pragma("unroll") for (int k = 0; k < 2; ++k) \
;         acc[ai][bj][m][n] = __builtin_amdgcn_mfma_f32_16x16x32_bf16(Bt[n][k], At[m][k], acc[ai][bj][m][n], 0, 0, 0); __builtin_amdgcn_s_setprio(0); } while (0)
; #define PG8_WAIT_V(n) asm volatile("s_waitcnt vmcnt(" #n ")" ::: "memory")
; #define PG8_WAIT_L(n) asm volatile("s_waitcnt lgkmcnt(" #n ")" ::: "memory")
; #define PG8_BAR __builtin_amdgcn_s_barrier()
; #define PG8_SCHED __builtin_amdgcn_sched_barrier(0)
; template <class Epi, class Sched, bool ALIGN_EPI = false, bool SP2 = false>
; __device__ __forceinline__ void gemm_phase(PG8_LAS unsigned char* lds, const Gemm g, const Sched& S, const Epi& E) {
;     ...
;             PG8_WAIT_V(8); PG8_WAIT_L(0); PG8_BAR; PG8_MMA(1, 0, At, B0); PG8_MMA(1, 1, At, B1); PG8_BAR; PG8_SCHED;
;             PG8_LDB(B0, 1, 0); PG8_LDB(B1, 1, 1); PG8_SCHED; PG8_LDA(At, 1, 0); PG8_STAGE(PG8_SA(0, 1), a2 + hstep, voffA);
;             PG8_WAIT_V(8); PG8_WAIT_L(0); PG8_BAR; PG8_MMA(0, 0, At, B0); PG8_MMA(0, 1, At, B1); PG8_BAR; PG8_SCHED;
	s_setprio 1
	s_waitcnt lgkmcnt(0)
	v_mfma_f32_16x16x32_bf16 v[62:65], v[130:133], v[184:187], v[62:65]
	v_mfma_f32_16x16x32_bf16 v[58:61], v[156:159], v[184:187], v[58:61]
	v_mfma_f32_16x16x32_bf16 v[46:49], v[130:133], v[192:195], v[46:49]
	v_mfma_f32_16x16x32_bf16 v[42:45], v[156:159], v[192:195], v[42:45]
	v_mfma_f32_16x16x32_bf16 v[38:41], v[130:133], v[200:203], v[38:41]
	v_mfma_f32_16x16x32_bf16 v[30:33], v[156:159], v[200:203], v[30:33]
	v_mfma_f32_16x16x32_bf16 v[22:25], v[130:133], v[208:211], v[22:25]
	v_mfma_f32_16x16x32_bf16 v[14:17], v[156:159], v[208:211], v[14:17]
	v_mfma_f32_16x16x32_bf16 v[62:65], v[134:137], v[188:191], v[62:65]
	v_mfma_f32_16x16x32_bf16 v[58:61], v[164:167], v[188:191], v[58:61]
	v_mfma_f32_16x16x32_bf16 v[46:49], v[134:137], v[196:199], v[46:49]
	v_mfma_f32_16x16x32_bf16 v[42:45], v[164:167], v[196:199], v[42:45]
	v_mfma_f32_16x16x32_bf16 v[38:41], v[134:137], v[204:207], v[38:41]
	v_mfma_f32_16x16x32_bf16 v[30:33], v[164:167], v[204:207], v[30:33]
	v_mfma_f32_16x16x32_bf16 v[22:25], v[134:137], v[212:215], v[22:25]
	v_mfma_f32_16x16x32_bf16 v[14:17], v[164:167], v[212:215], v[14:17]
	s_setprio 0
	s_setprio 1
	v_mfma_f32_16x16x32_bf16 v[54:57], v[168:171], v[184:187], v[54:57]
	v_mfma_f32_16x16x32_bf16 v[50:53], v[176:179], v[184:187], v[50:53]
	v_mfma_f32_16x16x32_bf16 v[34:37], v[168:171], v[192:195], v[34:37]
	v_mfma_f32_16x16x32_bf16 v[26:29], v[176:179], v[192:195], v[26:29]
	v_mfma_f32_16x16x32_bf16 v[18:21], v[168:171], v[200:203], v[18:21]
	v_mfma_f32_16x16x32_bf16 v[10:13], v[176:179], v[200:203], v[10:13]
	v_mfma_f32_16x16x32_bf16 v[6:9], v[168:171], v[208:211], v[6:9]
	v_mfma_f32_16x16x32_bf16 v[2:5], v[176:179], v[208:211], v[2:5]
	v_mfma_f32_16x16x32_bf16 v[54:57], v[172:175], v[188:191], v[54:57]
	v_mfma_f32_16x16x32_bf16 v[50:53], v[180:183], v[188:191], v[50:53]
	v_mfma_f32_16x16x32_bf16 v[34:37], v[172:175], v[196:199], v[34:37]
	v_mfma_f32_16x16x32_bf16 v[26:29], v[180:183], v[196:199], v[26:29]
	v_mfma_f32_16x16x32_bf16 v[18:21], v[172:175], v[204:207], v[18:21]
	v_mfma_f32_16x16x32_bf16 v[10:13], v[180:183], v[204:207], v[10:13]
	v_mfma_f32_16x16x32_bf16 v[6:9], v[172:175], v[212:215], v[6:9]
	v_mfma_f32_16x16x32_bf16 v[2:5], v[180:183], v[212:215], v[2:5]
	s_setprio 0
	s_barrier
	s_add_i32 s45, 0, 0x18000
	s_add_i32 s46, 0, 0x1c000
	v_add_u32_e32 v164, s45, v1
	v_add_u32_e32 v180, s46, v1
	ds_read_b128 v[130:133], v164
	ds_read_b128 v[134:137], v164 offset:1024
	ds_read_b128 v[156:159], v164 offset:2048
	ds_read_b128 v[164:167], v164 offset:3072
	ds_read_b128 v[168:171], v180
	ds_read_b128 v[172:175], v180 offset:1024
	ds_read_b128 v[176:179], v180 offset:2048
	ds_read_b128 v[180:183], v180 offset:3072
	s_add_u32 s26, s26, 0x40000
	s_addc_u32 s27, s27, 0
	s_mov_b32 m0, s30
	ds_read_b128 v[184:187], v163 offset:32768
	ds_read_b128 v[188:191], v163 offset:33792
	ds_read_b128 v[192:195], v163 offset:34816
	ds_read_b128 v[196:199], v163 offset:35840
	ds_read_b128 v[200:203], v163 offset:36864
	ds_read_b128 v[204:207], v163 offset:37888
	ds_read_b128 v[208:211], v163 offset:38912
	ds_read_b128 v[212:215], v163 offset:39936
	global_load_lds_dwordx4 v138, s[26:27]
	v_lshl_add_u64 v[222:223], s[26:27], 0, v[142:143]
	s_mov_b32 m0, s31
	s_nop 0
	global_load_lds_dwordx4 v[222:223], off
	s_waitcnt vmcnt(8)
	s_waitcnt lgkmcnt(0)
	s_barrier
	s_setprio 1
	s_waitcnt lgkmcnt(0)
	v_mfma_f32_16x16x32_bf16 v[126:129], v[130:133], v[184:187], v[126:129]
	v_mfma_f32_16x16x32_bf16 v[122:125], v[156:159], v[184:187], v[122:125]
	v_mfma_f32_16x16x32_bf16 v[118:121], v[130:133], v[192:195], v[118:121]
	v_mfma_f32_16x16x32_bf16 v[114:117], v[156:159], v[192:195], v[114:117]
	v_mfma_f32_16x16x32_bf16 v[94:97], v[130:133], v[200:203], v[94:97]
	v_mfma_f32_16x16x32_bf16 v[90:93], v[156:159], v[200:203], v[90:93]
	v_mfma_f32_16x16x32_bf16 v[82:85], v[130:133], v[208:211], v[82:85]
	v_mfma_f32_16x16x32_bf16 v[74:77], v[156:159], v[208:211], v[74:77]
	v_mfma_f32_16x16x32_bf16 v[126:129], v[134:137], v[188:191], v[126:129]
	v_mfma_f32_16x16x32_bf16 v[122:125], v[164:167], v[188:191], v[122:125]
	v_mfma_f32_16x16x32_bf16 v[118:121], v[134:137], v[196:199], v[118:121]
	v_mfma_f32_16x16x32_bf16 v[114:117], v[164:167], v[196:199], v[114:117]
	v_mfma_f32_16x16x32_bf16 v[94:97], v[134:137], v[204:207], v[94:97]
	v_mfma_f32_16x16x32_bf16 v[90:93], v[164:167], v[204:207], v[90:93]
	v_mfma_f32_16x16x32_bf16 v[82:85], v[134:137], v[212:215], v[82:85]
	v_mfma_f32_16x16x32_bf16 v[74:77], v[164:167], v[212:215], v[74:77]
	s_setprio 0
	s_setprio 1
	v_mfma_f32_16x16x32_bf16 v[110:113], v[168:171], v[184:187], v[110:113]
	v_mfma_f32_16x16x32_bf16 v[106:109], v[176:179], v[184:187], v[106:109]
	v_mfma_f32_16x16x32_bf16 v[102:105], v[168:171], v[192:195], v[102:105]
	v_mfma_f32_16x16x32_bf16 v[98:101], v[176:179], v[192:195], v[98:101]
	v_mfma_f32_16x16x32_bf16 v[86:89], v[168:171], v[200:203], v[86:89]
	v_mfma_f32_16x16x32_bf16 v[78:81], v[176:179], v[200:203], v[78:81]
	v_mfma_f32_16x16x32_bf16 v[70:73], v[168:171], v[208:211], v[70:73]
	v_mfma_f32_16x16x32_bf16 v[66:69], v[176:179], v[208:211], v[66:69]
	v_mfma_f32_16x16x32_bf16 v[110:113], v[172:175], v[188:191], v[110:113]
	v_mfma_f32_16x16x32_bf16 v[106:109], v[180:183], v[188:191], v[106:109]
	v_mfma_f32_16x16x32_bf16 v[102:105], v[172:175], v[196:199], v[102:105]
	v_mfma_f32_16x16x32_bf16 v[98:101], v[180:183], v[196:199], v[98:101]
	v_mfma_f32_16x16x32_bf16 v[86:89], v[172:175], v[204:207], v[86:89]
	v_mfma_f32_16x16x32_bf16 v[78:81], v[180:183], v[204:207], v[78:81]
	v_mfma_f32_16x16x32_bf16 v[70:73], v[172:175], v[212:215], v[70:73]
	v_mfma_f32_16x16x32_bf16 v[66:69], v[180:183], v[212:215], v[66:69]
	s_setprio 0
	s_barrier
; #define PG8_STAGE(bufoff, gbase, voff) do { _Pragma("unroll") for (int _i = 0; _i < 2; ++_i) \
;         __builtin_amdgcn_global_load_lds((const unsigned*)((const char*)(gbase) + (voff)[_i]), (PG8_LAS unsigned*)(lds + (bufoff) + ldsw + _i * 8192), 16, 0, 0); } while (0)
; #define PG8_LDA(dst, b, h) do { _Pragma("unroll") for (int m = 0; m < 4; ++m) _Pragma("unroll") for (int k = 0; k < 2; ++k) dst[m][k] = *(const PG8_LAS bf16x8*)(lds + PG8_SA(b, h) + aoff + m * 2048 + k * 1024); } while (0)
; #define PG8_MMA(ai, bj, At, Bt) do { __builtin_amdgcn_s_setprio(1); _Pragma("unroll") for (int m = 0; m < 4; ++m) _Pragma("unroll") for (int n = 0; n < 2; ++n) _Pragma("unroll") for (int k = 0; k < 2; ++k) \
;         acc[ai][bj][m][n] = __builtin_amdgcn_mfma_f32_16x16x32_bf16(Bt[n][k], At[m][k], acc[ai][bj][m][n], 0, 0, 0); __builtin_amdgcn_s_setprio(0); } while (0)
; #define PG8_WAIT_V(n) asm volatile("s_waitcnt vmcnt(" #n ")" ::: "memory")
; #define PG8_WAIT_L(n) asm volatile("s_waitcnt lgkmcnt(" #n ")" ::: "memory")
; #define PG8_BAR __builtin_amdgcn_s_barrier()
; #define PG8_SCHED __builtin_amdgcn_sched_barrier(0)
; template <class Epi, class Sched, bool ALIGN_EPI = false, bool SP2 = false>
; __device__ __forceinline__ void gemm_phase(PG8_LAS unsigned char* lds, const Gemm g, const Sched& S, const Epi& E) {
;     ...
;         for (int t = 0; t < nt; t += 2) {
;             const bool last = (t == nt - 2);
;             const char* a1 = cA + (size_t)(t + 1) * kstep;
;             const char* a2 = last ? nA : cA + (size_t)(t + 2) * kstep; const char* b2 = last ? nB : cB + (size_t)(t + 2) * kstep;
;     ...
;             PG8_LDA(At, 1, 1); PG8_STAGE(PG8_SB(1, 0), b3, voffB); PG8_STAGE(PG8_SB(1, 1), b3 + hstep, voffB); PG8_STAGE(PG8_SA(1, 0), a3, voffA);
;             PG8_WAIT_V(8); PG8_WAIT_L(0); PG8_BAR; PG8_MMA(1, 0, At, B0); PG8_MMA(1, 1, At, B1); PG8_BAR; PG8_SCHED;
	s_add_i32 s26, s45, s28
	v_lshl_add_u64 v[160:161], v[160:161], 0, s[8:9]
	s_mov_b32 m0, s26
	ds_read_b128 v[184:187], v163 offset:49152
	ds_read_b128 v[188:191], v163 offset:50176
	ds_read_b128 v[192:195], v163 offset:51200
	ds_read_b128 v[196:199], v163 offset:52224
	ds_read_b128 v[200:203], v163 offset:53248
	ds_read_b128 v[204:207], v163 offset:54272
	ds_read_b128 v[208:211], v163 offset:55296
	ds_read_b128 v[212:215], v163 offset:56320
	global_load_lds_dwordx4 v[160:161], off
	s_add_i32 m0, s26, 0x2000
	s_add_u32 s24, s24, 0x40080
	v_lshl_add_u64 v[160:161], v[216:217], 0, s[8:9]
	s_addc_u32 s25, s25, 0
	s_add_i32 s26, s46, s28
	global_load_lds_dwordx4 v[160:161], off
	s_mov_b32 m0, s26
	s_nop 0
	global_load_lds_dwordx4 v140, s[24:25]
	v_lshl_add_u64 v[160:161], s[24:25], 0, v[144:145]
	s_add_i32 m0, s26, 0x2000
	s_nop 0
	global_load_lds_dwordx4 v[160:161], off
	v_lshl_add_u64 v[160:161], v[218:219], 0, s[8:9]
	s_mov_b32 m0, s34
	s_nop 0
	global_load_lds_dwordx4 v[160:161], off
	v_lshl_add_u64 v[160:161], v[220:221], 0, s[8:9]
	s_mov_b32 m0, s35
	s_nop 0
	global_load_lds_dwordx4 v[160:161], off
	s_waitcnt vmcnt(8)
	s_waitcnt lgkmcnt(0)
	s_barrier
	s_setprio 1
	s_waitcnt lgkmcnt(0)
	v_mfma_f32_16x16x32_bf16 v[62:65], v[130:133], v[184:187], v[62:65]
	v_mfma_f32_16x16x32_bf16 v[58:61], v[156:159], v[184:187], v[58:61]
	v_mfma_f32_16x16x32_bf16 v[46:49], v[130:133], v[192:195], v[46:49]
	v_mfma_f32_16x16x32_bf16 v[42:45], v[156:159], v[192:195], v[42:45]
	v_mfma_f32_16x16x32_bf16 v[38:41], v[130:133], v[200:203], v[38:41]
	v_mfma_f32_16x16x32_bf16 v[30:33], v[156:159], v[200:203], v[30:33]
	v_mfma_f32_16x16x32_bf16 v[22:25], v[130:133], v[208:211], v[22:25]
	v_mfma_f32_16x16x32_bf16 v[14:17], v[156:159], v[208:211], v[14:17]
	v_mfma_f32_16x16x32_bf16 v[62:65], v[134:137], v[188:191], v[62:65]
	v_mfma_f32_16x16x32_bf16 v[58:61], v[164:167], v[188:191], v[58:61]
	v_mfma_f32_16x16x32_bf16 v[46:49], v[134:137], v[196:199], v[46:49]
	v_mfma_f32_16x16x32_bf16 v[42:45], v[164:167], v[196:199], v[42:45]
	v_mfma_f32_16x16x32_bf16 v[38:41], v[134:137], v[204:207], v[38:41]
	v_mfma_f32_16x16x32_bf16 v[30:33], v[164:167], v[204:207], v[30:33]
	v_mfma_f32_16x16x32_bf16 v[22:25], v[134:137], v[212:215], v[22:25]
	v_mfma_f32_16x16x32_bf16 v[14:17], v[164:167], v[212:215], v[14:17]
	s_setprio 0
	s_setprio 1
	v_mfma_f32_16x16x32_bf16 v[54:57], v[168:171], v[184:187], v[54:57]
	v_mfma_f32_16x16x32_bf16 v[50:53], v[176:179], v[184:187], v[50:53]
	v_mfma_f32_16x16x32_bf16 v[34:37], v[168:171], v[192:195], v[34:37]
	v_mfma_f32_16x16x32_bf16 v[26:29], v[176:179], v[192:195], v[26:29]
	v_mfma_f32_16x16x32_bf16 v[18:21], v[168:171], v[200:203], v[18:21]
	v_mfma_f32_16x16x32_bf16 v[10:13], v[176:179], v[200:203], v[10:13]
	v_mfma_f32_16x16x32_bf16 v[6:9], v[168:171], v[208:211], v[6:9]
	v_mfma_f32_16x16x32_bf16 v[2:5], v[176:179], v[208:211], v[2:5]
	v_mfma_f32_16x16x32_bf16 v[54:57], v[172:175], v[188:191], v[54:57]
	v_mfma_f32_16x16x32_bf16 v[50:53], v[180:183], v[188:191], v[50:53]
	v_mfma_f32_16x16x32_bf16 v[34:37], v[172:175], v[196:199], v[34:37]
	v_mfma_f32_16x16x32_bf16 v[26:29], v[180:183], v[196:199], v[26:29]
	v_mfma_f32_16x16x32_bf16 v[18:21], v[172:175], v[204:207], v[18:21]
	v_mfma_f32_16x16x32_bf16 v[10:13], v[180:183], v[204:207], v[10:13]
	v_mfma_f32_16x16x32_bf16 v[6:9], v[172:175], v[212:215], v[6:9]
	v_mfma_f32_16x16x32_bf16 v[2:5], v[180:183], v[212:215], v[2:5]
	s_setprio 0
	s_barrier
	s_add_i32 s44, s44, 2
	s_add_u32 s22, s22, 0x100
	s_addc_u32 s23, s23, 0
	s_add_u32 s42, s42, 0x100
	s_addc_u32 s43, s43, 0
	s_cmp_gt_u32 s44, 13
	s_cbranch_scc0 .LBB0_2528
	s_and_b64 vcc, exec, s[10:11]
	s_cbranch_vccz .LBB0_2531
	s_barrier

; #define PG8_STAGE(bufoff, gbase, voff) do { _Pragma("unroll") for (int _i = 0; _i < 2; ++_i) \
;         __builtin_amdgcn_global_load_lds((const unsigned*)((const char*)(gbase) + (voff)[_i]), (PG8_LAS unsigned*)(lds + (bufoff) + ldsw + _i * 8192), 16, 0, 0); } while (0)
; #define PG8_WAIT_V(n) asm volatile("s_waitcnt vmcnt(" #n ")" ::: "memory")
; #define PG8_BAR __builtin_amdgcn_s_barrier()
; template <class Epi, class Sched, bool ALIGN_EPI = false, bool SP2 = false>
; __device__ __forceinline__ void gemm_phase(PG8_LAS unsigned char* lds, const Gemm g, const Sched& S, const Epi& E) {
;     ...
;     const int K = g.K, nt = K / BK;
;     unsigned voffA[2], voffB[2];
; #pragma unroll
;     for (int i = 0; i < 2; ++i) { int R, C; stage_rc(tid * 16 + i * 8192, R, C); const int Rb = Epi::PERM ? ((R & ~31) + perm32(R & 31)) : R;
;         voffA[i] = (unsigned)(R * K + C) * 2u; voffB[i] = (unsigned)(Rb * K + C) * 2u; }
;     const size_t kstep = (size_t)(BK * 2);
;     const size_t hstep = (size_t)HALF * K * 2;
;     const size_t tstep = 2 * hstep;
;     const unsigned ldsw = (unsigned)wid * 1024u;
;     const int aoff = lds_byte(wr * 64 + fr, fq * 8), boff = lds_byte(wc * 32 + fr, fq * 8);
;     ...
;         PG8_STAGE(PG8_SB(1, 0), cB + kstep, voffB); PG8_STAGE(PG8_SA(1, 0), cA + kstep, voffA); PG8_STAGE(PG8_SB(1, 1), cB + hstep + kstep, voffB);
;         PG8_WAIT_V(6); PG8_BAR;
.LBB0_2549:
	s_mov_b64 s[10:11], 0x80
	s_and_b32 s1, s1, 3
	s_add_i32 m0, s3, 0x18000
	v_lshl_add_u64 v[8:9], v[8:9], 0, s[10:11]
	s_lshl_b32 s13, s14, 13
	s_lshl_b32 s15, s1, 12
	s_waitcnt vmcnt(2)
	s_barrier
	global_load_lds_dwordx4 v[8:9], off
	v_lshl_add_u64 v[6:7], v[6:7], 0, s[10:11]
	s_add_i32 m0, s3, 0x1a000
	s_add_i32 s35, s3, 0x8000
	s_add_i32 s36, s3, 0xa000
	global_load_lds_dwordx4 v[6:7], off
	v_lshl_add_u64 v[2:3], v[2:3], 0, s[10:11]
	s_mov_b32 m0, s35
	s_add_u32 s16, s26, 0x40080
	global_load_lds_dwordx4 v[2:3], off
	v_lshl_add_u64 v[2:3], v[4:5], 0, s[10:11]
	s_mov_b32 m0, s36
	s_addc_u32 s17, s27, 0
	global_load_lds_dwordx4 v[2:3], off
	s_add_i32 m0, s3, 0x1c000
	s_nop 0
	global_load_lds_dwordx4 v132, s[16:17]
	v_lshl_add_u64 v[2:3], s[16:17], 0, v[136:137]
	s_add_i32 m0, s3, 0x1e000
	v_lshlrev_b32_e32 v4, 2, v10
	global_load_lds_dwordx4 v136, s[16:17]
	v_bfe_u32 v3, v10, 4, 2
	v_and_b32_e32 v2, 15, v10
	v_lshlrev_b32_e32 v1, 4, v3
	v_lshl_or_b32 v1, v2, 6, v1
	v_lshlrev_b32_e32 v2, 3, v2
	v_and_b32_e32 v4, 32, v4
	v_lshl_or_b32 v138, v3, 7, v2
	v_lshlrev_b32_e32 v2, 14, v11
	v_bitop3_b32 v5, v1, s13, v4 bitop3:0xde
	v_bitop3_b32 v1, v1, s15, v4 bitop3:0xde
	v_bfe_u32 v4, v10, 2, 2
	v_and_b32_e32 v2, 0xffff8000, v2
	v_lshl_or_b32 v4, v3, 2, v4
	v_lshl_add_u32 v2, v12, 11, v2
	v_and_b32_e32 v3, 1, v11
	v_lshl_or_b32 v2, v3, 6, v2
	v_lshl_add_u32 v140, v13, 1, v2
	v_lshlrev_b32_e32 v2, 14, v14
	v_and_b32_e32 v6, 3, v10
	v_and_b32_e32 v2, 0xffff8000, v2
	s_waitcnt vmcnt(6)
	s_cmpk_lt_u32 s12, 0x100
	v_lshlrev_b32_e32 v7, 6, v6
	v_lshl_add_u32 v2, v15, 11, v2
	v_and_b32_e32 v3, 1, v14
	s_sext_i32_i8 s23, s0
	s_cselect_b64 s[12:13], -1, 0
	v_lshl_or_b32 v139, v4, 2, v7
	v_lshl_or_b32 v154, s14, 6, v4
	v_lshlrev_b32_e32 v4, 3, v6
	s_lshl_b32 s0, s14, 2
	v_lshl_or_b32 v2, v3, 6, v2
	s_add_i32 s38, 0, 0x10000
	s_add_i32 s39, 0, 0x14000
	v_lshl_or_b32 v155, s1, 5, v4
	s_or_b32 s37, s1, s0
	v_mov_b32_e32 v141, v133
	v_lshl_add_u32 v142, v16, 1, v2
	v_mov_b32_e32 v143, v133
	v_mov_b64_e32 v[144:145], 0x200
	v_mov_b64_e32 v[146:147], 0x1ff
	v_add_u32_e32 v156, s38, v1
	v_add_u32_e32 v157, s39, v1
	v_add_u32_e32 v158, 0, v5
	s_barrier
	s_branch .LBB0_2552

; #define PG8_STAGE(bufoff, gbase, voff) do { _Pragma("unroll") for (int _i = 0; _i < 2; ++_i) \
;         __builtin_amdgcn_global_load_lds((const unsigned*)((const char*)(gbase) + (voff)[_i]), (PG8_LAS unsigned*)(lds + (bufoff) + ldsw + _i * 8192), 16, 0, 0); } while (0)
; #define PG8_LDA(dst, b, h) do { _Pragma("unroll") for (int m = 0; m < 4; ++m) _Pragma("unroll") for (int k = 0; k < 2; ++k) dst[m][k] = *(const PG8_LAS bf16x8*)(lds + PG8_SA(b, h) + aoff + m * 2048 + k * 1024); } while (0)
; #define PG8_LDB(dst, b, h) do { _Pragma("unroll") for (int n = 0; n < 2; ++n) _Pragma("unroll") for (int k = 0; k < 2; ++k) dst[n][k] = *(const PG8_LAS bf16x8*)(lds + PG8_SB(b, h) + boff + n * 2048 + k * 1024); } while (0)
; #define PG8_MMA(ai, bj, At, Bt) do { __builtin_amdgcn_s_setprio(1); _Pragma("unroll") for (int m = 0; m < 4; ++m) _Pragma("unroll") for (int n = 0; n < 2; ++n) _Pragma("unroll") for (int k = 0; k < 2; ++k) \
;         acc[ai][bj][m][n] = __builtin_amdgcn_mfma_f32_16x16x32_bf16(Bt[n][k], At[m][k], acc[ai][bj][m][n], 0, 0, 0); __builtin_amdgcn_s_setprio(0); } while (0)
; #define PG8_WAIT_V(n) asm volatile("s_waitcnt vmcnt(" #n ")" ::: "memory")
; #define PG8_WAIT_L(n) asm volatile("s_waitcnt lgkmcnt(" #n ")" ::: "memory")
; #define PG8_BAR __builtin_amdgcn_s_barrier()
; #define PG8_SCHED __builtin_amdgcn_sched_barrier(0)
; template <class Epi, class Sched, bool ALIGN_EPI = false, bool SP2 = false>
; __device__ __forceinline__ void gemm_phase(PG8_LAS unsigned char* lds, const Gemm g, const Sched& S, const Epi& E) {
;     ...
;             PG8_LDB(B0, 0, 0); PG8_LDB(B1, 0, 1); PG8_SCHED; PG8_LDA(At, 0, 0); PG8_STAGE(PG8_SA(1, 1), a1 + hstep, voffA);
;             PG8_WAIT_V(8); PG8_WAIT_L(0); PG8_BAR; PG8_MMA(0, 0, At, B0); PG8_MMA(0, 1, At, B1); PG8_BAR; PG8_SCHED;
;             PG8_LDA(At, 0, 1); PG8_STAGE(PG8_SB(0, 0), b2, voffB); PG8_STAGE(PG8_SB(0, 1), b2 + hstep, voffB); PG8_STAGE(PG8_SA(0, 0), a2, voffA);
.LBB0_2559:
	ds_read_b128 v[148:151], v156
	ds_read_b128 v[160:163], v156 offset:1024
	ds_read_b128 v[164:167], v156 offset:2048
	ds_read_b128 v[168:171], v156 offset:3072
	ds_read_b128 v[172:175], v157
	ds_read_b128 v[176:179], v157 offset:1024
	ds_read_b128 v[180:183], v157 offset:2048
	ds_read_b128 v[184:187], v157 offset:3072
	s_add_u32 s26, s24, 0xfffc0080
	s_addc_u32 s27, s25, -1
	s_cmp_eq_u32 s44, 12
	s_cselect_b32 s29, s17, s27
	s_cselect_b32 s28, s40, s26
	s_cselect_b32 s27, s15, s43
	s_cselect_b32 s26, s41, s42
	s_add_i32 m0, s3, 0xc000
	ds_read_b128 v[188:191], v158
	ds_read_b128 v[192:195], v158 offset:1024
	ds_read_b128 v[196:199], v158 offset:2048
	ds_read_b128 v[200:203], v158 offset:3072
	ds_read_b128 v[204:207], v158 offset:4096
	ds_read_b128 v[208:211], v158 offset:5120
	ds_read_b128 v[212:215], v158 offset:6144
	ds_read_b128 v[216:219], v158 offset:7168
	global_load_lds_dwordx4 v140, s[24:25]
	v_lshl_add_u64 v[152:153], s[24:25], 0, v[142:143]
	s_add_i32 m0, s3, 0xe000
	s_nop 0
	global_load_lds_dwordx4 v[152:153], off
	s_waitcnt vmcnt(8)
	s_waitcnt lgkmcnt(0)
	s_barrier
	s_setprio 1
	s_waitcnt lgkmcnt(0)
	v_mfma_f32_16x16x32_bf16 v[126:129], v[148:151], v[188:191], v[126:129]
	v_mfma_f32_16x16x32_bf16 v[122:125], v[164:167], v[188:191], v[122:125]
	v_mfma_f32_16x16x32_bf16 v[110:113], v[148:151], v[196:199], v[110:113]
	v_mfma_f32_16x16x32_bf16 v[106:109], v[164:167], v[196:199], v[106:109]
	v_mfma_f32_16x16x32_bf16 v[94:97], v[148:151], v[204:207], v[94:97]
	v_mfma_f32_16x16x32_bf16 v[90:93], v[164:167], v[204:207], v[90:93]
	v_mfma_f32_16x16x32_bf16 v[78:81], v[148:151], v[212:215], v[78:81]
	v_mfma_f32_16x16x32_bf16 v[74:77], v[164:167], v[212:215], v[74:77]
	v_mfma_f32_16x16x32_bf16 v[126:129], v[160:163], v[192:195], v[126:129]
	v_mfma_f32_16x16x32_bf16 v[122:125], v[168:171], v[192:195], v[122:125]
	v_mfma_f32_16x16x32_bf16 v[110:113], v[160:163], v[200:203], v[110:113]
	v_mfma_f32_16x16x32_bf16 v[106:109], v[168:171], v[200:203], v[106:109]
	v_mfma_f32_16x16x32_bf16 v[94:97], v[160:163], v[208:211], v[94:97]
	v_mfma_f32_16x16x32_bf16 v[90:93], v[168:171], v[208:211], v[90:93]
	v_mfma_f32_16x16x32_bf16 v[78:81], v[160:163], v[216:219], v[78:81]
	v_mfma_f32_16x16x32_bf16 v[74:77], v[168:171], v[216:219], v[74:77]
	s_setprio 0
	s_setprio 1
	v_mfma_f32_16x16x32_bf16 v[118:121], v[172:175], v[188:191], v[118:121]
	v_mfma_f32_16x16x32_bf16 v[114:117], v[180:183], v[188:191], v[114:117]
	v_mfma_f32_16x16x32_bf16 v[102:105], v[172:175], v[196:199], v[102:105]
	v_mfma_f32_16x16x32_bf16 v[98:101], v[180:183], v[196:199], v[98:101]
	v_mfma_f32_16x16x32_bf16 v[86:89], v[172:175], v[204:207], v[86:89]
	v_mfma_f32_16x16x32_bf16 v[82:85], v[180:183], v[204:207], v[82:85]
	v_mfma_f32_16x16x32_bf16 v[70:73], v[172:175], v[212:215], v[70:73]
	v_mfma_f32_16x16x32_bf16 v[66:69], v[180:183], v[212:215], v[66:69]
	v_mfma_f32_16x16x32_bf16 v[118:121], v[176:179], v[192:195], v[118:121]
	v_mfma_f32_16x16x32_bf16 v[114:117], v[184:187], v[192:195], v[114:117]
	v_mfma_f32_16x16x32_bf16 v[102:105], v[176:179], v[200:203], v[102:105]
	v_mfma_f32_16x16x32_bf16 v[98:101], v[184:187], v[200:203], v[98:101]
	v_mfma_f32_16x16x32_bf16 v[86:89], v[176:179], v[208:211], v[86:89]
	v_mfma_f32_16x16x32_bf16 v[82:85], v[184:187], v[208:211], v[82:85]
	v_mfma_f32_16x16x32_bf16 v[70:73], v[176:179], v[216:219], v[70:73]
	v_mfma_f32_16x16x32_bf16 v[66:69], v[184:187], v[216:219], v[66:69]
	s_setprio 0
	s_barrier
	s_add_i32 s45, s38, s2
	v_lshl_add_u64 v[152:153], s[26:27], 0, v[132:133]
	s_mov_b32 m0, s45
	ds_read_b128 v[188:191], v158 offset:16384
	ds_read_b128 v[192:195], v158 offset:17408
	ds_read_b128 v[196:199], v158 offset:18432
	ds_read_b128 v[200:203], v158 offset:19456
	ds_read_b128 v[204:207], v158 offset:20480
	ds_read_b128 v[208:211], v158 offset:21504
	ds_read_b128 v[212:215], v158 offset:22528
	ds_read_b128 v[216:219], v158 offset:23552
	global_load_lds_dwordx4 v132, s[26:27]
	s_add_i32 m0, s45, 0x2000
	s_add_u32 s46, s26, 0x40000
	v_lshl_add_u64 v[220:221], s[26:27], 0, v[136:137]
	s_addc_u32 s47, s27, 0
	s_add_i32 s45, s39, s2
	global_load_lds_dwordx4 v136, s[26:27]
	s_mov_b32 m0, s45
	v_lshl_add_u64 v[224:225], s[28:29], 0, v[134:135]
	global_load_lds_dwordx4 v132, s[46:47]
	s_add_i32 m0, s45, 0x2000
	s_nop 0
	global_load_lds_dwordx4 v136, s[46:47]
	v_lshl_add_u64 v[222:223], s[28:29], 0, v[130:131]
	s_mov_b32 m0, s3
	s_nop 0
	global_load_lds_dwordx4 v130, s[28:29]
	s_mov_b32 m0, s30
	s_nop 0
	global_load_lds_dwordx4 v134, s[28:29]
	s_waitcnt vmcnt(8)
	s_waitcnt lgkmcnt(0)
	s_barrier
; #define PG8_STAGE(bufoff, gbase, voff) do { _Pragma("unroll") for (int _i = 0; _i < 2; ++_i) \
;         __builtin_amdgcn_global_load_lds((const unsigned*)((const char*)(gbase) + (voff)[_i]), (PG8_LAS unsigned*)(lds + (bufoff) + ldsw + _i * 8192), 16, 0, 0); } while (0)
; #define PG8_LDA(dst, b, h) do { _Pragma("unroll") for (int m = 0; m < 4; ++m) _Pragma("unroll") for (int k = 0; k < 2; ++k) dst[m][k] = *(const PG8_LAS bf16x8*)(lds + PG8_SA(b, h) + aoff + m * 2048 + k * 1024); } while (0)
; #define PG8_LDB(dst, b, h) do { _Pragma("unroll") for (int n = 0; n < 2; ++n) _Pragma("unroll") for (int k = 0; k < 2; ++k) dst[n][k] = *(const PG8_LAS bf16x8*)(lds + PG8_SB(b, h) + boff + n * 2048 + k * 1024); } while (0)
; #define PG8_MMA(ai, bj, At, Bt) do { __builtin_amdgcn_s_setprio(1); _Pragma("unroll") for (int m = 0; m < 4; ++m) _Pragma("unroll") for (int n = 0; n < 2; ++n) _Pragma("unroll") for (int k = 0; k < 2; ++k) \
;         acc[ai][bj][m][n] = __builtin_amdgcn_mfma_f32_16x16x32_bf16(Bt[n][k], At[m][k], acc[ai][bj][m][n], 0, 0, 0); __builtin_amdgcn_s_setprio(0); } while (0)
; #define PG8_WAIT_V(n) asm volatile("s_waitcnt vmcnt(" #n ")" ::: "memory")
; #define PG8_WAIT_L(n) asm volatile("s_waitcnt lgkmcnt(" #n ")" ::: "memory")
; #define PG8_BAR __builtin_amdgcn_s_barrier()
; #define PG8_SCHED __builtin_amdgcn_sched_barrier(0)
; template <class Epi, class Sched, bool ALIGN_EPI = false, bool SP2 = false>
; __device__ __forceinline__ void gemm_phase(PG8_LAS unsigned char* lds, const Gemm g, const Sched& S, const Epi& E) {
;     ...
;             PG8_WAIT_V(8); PG8_WAIT_L(0); PG8_BAR; PG8_MMA(1, 0, At, B0); PG8_MMA(1, 1, At, B1); PG8_BAR; PG8_SCHED;
;             PG8_LDB(B0, 1, 0); PG8_LDB(B1, 1, 1); PG8_SCHED; PG8_LDA(At, 1, 0); PG8_STAGE(PG8_SA(0, 1), a2 + hstep, voffA);
;             PG8_WAIT_V(8); PG8_WAIT_L(0); PG8_BAR; PG8_MMA(0, 0, At, B0); PG8_MMA(0, 1, At, B1); PG8_BAR; PG8_SCHED;
	s_setprio 1
	s_waitcnt lgkmcnt(0)
	v_mfma_f32_16x16x32_bf16 v[62:65], v[148:151], v[188:191], v[62:65]
	v_mfma_f32_16x16x32_bf16 v[58:61], v[164:167], v[188:191], v[58:61]
	v_mfma_f32_16x16x32_bf16 v[46:49], v[148:151], v[196:199], v[46:49]
	v_mfma_f32_16x16x32_bf16 v[42:45], v[164:167], v[196:199], v[42:45]
	v_mfma_f32_16x16x32_bf16 v[30:33], v[148:151], v[204:207], v[30:33]
	v_mfma_f32_16x16x32_bf16 v[26:29], v[164:167], v[204:207], v[26:29]
	v_mfma_f32_16x16x32_bf16 v[14:17], v[148:151], v[212:215], v[14:17]
	v_mfma_f32_16x16x32_bf16 v[10:13], v[164:167], v[212:215], v[10:13]
	v_mfma_f32_16x16x32_bf16 v[62:65], v[160:163], v[192:195], v[62:65]
	v_mfma_f32_16x16x32_bf16 v[58:61], v[168:171], v[192:195], v[58:61]
	v_mfma_f32_16x16x32_bf16 v[46:49], v[160:163], v[200:203], v[46:49]
	v_mfma_f32_16x16x32_bf16 v[42:45], v[168:171], v[200:203], v[42:45]
	v_mfma_f32_16x16x32_bf16 v[30:33], v[160:163], v[208:211], v[30:33]
	v_mfma_f32_16x16x32_bf16 v[26:29], v[168:171], v[208:211], v[26:29]
	v_mfma_f32_16x16x32_bf16 v[14:17], v[160:163], v[216:219], v[14:17]
	v_mfma_f32_16x16x32_bf16 v[10:13], v[168:171], v[216:219], v[10:13]
	s_setprio 0
	s_setprio 1
	v_mfma_f32_16x16x32_bf16 v[54:57], v[172:175], v[188:191], v[54:57]
	v_mfma_f32_16x16x32_bf16 v[50:53], v[180:183], v[188:191], v[50:53]
	v_mfma_f32_16x16x32_bf16 v[38:41], v[172:175], v[196:199], v[38:41]
	v_mfma_f32_16x16x32_bf16 v[34:37], v[180:183], v[196:199], v[34:37]
	v_mfma_f32_16x16x32_bf16 v[22:25], v[172:175], v[204:207], v[22:25]
	v_mfma_f32_16x16x32_bf16 v[18:21], v[180:183], v[204:207], v[18:21]
	v_mfma_f32_16x16x32_bf16 v[6:9], v[172:175], v[212:215], v[6:9]
	v_mfma_f32_16x16x32_bf16 v[2:5], v[180:183], v[212:215], v[2:5]
	v_mfma_f32_16x16x32_bf16 v[54:57], v[176:179], v[192:195], v[54:57]
	v_mfma_f32_16x16x32_bf16 v[50:53], v[184:187], v[192:195], v[50:53]
	v_mfma_f32_16x16x32_bf16 v[38:41], v[176:179], v[200:203], v[38:41]
	v_mfma_f32_16x16x32_bf16 v[34:37], v[184:187], v[200:203], v[34:37]
	v_mfma_f32_16x16x32_bf16 v[22:25], v[176:179], v[208:211], v[22:25]
	v_mfma_f32_16x16x32_bf16 v[18:21], v[184:187], v[208:211], v[18:21]
	v_mfma_f32_16x16x32_bf16 v[6:9], v[176:179], v[216:219], v[6:9]
	v_mfma_f32_16x16x32_bf16 v[2:5], v[184:187], v[216:219], v[2:5]
	s_setprio 0
	s_barrier
	s_add_i32 s45, 0, 0x18000
	v_add_u32_e32 v159, s45, v1
	s_add_i32 s46, 0, 0x1c000
	ds_read_b128 v[148:151], v159
	ds_read_b128 v[160:163], v159 offset:1024
	ds_read_b128 v[164:167], v159 offset:2048
	ds_read_b128 v[168:171], v159 offset:3072
	v_add_u32_e32 v159, s46, v1
	ds_read_b128 v[172:175], v159
	ds_read_b128 v[176:179], v159 offset:1024
	ds_read_b128 v[180:183], v159 offset:2048
	ds_read_b128 v[184:187], v159 offset:3072
	s_add_u32 s28, s28, 0x40000
	s_addc_u32 s29, s29, 0
	s_mov_b32 m0, s31
	ds_read_b128 v[188:191], v158 offset:32768
	ds_read_b128 v[192:195], v158 offset:33792
	ds_read_b128 v[196:199], v158 offset:34816
	ds_read_b128 v[200:203], v158 offset:35840
	ds_read_b128 v[204:207], v158 offset:36864
	ds_read_b128 v[208:211], v158 offset:37888
	ds_read_b128 v[212:215], v158 offset:38912
	ds_read_b128 v[216:219], v158 offset:39936
	global_load_lds_dwordx4 v130, s[28:29]
	v_lshl_add_u64 v[226:227], s[28:29], 0, v[134:135]
	s_mov_b32 m0, s33
	s_nop 0
	global_load_lds_dwordx4 v134, s[28:29]
	s_waitcnt vmcnt(8)
	s_waitcnt lgkmcnt(0)
	s_barrier
	s_setprio 1
	s_waitcnt lgkmcnt(0)
	v_mfma_f32_16x16x32_bf16 v[126:129], v[148:151], v[188:191], v[126:129]
	v_mfma_f32_16x16x32_bf16 v[122:125], v[164:167], v[188:191], v[122:125]
	v_mfma_f32_16x16x32_bf16 v[110:113], v[148:151], v[196:199], v[110:113]
	v_mfma_f32_16x16x32_bf16 v[106:109], v[164:167], v[196:199], v[106:109]
	v_mfma_f32_16x16x32_bf16 v[94:97], v[148:151], v[204:207], v[94:97]
	v_mfma_f32_16x16x32_bf16 v[90:93], v[164:167], v[204:207], v[90:93]
	v_mfma_f32_16x16x32_bf16 v[78:81], v[148:151], v[212:215], v[78:81]
	v_mfma_f32_16x16x32_bf16 v[74:77], v[164:167], v[212:215], v[74:77]
	v_mfma_f32_16x16x32_bf16 v[126:129], v[160:163], v[192:195], v[126:129]
	v_mfma_f32_16x16x32_bf16 v[122:125], v[168:171], v[192:195], v[122:125]
	v_mfma_f32_16x16x32_bf16 v[110:113], v[160:163], v[200:203], v[110:113]
	v_mfma_f32_16x16x32_bf16 v[106:109], v[168:171], v[200:203], v[106:109]
	v_mfma_f32_16x16x32_bf16 v[94:97], v[160:163], v[208:211], v[94:97]
	v_mfma_f32_16x16x32_bf16 v[90:93], v[168:171], v[208:211], v[90:93]
	v_mfma_f32_16x16x32_bf16 v[78:81], v[160:163], v[216:219], v[78:81]
	v_mfma_f32_16x16x32_bf16 v[74:77], v[168:171], v[216:219], v[74:77]
	s_setprio 0
	s_setprio 1
	v_mfma_f32_16x16x32_bf16 v[118:121], v[172:175], v[188:191], v[118:121]
	v_mfma_f32_16x16x32_bf16 v[114:117], v[180:183], v[188:191], v[114:117]
	v_mfma_f32_16x16x32_bf16 v[102:105], v[172:175], v[196:199], v[102:105]
	v_mfma_f32_16x16x32_bf16 v[98:101], v[180:183], v[196:199], v[98:101]
	v_mfma_f32_16x16x32_bf16 v[86:89], v[172:175], v[204:207], v[86:89]
	v_mfma_f32_16x16x32_bf16 v[82:85], v[180:183], v[204:207], v[82:85]
	v_mfma_f32_16x16x32_bf16 v[70:73], v[172:175], v[212:215], v[70:73]
	v_mfma_f32_16x16x32_bf16 v[66:69], v[180:183], v[212:215], v[66:69]
	v_mfma_f32_16x16x32_bf16 v[118:121], v[176:179], v[192:195], v[118:121]
	v_mfma_f32_16x16x32_bf16 v[114:117], v[184:187], v[192:195], v[114:117]
	v_mfma_f32_16x16x32_bf16 v[102:105], v[176:179], v[200:203], v[102:105]
	v_mfma_f32_16x16x32_bf16 v[98:101], v[184:187], v[200:203], v[98:101]
	v_mfma_f32_16x16x32_bf16 v[86:89], v[176:179], v[208:211], v[86:89]
	v_mfma_f32_16x16x32_bf16 v[82:85], v[184:187], v[208:211], v[82:85]
	v_mfma_f32_16x16x32_bf16 v[70:73], v[176:179], v[216:219], v[70:73]
	v_mfma_f32_16x16x32_bf16 v[66:69], v[184:187], v[216:219], v[66:69]
	s_setprio 0
	s_barrier
; #define PG8_STAGE(bufoff, gbase, voff) do { _Pragma("unroll") for (int _i = 0; _i < 2; ++_i) \
;         __builtin_amdgcn_global_load_lds((const unsigned*)((const char*)(gbase) + (voff)[_i]), (PG8_LAS unsigned*)(lds + (bufoff) + ldsw + _i * 8192), 16, 0, 0); } while (0)
; #define PG8_LDA(dst, b, h) do { _Pragma("unroll") for (int m = 0; m < 4; ++m) _Pragma("unroll") for (int k = 0; k < 2; ++k) dst[m][k] = *(const PG8_LAS bf16x8*)(lds + PG8_SA(b, h) + aoff + m * 2048 + k * 1024); } while (0)
; #define PG8_MMA(ai, bj, At, Bt) do { __builtin_amdgcn_s_setprio(1); _Pragma("unroll") for (int m = 0; m < 4; ++m) _Pragma("unroll") for (int n = 0; n < 2; ++n) _Pragma("unroll") for (int k = 0; k < 2; ++k) \
;         acc[ai][bj][m][n] = __builtin_amdgcn_mfma_f32_16x16x32_bf16(Bt[n][k], At[m][k], acc[ai][bj][m][n], 0, 0, 0); __builtin_amdgcn_s_setprio(0); } while (0)
; #define PG8_WAIT_V(n) asm volatile("s_waitcnt vmcnt(" #n ")" ::: "memory")
; #define PG8_WAIT_L(n) asm volatile("s_waitcnt lgkmcnt(" #n ")" ::: "memory")
; #define PG8_BAR __builtin_amdgcn_s_barrier()
; #define PG8_SCHED __builtin_amdgcn_sched_barrier(0)
; template <class Epi, class Sched, bool ALIGN_EPI = false, bool SP2 = false>
; __device__ __forceinline__ void gemm_phase(PG8_LAS unsigned char* lds, const Gemm g, const Sched& S, const Epi& E) {
;     ...
;         for (int t = 0; t < nt; t += 2) {
;             const bool last = (t == nt - 2);
;             const char* a1 = cA + (size_t)(t + 1) * kstep;
;             const char* a2 = last ? nA : cA + (size_t)(t + 2) * kstep; const char* b2 = last ? nB : cB + (size_t)(t + 2) * kstep;
;     ...
;             PG8_LDA(At, 1, 1); PG8_STAGE(PG8_SB(1, 0), b3, voffB); PG8_STAGE(PG8_SB(1, 1), b3 + hstep, voffB); PG8_STAGE(PG8_SA(1, 0), a3, voffA);
;             PG8_WAIT_V(8); PG8_WAIT_L(0); PG8_BAR; PG8_MMA(1, 0, At, B0); PG8_MMA(1, 1, At, B1); PG8_BAR; PG8_SCHED;
	s_add_i32 s28, s45, s2
	v_lshl_add_u64 v[152:153], v[152:153], 0, s[10:11]
	s_mov_b32 m0, s28
	ds_read_b128 v[188:191], v158 offset:49152
	ds_read_b128 v[192:195], v158 offset:50176
	ds_read_b128 v[196:199], v158 offset:51200
	ds_read_b128 v[200:203], v158 offset:52224
	ds_read_b128 v[204:207], v158 offset:53248
	ds_read_b128 v[208:211], v158 offset:54272
	ds_read_b128 v[212:215], v158 offset:55296
	ds_read_b128 v[216:219], v158 offset:56320
	global_load_lds_dwordx4 v[152:153], off
	s_add_i32 m0, s28, 0x2000
	s_add_u32 s26, s26, 0x40080
	v_lshl_add_u64 v[152:153], v[220:221], 0, s[10:11]
	s_addc_u32 s27, s27, 0
	s_add_i32 s28, s46, s2
	global_load_lds_dwordx4 v[152:153], off
	s_mov_b32 m0, s28
	s_nop 0
	global_load_lds_dwordx4 v132, s[26:27]
	s_add_i32 m0, s28, 0x2000
	s_nop 0
	global_load_lds_dwordx4 v136, s[26:27]
	v_lshl_add_u64 v[152:153], v[222:223], 0, s[10:11]
	s_mov_b32 m0, s35
	s_nop 0
	global_load_lds_dwordx4 v[152:153], off
	v_lshl_add_u64 v[152:153], v[224:225], 0, s[10:11]
	s_mov_b32 m0, s36
	s_nop 0
	global_load_lds_dwordx4 v[152:153], off
	s_waitcnt vmcnt(8)
	s_waitcnt lgkmcnt(0)
	s_barrier
	s_setprio 1
	s_waitcnt lgkmcnt(0)
	v_mfma_f32_16x16x32_bf16 v[62:65], v[148:151], v[188:191], v[62:65]
	v_mfma_f32_16x16x32_bf16 v[58:61], v[164:167], v[188:191], v[58:61]
	v_mfma_f32_16x16x32_bf16 v[46:49], v[148:151], v[196:199], v[46:49]
	v_mfma_f32_16x16x32_bf16 v[42:45], v[164:167], v[196:199], v[42:45]
	v_mfma_f32_16x16x32_bf16 v[30:33], v[148:151], v[204:207], v[30:33]
	v_mfma_f32_16x16x32_bf16 v[26:29], v[164:167], v[204:207], v[26:29]
	v_mfma_f32_16x16x32_bf16 v[14:17], v[148:151], v[212:215], v[14:17]
	v_mfma_f32_16x16x32_bf16 v[10:13], v[164:167], v[212:215], v[10:13]
	v_mfma_f32_16x16x32_bf16 v[62:65], v[160:163], v[192:195], v[62:65]
	v_mfma_f32_16x16x32_bf16 v[58:61], v[168:171], v[192:195], v[58:61]
	v_mfma_f32_16x16x32_bf16 v[46:49], v[160:163], v[200:203], v[46:49]
	v_mfma_f32_16x16x32_bf16 v[42:45], v[168:171], v[200:203], v[42:45]
	v_mfma_f32_16x16x32_bf16 v[30:33], v[160:163], v[208:211], v[30:33]
	v_mfma_f32_16x16x32_bf16 v[26:29], v[168:171], v[208:211], v[26:29]
	v_mfma_f32_16x16x32_bf16 v[14:17], v[160:163], v[216:219], v[14:17]
	v_mfma_f32_16x16x32_bf16 v[10:13], v[168:171], v[216:219], v[10:13]
	s_setprio 0
	s_setprio 1
	v_mfma_f32_16x16x32_bf16 v[54:57], v[172:175], v[188:191], v[54:57]
	v_mfma_f32_16x16x32_bf16 v[50:53], v[180:183], v[188:191], v[50:53]
	v_mfma_f32_16x16x32_bf16 v[38:41], v[172:175], v[196:199], v[38:41]
	v_mfma_f32_16x16x32_bf16 v[34:37], v[180:183], v[196:199], v[34:37]
	v_mfma_f32_16x16x32_bf16 v[22:25], v[172:175], v[204:207], v[22:25]
	v_mfma_f32_16x16x32_bf16 v[18:21], v[180:183], v[204:207], v[18:21]
	v_mfma_f32_16x16x32_bf16 v[6:9], v[172:175], v[212:215], v[6:9]
	v_mfma_f32_16x16x32_bf16 v[2:5], v[180:183], v[212:215], v[2:5]
	v_mfma_f32_16x16x32_bf16 v[54:57], v[176:179], v[192:195], v[54:57]
	v_mfma_f32_16x16x32_bf16 v[50:53], v[184:187], v[192:195], v[50:53]
	v_mfma_f32_16x16x32_bf16 v[38:41], v[176:179], v[200:203], v[38:41]
	v_mfma_f32_16x16x32_bf16 v[34:37], v[184:187], v[200:203], v[34:37]
	v_mfma_f32_16x16x32_bf16 v[22:25], v[176:179], v[208:211], v[22:25]
	v_mfma_f32_16x16x32_bf16 v[18:21], v[184:187], v[208:211], v[18:21]
	v_mfma_f32_16x16x32_bf16 v[6:9], v[176:179], v[216:219], v[6:9]
	v_mfma_f32_16x16x32_bf16 v[2:5], v[184:187], v[216:219], v[2:5]
	s_setprio 0
	s_barrier
	s_add_i32 s44, s44, 2
	s_add_u32 s24, s24, 0x100
	s_addc_u32 s25, s25, 0
	s_add_u32 s42, s42, 0x100
	s_addc_u32 s43, s43, 0
	s_cmp_gt_u32 s44, 13
	s_cbranch_scc0 .LBB0_2559
	s_and_b64 vcc, exec, s[12:13]
	s_cbranch_vccz .LBB0_2562
	s_barrier

; #define PG8_STAGE(bufoff, gbase, voff) do { _Pragma("unroll") for (int _i = 0; _i < 2; ++_i) \
;         __builtin_amdgcn_global_load_lds((const unsigned*)((const char*)(gbase) + (voff)[_i]), (PG8_LAS unsigned*)(lds + (bufoff) + ldsw + _i * 8192), 16, 0, 0); } while (0)
; #define PG8_WAIT_V(n) asm volatile("s_waitcnt vmcnt(" #n ")" ::: "memory")
; #define PG8_BAR __builtin_amdgcn_s_barrier()
; template <class Epi, class Sched, bool ALIGN_EPI = false, bool SP2 = false>
; __device__ __forceinline__ void gemm_phase(PG8_LAS unsigned char* lds, const Gemm g, const Sched& S, const Epi& E) {
;     ...
;     const int K = g.K, nt = K / BK;
;     unsigned voffA[2], voffB[2];
; #pragma unroll
;     for (int i = 0; i < 2; ++i) { int R, C; stage_rc(tid * 16 + i * 8192, R, C); const int Rb = Epi::PERM ? ((R & ~31) + perm32(R & 31)) : R;
;         voffA[i] = (unsigned)(R * K + C) * 2u; voffB[i] = (unsigned)(Rb * K + C) * 2u; }
;     const size_t kstep = (size_t)(BK * 2);
;     const size_t hstep = (size_t)HALF * K * 2;
;     const size_t tstep = 2 * hstep;
;     const unsigned ldsw = (unsigned)wid * 1024u;
;     const int aoff = lds_byte(wr * 64 + fr, fq * 8), boff = lds_byte(wc * 32 + fr, fq * 8);
;     ...
;         PG8_STAGE(PG8_SB(1, 0), cB + kstep, voffB); PG8_STAGE(PG8_SA(1, 0), cA + kstep, voffA); PG8_STAGE(PG8_SB(1, 1), cB + hstep + kstep, voffB);
;         PG8_WAIT_V(6); PG8_BAR;
.LBB0_2632:
	s_lshl_b32 s10, s10, 5
	s_and_b32 s16, s10, 0x60
	s_mov_b64 s[10:11], 0x80
	s_add_i32 m0, s3, 0x18000
	v_lshl_add_u64 v[8:9], v[8:9], 0, s[10:11]
	s_lshl_b32 s13, s1, 13
	s_lshl_b32 s17, s16, 7
	s_waitcnt vmcnt(2)
	s_barrier
	global_load_lds_dwordx4 v[8:9], off
	v_lshl_add_u64 v[4:5], v[4:5], 0, s[10:11]
	s_add_i32 m0, s3, 0x1a000
	s_add_i32 s38, s3, 0x8000
	s_add_i32 s39, s3, 0xa000
	global_load_lds_dwordx4 v[4:5], off
	v_lshl_add_u64 v[2:3], v[2:3], 0, s[10:11]
	s_mov_b32 m0, s38
	s_add_u32 s14, s30, 0x80080
	global_load_lds_dwordx4 v[2:3], off
	v_lshl_add_u64 v[2:3], v[6:7], 0, s[10:11]
	s_mov_b32 m0, s39
	s_addc_u32 s15, s31, 0
	global_load_lds_dwordx4 v[2:3], off
	s_add_i32 m0, s3, 0x1c000
	s_nop 0
	global_load_lds_dwordx4 v132, s[14:15]
	v_lshl_add_u64 v[2:3], s[14:15], 0, v[136:137]
	s_add_i32 m0, s3, 0x1e000
	v_and_b32_e32 v1, 15, v10
	global_load_lds_dwordx4 v136, s[14:15]
	v_bfe_u32 v2, v10, 4, 2
	v_lshlrev_b32_e32 v3, 4, v2
	v_lshl_or_b32 v1, v1, 6, v3
	v_lshlrev_b32_e32 v3, 2, v10
	v_and_b32_e32 v3, 32, v3
	v_bitop3_b32 v4, v1, s13, v3 bitop3:0xde
	v_bitop3_b32 v1, v1, s17, v3 bitop3:0xde
	v_bfe_u32 v3, v10, 2, 2
	v_lshl_or_b32 v2, v2, 2, v3
	v_and_b32_e32 v3, 3, v10
	v_lshlrev_b32_e32 v5, 6, v3
	v_lshl_or_b32 v146, v2, 2, v5
	v_lshl_or_b32 v147, s1, 6, v2
	v_lshlrev_b32_e32 v2, 15, v11
	v_and_b32_e32 v2, 0xffff0000, v2
	v_lshl_or_b32 v148, v3, 3, s16
	v_lshl_add_u32 v2, v12, 12, v2
	v_and_b32_e32 v3, 1, v11
	v_lshl_or_b32 v2, v3, 6, v2
	v_lshl_add_u32 v138, v13, 1, v2
	v_lshlrev_b32_e32 v2, 15, v14
	v_and_b32_e32 v2, 0xffff0000, v2
	s_waitcnt vmcnt(6)
	s_cmpk_lt_u32 s12, 0x100
	v_lshl_add_u32 v2, v15, 12, v2
	v_and_b32_e32 v3, 1, v14
	s_cselect_b64 s[12:13], -1, 0
	v_lshl_or_b32 v2, v3, 6, v2
	s_add_i32 s40, 0, 0x10000
	s_add_i32 s41, 0, 0x14000
	s_sext_i32_i8 s44, s0
	v_mov_b32_e32 v139, v133
	v_lshl_add_u32 v140, v16, 1, v2
	v_mov_b32_e32 v141, v133
	v_mov_b64_e32 v[142:143], 0x200
	v_mov_b64_e32 v[144:145], 0x1ff
	v_add_u32_e32 v149, s40, v1
	v_add_u32_e32 v150, s41, v1
	v_add_u32_e32 v151, 0, v4
	s_mov_b64 s[14:15], 0xa0000
	s_mov_b32 s42, 0xa0000
	s_mov_b64 s[16:17], 0xb0000
	s_mov_b32 s43, 0xb0000
	s_barrier
	s_branch .LBB0_2635

; #define PG8_STAGE(bufoff, gbase, voff) do { _Pragma("unroll") for (int _i = 0; _i < 2; ++_i) \
;         __builtin_amdgcn_global_load_lds((const unsigned*)((const char*)(gbase) + (voff)[_i]), (PG8_LAS unsigned*)(lds + (bufoff) + ldsw + _i * 8192), 16, 0, 0); } while (0)
; #define PG8_LDA(dst, b, h) do { _Pragma("unroll") for (int m = 0; m < 4; ++m) _Pragma("unroll") for (int k = 0; k < 2; ++k) dst[m][k] = *(const PG8_LAS bf16x8*)(lds + PG8_SA(b, h) + aoff + m * 2048 + k * 1024); } while (0)
; #define PG8_LDB(dst, b, h) do { _Pragma("unroll") for (int n = 0; n < 2; ++n) _Pragma("unroll") for (int k = 0; k < 2; ++k) dst[n][k] = *(const PG8_LAS bf16x8*)(lds + PG8_SB(b, h) + boff + n * 2048 + k * 1024); } while (0)
; #define PG8_MMA(ai, bj, At, Bt) do { __builtin_amdgcn_s_setprio(1); _Pragma("unroll") for (int m = 0; m < 4; ++m) _Pragma("unroll") for (int n = 0; n < 2; ++n) _Pragma("unroll") for (int k = 0; k < 2; ++k) \
;         acc[ai][bj][m][n] = __builtin_amdgcn_mfma_f32_16x16x32_bf16(Bt[n][k], At[m][k], acc[ai][bj][m][n], 0, 0, 0); __builtin_amdgcn_s_setprio(0); } while (0)
; #define PG8_WAIT_V(n) asm volatile("s_waitcnt vmcnt(" #n ")" ::: "memory")
; #define PG8_WAIT_L(n) asm volatile("s_waitcnt lgkmcnt(" #n ")" ::: "memory")
; #define PG8_BAR __builtin_amdgcn_s_barrier()
; #define PG8_SCHED __builtin_amdgcn_sched_barrier(0)
; template <class Epi, class Sched, bool ALIGN_EPI = false, bool SP2 = false>
; __device__ __forceinline__ void gemm_phase(PG8_LAS unsigned char* lds, const Gemm g, const Sched& S, const Epi& E) {
;     ...
;             PG8_LDB(B0, 0, 0); PG8_LDB(B1, 0, 1); PG8_SCHED; PG8_LDA(At, 0, 0); PG8_STAGE(PG8_SA(1, 1), a1 + hstep, voffA);
;             PG8_WAIT_V(8); PG8_WAIT_L(0); PG8_BAR; PG8_MMA(0, 0, At, B0); PG8_MMA(0, 1, At, B1); PG8_BAR; PG8_SCHED;
;             PG8_LDA(At, 0, 1); PG8_STAGE(PG8_SB(0, 0), b2, voffB); PG8_STAGE(PG8_SB(0, 1), b2 + hstep, voffB); PG8_STAGE(PG8_SA(0, 0), a2, voffA);
.LBB0_2642:
	ds_read_b128 v[152:155], v149
	ds_read_b128 v[156:159], v149 offset:1024
	ds_read_b128 v[160:163], v149 offset:2048
	ds_read_b128 v[164:167], v149 offset:3072
	ds_read_b128 v[168:171], v150
	ds_read_b128 v[172:175], v150 offset:1024
	ds_read_b128 v[176:179], v150 offset:2048
	ds_read_b128 v[180:183], v150 offset:3072
	s_add_u32 s30, s28, 0xfff80080
	s_addc_u32 s31, s29, -1
	s_cmp_eq_u32 s51, 28
	s_cselect_b32 s35, s21, s31
	s_cselect_b32 s34, s45, s30
	s_cselect_b32 s31, s19, s50
	s_cselect_b32 s30, s46, s47
	s_add_i32 m0, s3, 0xc000
	ds_read_b128 v[184:187], v151
	ds_read_b128 v[188:191], v151 offset:1024
	ds_read_b128 v[192:195], v151 offset:2048
	ds_read_b128 v[196:199], v151 offset:3072
	ds_read_b128 v[200:203], v151 offset:4096
	ds_read_b128 v[204:207], v151 offset:5120
	ds_read_b128 v[208:211], v151 offset:6144
	ds_read_b128 v[212:215], v151 offset:7168
	global_load_lds_dwordx4 v138, s[28:29]
	s_add_i32 m0, s3, 0xe000
	s_nop 0
	global_load_lds_dwordx4 v140, s[28:29]
	s_waitcnt vmcnt(8)
	s_waitcnt lgkmcnt(0)
	s_barrier
	s_setprio 1
	s_waitcnt lgkmcnt(0)
	v_mfma_f32_16x16x32_bf16 v[126:129], v[152:155], v[184:187], v[126:129]
	v_mfma_f32_16x16x32_bf16 v[122:125], v[160:163], v[184:187], v[122:125]
	v_mfma_f32_16x16x32_bf16 v[118:121], v[152:155], v[192:195], v[118:121]
	v_mfma_f32_16x16x32_bf16 v[110:113], v[160:163], v[192:195], v[110:113]
	v_mfma_f32_16x16x32_bf16 v[102:105], v[152:155], v[200:203], v[102:105]
	v_mfma_f32_16x16x32_bf16 v[94:97], v[160:163], v[200:203], v[94:97]
	v_mfma_f32_16x16x32_bf16 v[86:89], v[152:155], v[208:211], v[86:89]
	v_mfma_f32_16x16x32_bf16 v[78:81], v[160:163], v[208:211], v[78:81]
	v_mfma_f32_16x16x32_bf16 v[126:129], v[156:159], v[188:191], v[126:129]
	v_mfma_f32_16x16x32_bf16 v[122:125], v[164:167], v[188:191], v[122:125]
	v_mfma_f32_16x16x32_bf16 v[118:121], v[156:159], v[196:199], v[118:121]
	v_mfma_f32_16x16x32_bf16 v[110:113], v[164:167], v[196:199], v[110:113]
	v_mfma_f32_16x16x32_bf16 v[102:105], v[156:159], v[204:207], v[102:105]
	v_mfma_f32_16x16x32_bf16 v[94:97], v[164:167], v[204:207], v[94:97]
	v_mfma_f32_16x16x32_bf16 v[86:89], v[156:159], v[212:215], v[86:89]
	v_mfma_f32_16x16x32_bf16 v[78:81], v[164:167], v[212:215], v[78:81]
	s_setprio 0
	s_setprio 1
	v_mfma_f32_16x16x32_bf16 v[114:117], v[168:171], v[184:187], v[114:117]
	v_mfma_f32_16x16x32_bf16 v[106:109], v[176:179], v[184:187], v[106:109]
	v_mfma_f32_16x16x32_bf16 v[98:101], v[168:171], v[192:195], v[98:101]
	v_mfma_f32_16x16x32_bf16 v[90:93], v[176:179], v[192:195], v[90:93]
	v_mfma_f32_16x16x32_bf16 v[82:85], v[168:171], v[200:203], v[82:85]
	v_mfma_f32_16x16x32_bf16 v[74:77], v[176:179], v[200:203], v[74:77]
	v_mfma_f32_16x16x32_bf16 v[70:73], v[168:171], v[208:211], v[70:73]
	v_mfma_f32_16x16x32_bf16 v[66:69], v[176:179], v[208:211], v[66:69]
	v_mfma_f32_16x16x32_bf16 v[114:117], v[172:175], v[188:191], v[114:117]
	v_mfma_f32_16x16x32_bf16 v[106:109], v[180:183], v[188:191], v[106:109]
	v_mfma_f32_16x16x32_bf16 v[98:101], v[172:175], v[196:199], v[98:101]
	v_mfma_f32_16x16x32_bf16 v[90:93], v[180:183], v[196:199], v[90:93]
	v_mfma_f32_16x16x32_bf16 v[82:85], v[172:175], v[204:207], v[82:85]
	v_mfma_f32_16x16x32_bf16 v[74:77], v[180:183], v[204:207], v[74:77]
	v_mfma_f32_16x16x32_bf16 v[70:73], v[172:175], v[212:215], v[70:73]
	v_mfma_f32_16x16x32_bf16 v[66:69], v[180:183], v[212:215], v[66:69]
	s_setprio 0
	s_barrier
	s_add_i32 s52, s40, s2
	v_lshl_add_u64 v[216:217], s[30:31], 0, v[132:133]
	s_mov_b32 m0, s52
	ds_read_b128 v[184:187], v151 offset:16384
	ds_read_b128 v[188:191], v151 offset:17408
	ds_read_b128 v[192:195], v151 offset:18432
	ds_read_b128 v[196:199], v151 offset:19456
	ds_read_b128 v[200:203], v151 offset:20480
	ds_read_b128 v[204:207], v151 offset:21504
	ds_read_b128 v[208:211], v151 offset:22528
	ds_read_b128 v[212:215], v151 offset:23552
	global_load_lds_dwordx4 v132, s[30:31]
	s_add_i32 m0, s52, 0x2000
	s_add_u32 s52, s30, 0x80000
	v_lshl_add_u64 v[218:219], s[30:31], 0, v[136:137]
	s_addc_u32 s53, s31, 0
	s_add_i32 s54, s41, s2
	global_load_lds_dwordx4 v136, s[30:31]
	s_mov_b32 m0, s54
	v_lshl_add_u64 v[222:223], s[34:35], 0, v[134:135]
	global_load_lds_dwordx4 v132, s[52:53]
	s_add_i32 m0, s54, 0x2000
	s_nop 0
	global_load_lds_dwordx4 v136, s[52:53]
	v_lshl_add_u64 v[220:221], s[34:35], 0, v[130:131]
	s_mov_b32 m0, s3
	s_nop 0
	global_load_lds_dwordx4 v130, s[34:35]
	s_mov_b32 m0, s27
	s_nop 0
	global_load_lds_dwordx4 v134, s[34:35]
	s_waitcnt vmcnt(8)
	s_waitcnt lgkmcnt(0)
	s_barrier
; #define PG8_STAGE(bufoff, gbase, voff) do { _Pragma("unroll") for (int _i = 0; _i < 2; ++_i) \
;         __builtin_amdgcn_global_load_lds((const unsigned*)((const char*)(gbase) + (voff)[_i]), (PG8_LAS unsigned*)(lds + (bufoff) + ldsw + _i * 8192), 16, 0, 0); } while (0)
; #define PG8_LDA(dst, b, h) do { _Pragma("unroll") for (int m = 0; m < 4; ++m) _Pragma("unroll") for (int k = 0; k < 2; ++k) dst[m][k] = *(const PG8_LAS bf16x8*)(lds + PG8_SA(b, h) + aoff + m * 2048 + k * 1024); } while (0)
; #define PG8_LDB(dst, b, h) do { _Pragma("unroll") for (int n = 0; n < 2; ++n) _Pragma("unroll") for (int k = 0; k < 2; ++k) dst[n][k] = *(const PG8_LAS bf16x8*)(lds + PG8_SB(b, h) + boff + n * 2048 + k * 1024); } while (0)
; #define PG8_MMA(ai, bj, At, Bt) do { __builtin_amdgcn_s_setprio(1); _Pragma("unroll") for (int m = 0; m < 4; ++m) _Pragma("unroll") for (int n = 0; n < 2; ++n) _Pragma("unroll") for (int k = 0; k < 2; ++k) \
;         acc[ai][bj][m][n] = __builtin_amdgcn_mfma_f32_16x16x32_bf16(Bt[n][k], At[m][k], acc[ai][bj][m][n], 0, 0, 0); __builtin_amdgcn_s_setprio(0); } while (0)
; #define PG8_WAIT_V(n) asm volatile("s_waitcnt vmcnt(" #n ")" ::: "memory")
; #define PG8_WAIT_L(n) asm volatile("s_waitcnt lgkmcnt(" #n ")" ::: "memory")
; #define PG8_BAR __builtin_amdgcn_s_barrier()
; #define PG8_SCHED __builtin_amdgcn_sched_barrier(0)
; template <class Epi, class Sched, bool ALIGN_EPI = false, bool SP2 = false>
; __device__ __forceinline__ void gemm_phase(PG8_LAS unsigned char* lds, const Gemm g, const Sched& S, const Epi& E) {
;     ...
;             PG8_WAIT_V(8); PG8_WAIT_L(0); PG8_BAR; PG8_MMA(1, 0, At, B0); PG8_MMA(1, 1, At, B1); PG8_BAR; PG8_SCHED;
;             PG8_LDB(B0, 1, 0); PG8_LDB(B1, 1, 1); PG8_SCHED; PG8_LDA(At, 1, 0); PG8_STAGE(PG8_SA(0, 1), a2 + hstep, voffA);
;             PG8_WAIT_V(8); PG8_WAIT_L(0); PG8_BAR; PG8_MMA(0, 0, At, B0); PG8_MMA(0, 1, At, B1); PG8_BAR; PG8_SCHED;
	s_setprio 1
	s_waitcnt lgkmcnt(0)
	v_mfma_f32_16x16x32_bf16 v[62:65], v[152:155], v[184:187], v[62:65]
	v_mfma_f32_16x16x32_bf16 v[58:61], v[160:163], v[184:187], v[58:61]
	v_mfma_f32_16x16x32_bf16 v[54:57], v[152:155], v[192:195], v[54:57]
	v_mfma_f32_16x16x32_bf16 v[46:49], v[160:163], v[192:195], v[46:49]
	v_mfma_f32_16x16x32_bf16 v[38:41], v[152:155], v[200:203], v[38:41]
	v_mfma_f32_16x16x32_bf16 v[34:37], v[160:163], v[200:203], v[34:37]
	v_mfma_f32_16x16x32_bf16 v[22:25], v[152:155], v[208:211], v[22:25]
	v_mfma_f32_16x16x32_bf16 v[18:21], v[160:163], v[208:211], v[18:21]
	v_mfma_f32_16x16x32_bf16 v[62:65], v[156:159], v[188:191], v[62:65]
	v_mfma_f32_16x16x32_bf16 v[58:61], v[164:167], v[188:191], v[58:61]
	v_mfma_f32_16x16x32_bf16 v[54:57], v[156:159], v[196:199], v[54:57]
	v_mfma_f32_16x16x32_bf16 v[46:49], v[164:167], v[196:199], v[46:49]
	v_mfma_f32_16x16x32_bf16 v[38:41], v[156:159], v[204:207], v[38:41]
	v_mfma_f32_16x16x32_bf16 v[34:37], v[164:167], v[204:207], v[34:37]
	v_mfma_f32_16x16x32_bf16 v[22:25], v[156:159], v[212:215], v[22:25]
	v_mfma_f32_16x16x32_bf16 v[18:21], v[164:167], v[212:215], v[18:21]
	s_setprio 0
	s_setprio 1
	v_mfma_f32_16x16x32_bf16 v[50:53], v[168:171], v[184:187], v[50:53]
	v_mfma_f32_16x16x32_bf16 v[42:45], v[176:179], v[184:187], v[42:45]
	v_mfma_f32_16x16x32_bf16 v[30:33], v[168:171], v[192:195], v[30:33]
	v_mfma_f32_16x16x32_bf16 v[26:29], v[176:179], v[192:195], v[26:29]
	v_mfma_f32_16x16x32_bf16 v[14:17], v[168:171], v[200:203], v[14:17]
	v_mfma_f32_16x16x32_bf16 v[10:13], v[176:179], v[200:203], v[10:13]
	v_mfma_f32_16x16x32_bf16 v[6:9], v[168:171], v[208:211], v[6:9]
	v_mfma_f32_16x16x32_bf16 v[2:5], v[176:179], v[208:211], v[2:5]
	v_mfma_f32_16x16x32_bf16 v[50:53], v[172:175], v[188:191], v[50:53]
	v_mfma_f32_16x16x32_bf16 v[42:45], v[180:183], v[188:191], v[42:45]
	v_mfma_f32_16x16x32_bf16 v[30:33], v[172:175], v[196:199], v[30:33]
	v_mfma_f32_16x16x32_bf16 v[26:29], v[180:183], v[196:199], v[26:29]
	v_mfma_f32_16x16x32_bf16 v[14:17], v[172:175], v[204:207], v[14:17]
	v_mfma_f32_16x16x32_bf16 v[10:13], v[180:183], v[204:207], v[10:13]
	v_mfma_f32_16x16x32_bf16 v[6:9], v[172:175], v[212:215], v[6:9]
	v_mfma_f32_16x16x32_bf16 v[2:5], v[180:183], v[212:215], v[2:5]
	s_setprio 0
	s_barrier
	s_add_i32 s52, 0, 0x18000
	s_add_i32 s53, 0, 0x1c000
	v_add_u32_e32 v164, s52, v1
	v_add_u32_e32 v180, s53, v1
	ds_read_b128 v[152:155], v164
	ds_read_b128 v[156:159], v164 offset:1024
	ds_read_b128 v[160:163], v164 offset:2048
	ds_read_b128 v[164:167], v164 offset:3072
	ds_read_b128 v[168:171], v180
	ds_read_b128 v[172:175], v180 offset:1024
	ds_read_b128 v[176:179], v180 offset:2048
	ds_read_b128 v[180:183], v180 offset:3072
	s_add_u32 s34, s34, 0x80000
	s_addc_u32 s35, s35, 0
	s_mov_b32 m0, s33
	ds_read_b128 v[184:187], v151 offset:32768
	ds_read_b128 v[188:191], v151 offset:33792
	ds_read_b128 v[192:195], v151 offset:34816
	ds_read_b128 v[196:199], v151 offset:35840
	ds_read_b128 v[200:203], v151 offset:36864
	ds_read_b128 v[204:207], v151 offset:37888
	ds_read_b128 v[208:211], v151 offset:38912
	ds_read_b128 v[212:215], v151 offset:39936
	global_load_lds_dwordx4 v130, s[34:35]
	v_lshl_add_u64 v[224:225], s[34:35], 0, v[134:135]
	s_mov_b32 m0, s36
	s_nop 0
	global_load_lds_dwordx4 v134, s[34:35]
	s_waitcnt vmcnt(8)
	s_waitcnt lgkmcnt(0)
	s_barrier
	s_setprio 1
	s_waitcnt lgkmcnt(0)
	v_mfma_f32_16x16x32_bf16 v[126:129], v[152:155], v[184:187], v[126:129]
	v_mfma_f32_16x16x32_bf16 v[122:125], v[160:163], v[184:187], v[122:125]
	v_mfma_f32_16x16x32_bf16 v[118:121], v[152:155], v[192:195], v[118:121]
	v_mfma_f32_16x16x32_bf16 v[110:113], v[160:163], v[192:195], v[110:113]
	v_mfma_f32_16x16x32_bf16 v[102:105], v[152:155], v[200:203], v[102:105]
	v_mfma_f32_16x16x32_bf16 v[94:97], v[160:163], v[200:203], v[94:97]
	v_mfma_f32_16x16x32_bf16 v[86:89], v[152:155], v[208:211], v[86:89]
	v_mfma_f32_16x16x32_bf16 v[78:81], v[160:163], v[208:211], v[78:81]
	v_mfma_f32_16x16x32_bf16 v[126:129], v[156:159], v[188:191], v[126:129]
	v_mfma_f32_16x16x32_bf16 v[122:125], v[164:167], v[188:191], v[122:125]
	v_mfma_f32_16x16x32_bf16 v[118:121], v[156:159], v[196:199], v[118:121]
	v_mfma_f32_16x16x32_bf16 v[110:113], v[164:167], v[196:199], v[110:113]
	v_mfma_f32_16x16x32_bf16 v[102:105], v[156:159], v[204:207], v[102:105]
	v_mfma_f32_16x16x32_bf16 v[94:97], v[164:167], v[204:207], v[94:97]
	v_mfma_f32_16x16x32_bf16 v[86:89], v[156:159], v[212:215], v[86:89]
	v_mfma_f32_16x16x32_bf16 v[78:81], v[164:167], v[212:215], v[78:81]
	s_setprio 0
	s_setprio 1
	v_mfma_f32_16x16x32_bf16 v[114:117], v[168:171], v[184:187], v[114:117]
	v_mfma_f32_16x16x32_bf16 v[106:109], v[176:179], v[184:187], v[106:109]
	v_mfma_f32_16x16x32_bf16 v[98:101], v[168:171], v[192:195], v[98:101]
	v_mfma_f32_16x16x32_bf16 v[90:93], v[176:179], v[192:195], v[90:93]
	v_mfma_f32_16x16x32_bf16 v[82:85], v[168:171], v[200:203], v[82:85]
	v_mfma_f32_16x16x32_bf16 v[74:77], v[176:179], v[200:203], v[74:77]
	v_mfma_f32_16x16x32_bf16 v[70:73], v[168:171], v[208:211], v[70:73]
	v_mfma_f32_16x16x32_bf16 v[66:69], v[176:179], v[208:211], v[66:69]
	v_mfma_f32_16x16x32_bf16 v[114:117], v[172:175], v[188:191], v[114:117]
	v_mfma_f32_16x16x32_bf16 v[106:109], v[180:183], v[188:191], v[106:109]
	v_mfma_f32_16x16x32_bf16 v[98:101], v[172:175], v[196:199], v[98:101]
	v_mfma_f32_16x16x32_bf16 v[90:93], v[180:183], v[196:199], v[90:93]
	v_mfma_f32_16x16x32_bf16 v[82:85], v[172:175], v[204:207], v[82:85]
	v_mfma_f32_16x16x32_bf16 v[74:77], v[180:183], v[204:207], v[74:77]
	v_mfma_f32_16x16x32_bf16 v[70:73], v[172:175], v[212:215], v[70:73]
	v_mfma_f32_16x16x32_bf16 v[66:69], v[180:183], v[212:215], v[66:69]
	s_setprio 0
	s_barrier
; #define PG8_STAGE(bufoff, gbase, voff) do { _Pragma("unroll") for (int _i = 0; _i < 2; ++_i) \
;         __builtin_amdgcn_global_load_lds((const unsigned*)((const char*)(gbase) + (voff)[_i]), (PG8_LAS unsigned*)(lds + (bufoff) + ldsw + _i * 8192), 16, 0, 0); } while (0)
; #define PG8_LDA(dst, b, h) do { _Pragma("unroll") for (int m = 0; m < 4; ++m) _Pragma("unroll") for (int k = 0; k < 2; ++k) dst[m][k] = *(const PG8_LAS bf16x8*)(lds + PG8_SA(b, h) + aoff + m * 2048 + k * 1024); } while (0)
; #define PG8_MMA(ai, bj, At, Bt) do { __builtin_amdgcn_s_setprio(1); _Pragma("unroll") for (int m = 0; m < 4; ++m) _Pragma("unroll") for (int n = 0; n < 2; ++n) _Pragma("unroll") for (int k = 0; k < 2; ++k) \
;         acc[ai][bj][m][n] = __builtin_amdgcn_mfma_f32_16x16x32_bf16(Bt[n][k], At[m][k], acc[ai][bj][m][n], 0, 0, 0); __builtin_amdgcn_s_setprio(0); } while (0)
; #define PG8_WAIT_V(n) asm volatile("s_waitcnt vmcnt(" #n ")" ::: "memory")
; #define PG8_WAIT_L(n) asm volatile("s_waitcnt lgkmcnt(" #n ")" ::: "memory")
; #define PG8_BAR __builtin_amdgcn_s_barrier()
; #define PG8_SCHED __builtin_amdgcn_sched_barrier(0)
; template <class Epi, class Sched, bool ALIGN_EPI = false, bool SP2 = false>
; __device__ __forceinline__ void gemm_phase(PG8_LAS unsigned char* lds, const Gemm g, const Sched& S, const Epi& E) {
;     ...
;         for (int t = 0; t < nt; t += 2) {
;     ...
;             PG8_LDA(At, 1, 1); PG8_STAGE(PG8_SB(1, 0), b3, voffB); PG8_STAGE(PG8_SB(1, 1), b3 + hstep, voffB); PG8_STAGE(PG8_SA(1, 0), a3, voffA);
;             PG8_WAIT_V(8); PG8_WAIT_L(0); PG8_BAR; PG8_MMA(1, 0, At, B0); PG8_MMA(1, 1, At, B1); PG8_BAR; PG8_SCHED;
;     ...
;         if constexpr (ALIGN_EPI) { if (wr == 0) PG8_BAR; }
	s_add_i32 s34, s52, s2
	v_lshl_add_u64 v[216:217], v[216:217], 0, s[10:11]
	s_mov_b32 m0, s34
	ds_read_b128 v[184:187], v151 offset:49152
	ds_read_b128 v[188:191], v151 offset:50176
	ds_read_b128 v[192:195], v151 offset:51200
	ds_read_b128 v[196:199], v151 offset:52224
	ds_read_b128 v[200:203], v151 offset:53248
	ds_read_b128 v[204:207], v151 offset:54272
	ds_read_b128 v[208:211], v151 offset:55296
	ds_read_b128 v[212:215], v151 offset:56320
	global_load_lds_dwordx4 v[216:217], off
	s_add_i32 m0, s34, 0x2000
	s_add_u32 s30, s30, 0x80080
	v_lshl_add_u64 v[216:217], v[218:219], 0, s[10:11]
	s_addc_u32 s31, s31, 0
	s_add_i32 s34, s53, s2
	global_load_lds_dwordx4 v[216:217], off
	s_mov_b32 m0, s34
	s_nop 0
	global_load_lds_dwordx4 v132, s[30:31]
	s_add_i32 m0, s34, 0x2000
	s_nop 0
	global_load_lds_dwordx4 v136, s[30:31]
	v_lshl_add_u64 v[216:217], v[220:221], 0, s[10:11]
	s_mov_b32 m0, s38
	s_nop 0
	global_load_lds_dwordx4 v[216:217], off
	v_lshl_add_u64 v[216:217], v[222:223], 0, s[10:11]
	s_mov_b32 m0, s39
	s_nop 0
	global_load_lds_dwordx4 v[216:217], off
	s_waitcnt vmcnt(8)
	s_waitcnt lgkmcnt(0)
	s_barrier
	s_setprio 1
	s_waitcnt lgkmcnt(0)
	v_mfma_f32_16x16x32_bf16 v[62:65], v[152:155], v[184:187], v[62:65]
	v_mfma_f32_16x16x32_bf16 v[58:61], v[160:163], v[184:187], v[58:61]
	v_mfma_f32_16x16x32_bf16 v[54:57], v[152:155], v[192:195], v[54:57]
	v_mfma_f32_16x16x32_bf16 v[46:49], v[160:163], v[192:195], v[46:49]
	v_mfma_f32_16x16x32_bf16 v[38:41], v[152:155], v[200:203], v[38:41]
	v_mfma_f32_16x16x32_bf16 v[34:37], v[160:163], v[200:203], v[34:37]
	v_mfma_f32_16x16x32_bf16 v[22:25], v[152:155], v[208:211], v[22:25]
	v_mfma_f32_16x16x32_bf16 v[18:21], v[160:163], v[208:211], v[18:21]
	v_mfma_f32_16x16x32_bf16 v[62:65], v[156:159], v[188:191], v[62:65]
	v_mfma_f32_16x16x32_bf16 v[58:61], v[164:167], v[188:191], v[58:61]
	v_mfma_f32_16x16x32_bf16 v[54:57], v[156:159], v[196:199], v[54:57]
	v_mfma_f32_16x16x32_bf16 v[46:49], v[164:167], v[196:199], v[46:49]
	v_mfma_f32_16x16x32_bf16 v[38:41], v[156:159], v[204:207], v[38:41]
	v_mfma_f32_16x16x32_bf16 v[34:37], v[164:167], v[204:207], v[34:37]
	v_mfma_f32_16x16x32_bf16 v[22:25], v[156:159], v[212:215], v[22:25]
	v_mfma_f32_16x16x32_bf16 v[18:21], v[164:167], v[212:215], v[18:21]
	s_setprio 0
	s_setprio 1
	v_mfma_f32_16x16x32_bf16 v[50:53], v[168:171], v[184:187], v[50:53]
	v_mfma_f32_16x16x32_bf16 v[42:45], v[176:179], v[184:187], v[42:45]
	v_mfma_f32_16x16x32_bf16 v[30:33], v[168:171], v[192:195], v[30:33]
	v_mfma_f32_16x16x32_bf16 v[26:29], v[176:179], v[192:195], v[26:29]
	v_mfma_f32_16x16x32_bf16 v[14:17], v[168:171], v[200:203], v[14:17]
	v_mfma_f32_16x16x32_bf16 v[10:13], v[176:179], v[200:203], v[10:13]
	v_mfma_f32_16x16x32_bf16 v[6:9], v[168:171], v[208:211], v[6:9]
	v_mfma_f32_16x16x32_bf16 v[2:5], v[176:179], v[208:211], v[2:5]
	v_mfma_f32_16x16x32_bf16 v[50:53], v[172:175], v[188:191], v[50:53]
	v_mfma_f32_16x16x32_bf16 v[42:45], v[180:183], v[188:191], v[42:45]
	v_mfma_f32_16x16x32_bf16 v[30:33], v[172:175], v[196:199], v[30:33]
	v_mfma_f32_16x16x32_bf16 v[26:29], v[180:183], v[196:199], v[26:29]
	v_mfma_f32_16x16x32_bf16 v[14:17], v[172:175], v[204:207], v[14:17]
	v_mfma_f32_16x16x32_bf16 v[10:13], v[180:183], v[204:207], v[10:13]
	v_mfma_f32_16x16x32_bf16 v[6:9], v[172:175], v[212:215], v[6:9]
	v_mfma_f32_16x16x32_bf16 v[2:5], v[180:183], v[212:215], v[2:5]
	s_setprio 0
	s_barrier
	s_add_i32 s51, s51, 2
	s_add_u32 s28, s28, 0x100
	s_addc_u32 s29, s29, 0
	s_add_u32 s47, s47, 0x100
	s_addc_u32 s50, s50, 0
	s_cmp_gt_u32 s51, 29
	s_cbranch_scc0 .LBB0_2642
	s_and_b64 vcc, exec, s[12:13]
	s_cbranch_vccz .LBB0_2645
	s_barrier

; #define PG8_STAGE(bufoff, gbase, voff) do { _Pragma("unroll") for (int _i = 0; _i < 2; ++_i) \
;         __builtin_amdgcn_global_load_lds((const unsigned*)((const char*)(gbase) + (voff)[_i]), (PG8_LAS unsigned*)(lds + (bufoff) + ldsw + _i * 8192), 16, 0, 0); } while (0)
; #define PG8_WAIT_V(n) asm volatile("s_waitcnt vmcnt(" #n ")" ::: "memory")
; #define PG8_BAR __builtin_amdgcn_s_barrier()
; template <class Epi, class Sched, bool ALIGN_EPI = false, bool SP2 = false>
; __device__ __forceinline__ void gemm_phase(PG8_LAS unsigned char* lds, const Gemm g, const Sched& S, const Epi& E) {
;     ...
;     for (int i = 0; i < 2; ++i) { int R, C; stage_rc(tid * 16 + i * 8192, R, C); const int Rb = Epi::PERM ? ((R & ~31) + perm32(R & 31)) : R;
;         voffA[i] = (unsigned)(R * K + C) * 2u; voffB[i] = (unsigned)(Rb * K + C) * 2u; }
;     const size_t kstep = (size_t)(BK * 2);
;     const size_t hstep = (size_t)HALF * K * 2;
;     const size_t tstep = 2 * hstep;
;     const unsigned ldsw = (unsigned)wid * 1024u;
;     const int aoff = lds_byte(wr * 64 + fr, fq * 8), boff = lds_byte(wc * 32 + fr, fq * 8);
;     ...
;         PG8_STAGE(PG8_SB(1, 0), cB + kstep, voffB); PG8_STAGE(PG8_SA(1, 0), cA + kstep, voffA); PG8_STAGE(PG8_SB(1, 1), cB + hstep + kstep, voffB);
;         PG8_WAIT_V(6); PG8_BAR;
.LBB0_2768:
	s_lshl_b32 s8, s8, 5
	s_and_b32 s14, s8, 0x60
	s_mov_b64 s[8:9], 0x80
	s_add_i32 m0, s21, 0x18000
	v_lshl_add_u64 v[8:9], v[8:9], 0, s[8:9]
	s_lshl_b32 s11, s1, 13
	s_lshl_b32 s15, s14, 7
	s_waitcnt vmcnt(2)
	s_barrier
	global_load_lds_dwordx4 v[8:9], off
	v_lshl_add_u64 v[6:7], v[6:7], 0, s[8:9]
	s_add_i32 m0, s21, 0x1a000
	s_add_i32 s34, s21, 0x8000
	s_add_i32 s35, s21, 0xa000
	global_load_lds_dwordx4 v[6:7], off
	v_lshl_add_u64 v[2:3], v[2:3], 0, s[8:9]
	s_mov_b32 m0, s34
	s_add_u32 s12, s24, 0x80080
	global_load_lds_dwordx4 v[2:3], off
	v_lshl_add_u64 v[2:3], v[4:5], 0, s[8:9]
	s_mov_b32 m0, s35
	s_addc_u32 s13, s25, 0
	global_load_lds_dwordx4 v[2:3], off
	s_add_i32 m0, s21, 0x1c000
	s_nop 0
	global_load_lds_dwordx4 v134, s[12:13]
	v_lshl_add_u64 v[2:3], s[12:13], 0, v[130:131]
	s_add_i32 m0, s21, 0x1e000
	v_and_b32_e32 v1, 15, v10
	global_load_lds_dwordx4 v130, s[12:13]
	v_bfe_u32 v2, v10, 4, 2
	v_lshlrev_b32_e32 v3, 4, v2
	v_lshl_or_b32 v1, v1, 6, v3
	v_lshlrev_b32_e32 v3, 2, v10
	v_and_b32_e32 v3, 32, v3
	v_bitop3_b32 v4, v1, s11, v3 bitop3:0xde
	v_bitop3_b32 v1, v1, s15, v3 bitop3:0xde
	v_bfe_u32 v3, v10, 2, 2
	v_lshl_or_b32 v2, v2, 2, v3
	v_and_b32_e32 v3, 3, v10
	v_lshlrev_b32_e32 v5, 6, v3
	v_lshl_or_b32 v150, v2, 2, v5
	v_lshl_or_b32 v151, s1, 6, v2
	v_lshlrev_b32_e32 v2, 15, v15
	v_and_b32_e32 v2, 0xffff0000, v2
	v_lshl_or_b32 v152, v3, 3, s14
	v_lshl_add_u32 v2, v14, 12, v2
	v_and_b32_e32 v3, 1, v15
	v_lshl_or_b32 v2, v3, 6, v2
	v_lshl_add_u32 v138, v16, 1, v2
	v_lshlrev_b32_e32 v2, 15, v11
	v_and_b32_e32 v2, 0xffff0000, v2
	s_waitcnt vmcnt(6)
	s_cmpk_lt_u32 s10, 0x100
	v_lshl_add_u32 v2, v12, 12, v2
	v_and_b32_e32 v3, 1, v11
	s_cselect_b64 s[10:11], -1, 0
	v_lshl_or_b32 v2, v3, 6, v2
	s_add_i32 s36, 0, 0x10000
	s_add_i32 s37, 0, 0x14000
	s_sext_i32_i16 s39, s0
	v_mov_b32_e32 v139, v135
	v_lshl_add_u32 v140, v13, 1, v2
	v_mov_b32_e32 v141, v135
	v_mov_b64_e32 v[142:143], 0xb00
	v_mov_b64_e32 v[144:145], 0xaff
	v_add_u32_e32 v153, s36, v1
	v_add_u32_e32 v154, s37, v1
	v_add_u32_e32 v155, 0, v4
	s_movk_i32 s38, 0x2c00
	s_barrier
	s_branch .LBB0_2771

; #define PG8_STAGE(bufoff, gbase, voff) do { _Pragma("unroll") for (int _i = 0; _i < 2; ++_i) \
;         __builtin_amdgcn_global_load_lds((const unsigned*)((const char*)(gbase) + (voff)[_i]), (PG8_LAS unsigned*)(lds + (bufoff) + ldsw + _i * 8192), 16, 0, 0); } while (0)
; #define PG8_LDA(dst, b, h) do { _Pragma("unroll") for (int m = 0; m < 4; ++m) _Pragma("unroll") for (int k = 0; k < 2; ++k) dst[m][k] = *(const PG8_LAS bf16x8*)(lds + PG8_SA(b, h) + aoff + m * 2048 + k * 1024); } while (0)
; #define PG8_LDB(dst, b, h) do { _Pragma("unroll") for (int n = 0; n < 2; ++n) _Pragma("unroll") for (int k = 0; k < 2; ++k) dst[n][k] = *(const PG8_LAS bf16x8*)(lds + PG8_SB(b, h) + boff + n * 2048 + k * 1024); } while (0)
; #define PG8_MMA(ai, bj, At, Bt) do { __builtin_amdgcn_s_setprio(1); _Pragma("unroll") for (int m = 0; m < 4; ++m) _Pragma("unroll") for (int n = 0; n < 2; ++n) _Pragma("unroll") for (int k = 0; k < 2; ++k) \
;         acc[ai][bj][m][n] = __builtin_amdgcn_mfma_f32_16x16x32_bf16(Bt[n][k], At[m][k], acc[ai][bj][m][n], 0, 0, 0); __builtin_amdgcn_s_setprio(0); } while (0)
; #define PG8_WAIT_V(n) asm volatile("s_waitcnt vmcnt(" #n ")" ::: "memory")
; #define PG8_WAIT_L(n) asm volatile("s_waitcnt lgkmcnt(" #n ")" ::: "memory")
; #define PG8_BAR __builtin_amdgcn_s_barrier()
; #define PG8_SCHED __builtin_amdgcn_sched_barrier(0)
; template <class Epi, class Sched, bool ALIGN_EPI = false, bool SP2 = false>
; __device__ __forceinline__ void gemm_phase(PG8_LAS unsigned char* lds, const Gemm g, const Sched& S, const Epi& E) {
;     ...
;             PG8_LDB(B0, 0, 0); PG8_LDB(B1, 0, 1); PG8_SCHED; PG8_LDA(At, 0, 0); PG8_STAGE(PG8_SA(1, 1), a1 + hstep, voffA);
;             PG8_WAIT_V(8); PG8_WAIT_L(0); PG8_BAR; PG8_MMA(0, 0, At, B0); PG8_MMA(0, 1, At, B1); PG8_BAR; PG8_SCHED;
;             PG8_LDA(At, 0, 1); PG8_STAGE(PG8_SB(0, 0), b2, voffB); PG8_STAGE(PG8_SB(0, 1), b2 + hstep, voffB); PG8_STAGE(PG8_SA(0, 0), a2, voffA);
.LBB0_2774:
	ds_read_b128 v[146:149], v153
	ds_read_b128 v[156:159], v153 offset:1024
	ds_read_b128 v[160:163], v153 offset:2048
	ds_read_b128 v[164:167], v153 offset:3072
	ds_read_b128 v[168:171], v154
	ds_read_b128 v[172:175], v154 offset:1024
	ds_read_b128 v[176:179], v154 offset:2048
	ds_read_b128 v[180:183], v154 offset:3072
	s_add_u32 s24, s22, 0xfff80080
	s_addc_u32 s25, s23, -1
	s_cmp_eq_u32 s44, 28
	s_cselect_b32 s27, s15, s25
	s_cselect_b32 s26, s40, s24
	s_cselect_b32 s25, s13, s43
	s_cselect_b32 s24, s41, s42
	s_add_i32 m0, s21, 0xc000
	ds_read_b128 v[184:187], v155
	ds_read_b128 v[188:191], v155 offset:1024
	ds_read_b128 v[192:195], v155 offset:2048
	ds_read_b128 v[196:199], v155 offset:3072
	ds_read_b128 v[200:203], v155 offset:4096
	ds_read_b128 v[204:207], v155 offset:5120
	ds_read_b128 v[208:211], v155 offset:6144
	ds_read_b128 v[212:215], v155 offset:7168
	global_load_lds_dwordx4 v138, s[22:23]
	s_add_i32 m0, s21, 0xe000
	s_nop 0
	global_load_lds_dwordx4 v140, s[22:23]
	s_waitcnt vmcnt(8)
	s_waitcnt lgkmcnt(0)
	s_barrier
	s_setprio 1
	s_waitcnt lgkmcnt(0)
	v_mfma_f32_16x16x32_bf16 v[126:129], v[146:149], v[184:187], v[126:129]
	v_mfma_f32_16x16x32_bf16 v[122:125], v[160:163], v[184:187], v[122:125]
	v_mfma_f32_16x16x32_bf16 v[110:113], v[146:149], v[192:195], v[110:113]
	v_mfma_f32_16x16x32_bf16 v[106:109], v[160:163], v[192:195], v[106:109]
	v_mfma_f32_16x16x32_bf16 v[94:97], v[146:149], v[200:203], v[94:97]
	v_mfma_f32_16x16x32_bf16 v[90:93], v[160:163], v[200:203], v[90:93]
	v_mfma_f32_16x16x32_bf16 v[78:81], v[146:149], v[208:211], v[78:81]
	v_mfma_f32_16x16x32_bf16 v[74:77], v[160:163], v[208:211], v[74:77]
	v_mfma_f32_16x16x32_bf16 v[126:129], v[156:159], v[188:191], v[126:129]
	v_mfma_f32_16x16x32_bf16 v[122:125], v[164:167], v[188:191], v[122:125]
	v_mfma_f32_16x16x32_bf16 v[110:113], v[156:159], v[196:199], v[110:113]
	v_mfma_f32_16x16x32_bf16 v[106:109], v[164:167], v[196:199], v[106:109]
	v_mfma_f32_16x16x32_bf16 v[94:97], v[156:159], v[204:207], v[94:97]
	v_mfma_f32_16x16x32_bf16 v[90:93], v[164:167], v[204:207], v[90:93]
	v_mfma_f32_16x16x32_bf16 v[78:81], v[156:159], v[212:215], v[78:81]
	v_mfma_f32_16x16x32_bf16 v[74:77], v[164:167], v[212:215], v[74:77]
	s_setprio 0
	s_setprio 1
	v_mfma_f32_16x16x32_bf16 v[118:121], v[168:171], v[184:187], v[118:121]
	v_mfma_f32_16x16x32_bf16 v[114:117], v[176:179], v[184:187], v[114:117]
	v_mfma_f32_16x16x32_bf16 v[102:105], v[168:171], v[192:195], v[102:105]
	v_mfma_f32_16x16x32_bf16 v[98:101], v[176:179], v[192:195], v[98:101]
	v_mfma_f32_16x16x32_bf16 v[86:89], v[168:171], v[200:203], v[86:89]
	v_mfma_f32_16x16x32_bf16 v[82:85], v[176:179], v[200:203], v[82:85]
	v_mfma_f32_16x16x32_bf16 v[70:73], v[168:171], v[208:211], v[70:73]
	v_mfma_f32_16x16x32_bf16 v[66:69], v[176:179], v[208:211], v[66:69]
	v_mfma_f32_16x16x32_bf16 v[118:121], v[172:175], v[188:191], v[118:121]
	v_mfma_f32_16x16x32_bf16 v[114:117], v[180:183], v[188:191], v[114:117]
	v_mfma_f32_16x16x32_bf16 v[102:105], v[172:175], v[196:199], v[102:105]
	v_mfma_f32_16x16x32_bf16 v[98:101], v[180:183], v[196:199], v[98:101]
	v_mfma_f32_16x16x32_bf16 v[86:89], v[172:175], v[204:207], v[86:89]
	v_mfma_f32_16x16x32_bf16 v[82:85], v[180:183], v[204:207], v[82:85]
	v_mfma_f32_16x16x32_bf16 v[70:73], v[172:175], v[212:215], v[70:73]
	v_mfma_f32_16x16x32_bf16 v[66:69], v[180:183], v[212:215], v[66:69]
	s_setprio 0
	s_barrier
	s_add_i32 s45, s36, s2
	v_lshl_add_u64 v[216:217], s[24:25], 0, v[134:135]
	s_mov_b32 m0, s45
	ds_read_b128 v[184:187], v155 offset:16384
	ds_read_b128 v[188:191], v155 offset:17408
	ds_read_b128 v[192:195], v155 offset:18432
	ds_read_b128 v[196:199], v155 offset:19456
	ds_read_b128 v[200:203], v155 offset:20480
	ds_read_b128 v[204:207], v155 offset:21504
	ds_read_b128 v[208:211], v155 offset:22528
	ds_read_b128 v[212:215], v155 offset:23552
	global_load_lds_dwordx4 v134, s[24:25]
	s_add_i32 m0, s45, 0x2000
	s_add_u32 s46, s24, 0x80000
	v_lshl_add_u64 v[218:219], s[24:25], 0, v[130:131]
	s_addc_u32 s47, s25, 0
	s_add_i32 s45, s37, s2
	global_load_lds_dwordx4 v130, s[24:25]
	s_mov_b32 m0, s45
	v_lshl_add_u64 v[222:223], s[26:27], 0, v[132:133]
	global_load_lds_dwordx4 v134, s[46:47]
	s_add_i32 m0, s45, 0x2000
	s_nop 0
	global_load_lds_dwordx4 v130, s[46:47]
	v_lshl_add_u64 v[220:221], s[26:27], 0, v[136:137]
	s_mov_b32 m0, s21
	s_nop 0
	global_load_lds_dwordx4 v136, s[26:27]
	s_mov_b32 m0, s28
	s_nop 0
	global_load_lds_dwordx4 v132, s[26:27]
	s_waitcnt vmcnt(8)
	s_waitcnt lgkmcnt(0)
	s_barrier
; #define PG8_STAGE(bufoff, gbase, voff) do { _Pragma("unroll") for (int _i = 0; _i < 2; ++_i) \
;         __builtin_amdgcn_global_load_lds((const unsigned*)((const char*)(gbase) + (voff)[_i]), (PG8_LAS unsigned*)(lds + (bufoff) + ldsw + _i * 8192), 16, 0, 0); } while (0)
; #define PG8_LDA(dst, b, h) do { _Pragma("unroll") for (int m = 0; m < 4; ++m) _Pragma("unroll") for (int k = 0; k < 2; ++k) dst[m][k] = *(const PG8_LAS bf16x8*)(lds + PG8_SA(b, h) + aoff + m * 2048 + k * 1024); } while (0)
; #define PG8_LDB(dst, b, h) do { _Pragma("unroll") for (int n = 0; n < 2; ++n) _Pragma("unroll") for (int k = 0; k < 2; ++k) dst[n][k] = *(const PG8_LAS bf16x8*)(lds + PG8_SB(b, h) + boff + n * 2048 + k * 1024); } while (0)
; #define PG8_MMA(ai, bj, At, Bt) do { __builtin_amdgcn_s_setprio(1); _Pragma("unroll") for (int m = 0; m < 4; ++m) _Pragma("unroll") for (int n = 0; n < 2; ++n) _Pragma("unroll") for (int k = 0; k < 2; ++k) \
;         acc[ai][bj][m][n] = __builtin_amdgcn_mfma_f32_16x16x32_bf16(Bt[n][k], At[m][k], acc[ai][bj][m][n], 0, 0, 0); __builtin_amdgcn_s_setprio(0); } while (0)
; #define PG8_WAIT_V(n) asm volatile("s_waitcnt vmcnt(" #n ")" ::: "memory")
; #define PG8_WAIT_L(n) asm volatile("s_waitcnt lgkmcnt(" #n ")" ::: "memory")
; #define PG8_BAR __builtin_amdgcn_s_barrier()
; #define PG8_SCHED __builtin_amdgcn_sched_barrier(0)
; template <class Epi, class Sched, bool ALIGN_EPI = false, bool SP2 = false>
; __device__ __forceinline__ void gemm_phase(PG8_LAS unsigned char* lds, const Gemm g, const Sched& S, const Epi& E) {
;     ...
;             PG8_WAIT_V(8); PG8_WAIT_L(0); PG8_BAR; PG8_MMA(1, 0, At, B0); PG8_MMA(1, 1, At, B1); PG8_BAR; PG8_SCHED;
;             PG8_LDB(B0, 1, 0); PG8_LDB(B1, 1, 1); PG8_SCHED; PG8_LDA(At, 1, 0); PG8_STAGE(PG8_SA(0, 1), a2 + hstep, voffA);
;             PG8_WAIT_V(8); PG8_WAIT_L(0); PG8_BAR; PG8_MMA(0, 0, At, B0); PG8_MMA(0, 1, At, B1); PG8_BAR; PG8_SCHED;
	s_setprio 1
	s_waitcnt lgkmcnt(0)
	v_mfma_f32_16x16x32_bf16 v[62:65], v[146:149], v[184:187], v[62:65]
	v_mfma_f32_16x16x32_bf16 v[58:61], v[160:163], v[184:187], v[58:61]
	v_mfma_f32_16x16x32_bf16 v[46:49], v[146:149], v[192:195], v[46:49]
	v_mfma_f32_16x16x32_bf16 v[42:45], v[160:163], v[192:195], v[42:45]
	v_mfma_f32_16x16x32_bf16 v[30:33], v[146:149], v[200:203], v[30:33]
	v_mfma_f32_16x16x32_bf16 v[26:29], v[160:163], v[200:203], v[26:29]
	v_mfma_f32_16x16x32_bf16 v[14:17], v[146:149], v[208:211], v[14:17]
	v_mfma_f32_16x16x32_bf16 v[10:13], v[160:163], v[208:211], v[10:13]
	v_mfma_f32_16x16x32_bf16 v[62:65], v[156:159], v[188:191], v[62:65]
	v_mfma_f32_16x16x32_bf16 v[58:61], v[164:167], v[188:191], v[58:61]
	v_mfma_f32_16x16x32_bf16 v[46:49], v[156:159], v[196:199], v[46:49]
	v_mfma_f32_16x16x32_bf16 v[42:45], v[164:167], v[196:199], v[42:45]
	v_mfma_f32_16x16x32_bf16 v[30:33], v[156:159], v[204:207], v[30:33]
	v_mfma_f32_16x16x32_bf16 v[26:29], v[164:167], v[204:207], v[26:29]
	v_mfma_f32_16x16x32_bf16 v[14:17], v[156:159], v[212:215], v[14:17]
	v_mfma_f32_16x16x32_bf16 v[10:13], v[164:167], v[212:215], v[10:13]
	s_setprio 0
	s_setprio 1
	v_mfma_f32_16x16x32_bf16 v[54:57], v[168:171], v[184:187], v[54:57]
	v_mfma_f32_16x16x32_bf16 v[50:53], v[176:179], v[184:187], v[50:53]
	v_mfma_f32_16x16x32_bf16 v[38:41], v[168:171], v[192:195], v[38:41]
	v_mfma_f32_16x16x32_bf16 v[34:37], v[176:179], v[192:195], v[34:37]
	v_mfma_f32_16x16x32_bf16 v[22:25], v[168:171], v[200:203], v[22:25]
	v_mfma_f32_16x16x32_bf16 v[18:21], v[176:179], v[200:203], v[18:21]
	v_mfma_f32_16x16x32_bf16 v[6:9], v[168:171], v[208:211], v[6:9]
	v_mfma_f32_16x16x32_bf16 v[2:5], v[176:179], v[208:211], v[2:5]
	v_mfma_f32_16x16x32_bf16 v[54:57], v[172:175], v[188:191], v[54:57]
	v_mfma_f32_16x16x32_bf16 v[50:53], v[180:183], v[188:191], v[50:53]
	v_mfma_f32_16x16x32_bf16 v[38:41], v[172:175], v[196:199], v[38:41]
	v_mfma_f32_16x16x32_bf16 v[34:37], v[180:183], v[196:199], v[34:37]
	v_mfma_f32_16x16x32_bf16 v[22:25], v[172:175], v[204:207], v[22:25]
	v_mfma_f32_16x16x32_bf16 v[18:21], v[180:183], v[204:207], v[18:21]
	v_mfma_f32_16x16x32_bf16 v[6:9], v[172:175], v[212:215], v[6:9]
	v_mfma_f32_16x16x32_bf16 v[2:5], v[180:183], v[212:215], v[2:5]
	s_setprio 0
	s_barrier
	s_add_i32 s45, 0, 0x18000
	s_add_i32 s46, 0, 0x1c000
	v_add_u32_e32 v164, s45, v1
	v_add_u32_e32 v180, s46, v1
	ds_read_b128 v[146:149], v164
	ds_read_b128 v[156:159], v164 offset:1024
	ds_read_b128 v[160:163], v164 offset:2048
	ds_read_b128 v[164:167], v164 offset:3072
	ds_read_b128 v[168:171], v180
	ds_read_b128 v[172:175], v180 offset:1024
	ds_read_b128 v[176:179], v180 offset:2048
	ds_read_b128 v[180:183], v180 offset:3072
	s_add_u32 s26, s26, 0x80000
	s_addc_u32 s27, s27, 0
	s_mov_b32 m0, s29
	ds_read_b128 v[184:187], v155 offset:32768
	ds_read_b128 v[188:191], v155 offset:33792
	ds_read_b128 v[192:195], v155 offset:34816
	ds_read_b128 v[196:199], v155 offset:35840
	ds_read_b128 v[200:203], v155 offset:36864
	ds_read_b128 v[204:207], v155 offset:37888
	ds_read_b128 v[208:211], v155 offset:38912
	ds_read_b128 v[212:215], v155 offset:39936
	global_load_lds_dwordx4 v136, s[26:27]
	v_lshl_add_u64 v[224:225], s[26:27], 0, v[132:133]
	s_mov_b32 m0, s30
	s_nop 0
	global_load_lds_dwordx4 v132, s[26:27]
	s_waitcnt vmcnt(8)
	s_waitcnt lgkmcnt(0)
	s_barrier
	s_setprio 1
	s_waitcnt lgkmcnt(0)
	v_mfma_f32_16x16x32_bf16 v[126:129], v[146:149], v[184:187], v[126:129]
	v_mfma_f32_16x16x32_bf16 v[122:125], v[160:163], v[184:187], v[122:125]
	v_mfma_f32_16x16x32_bf16 v[110:113], v[146:149], v[192:195], v[110:113]
	v_mfma_f32_16x16x32_bf16 v[106:109], v[160:163], v[192:195], v[106:109]
	v_mfma_f32_16x16x32_bf16 v[94:97], v[146:149], v[200:203], v[94:97]
	v_mfma_f32_16x16x32_bf16 v[90:93], v[160:163], v[200:203], v[90:93]
	v_mfma_f32_16x16x32_bf16 v[78:81], v[146:149], v[208:211], v[78:81]
	v_mfma_f32_16x16x32_bf16 v[74:77], v[160:163], v[208:211], v[74:77]
	v_mfma_f32_16x16x32_bf16 v[126:129], v[156:159], v[188:191], v[126:129]
	v_mfma_f32_16x16x32_bf16 v[122:125], v[164:167], v[188:191], v[122:125]
	v_mfma_f32_16x16x32_bf16 v[110:113], v[156:159], v[196:199], v[110:113]
	v_mfma_f32_16x16x32_bf16 v[106:109], v[164:167], v[196:199], v[106:109]
	v_mfma_f32_16x16x32_bf16 v[94:97], v[156:159], v[204:207], v[94:97]
	v_mfma_f32_16x16x32_bf16 v[90:93], v[164:167], v[204:207], v[90:93]
	v_mfma_f32_16x16x32_bf16 v[78:81], v[156:159], v[212:215], v[78:81]
	v_mfma_f32_16x16x32_bf16 v[74:77], v[164:167], v[212:215], v[74:77]
	s_setprio 0
	s_setprio 1
	v_mfma_f32_16x16x32_bf16 v[118:121], v[168:171], v[184:187], v[118:121]
	v_mfma_f32_16x16x32_bf16 v[114:117], v[176:179], v[184:187], v[114:117]
	v_mfma_f32_16x16x32_bf16 v[102:105], v[168:171], v[192:195], v[102:105]
	v_mfma_f32_16x16x32_bf16 v[98:101], v[176:179], v[192:195], v[98:101]
	v_mfma_f32_16x16x32_bf16 v[86:89], v[168:171], v[200:203], v[86:89]
	v_mfma_f32_16x16x32_bf16 v[82:85], v[176:179], v[200:203], v[82:85]
	v_mfma_f32_16x16x32_bf16 v[70:73], v[168:171], v[208:211], v[70:73]
	v_mfma_f32_16x16x32_bf16 v[66:69], v[176:179], v[208:211], v[66:69]
	v_mfma_f32_16x16x32_bf16 v[118:121], v[172:175], v[188:191], v[118:121]
	v_mfma_f32_16x16x32_bf16 v[114:117], v[180:183], v[188:191], v[114:117]
	v_mfma_f32_16x16x32_bf16 v[102:105], v[172:175], v[196:199], v[102:105]
	v_mfma_f32_16x16x32_bf16 v[98:101], v[180:183], v[196:199], v[98:101]
	v_mfma_f32_16x16x32_bf16 v[86:89], v[172:175], v[204:207], v[86:89]
	v_mfma_f32_16x16x32_bf16 v[82:85], v[180:183], v[204:207], v[82:85]
	v_mfma_f32_16x16x32_bf16 v[70:73], v[172:175], v[212:215], v[70:73]
	v_mfma_f32_16x16x32_bf16 v[66:69], v[180:183], v[212:215], v[66:69]
	s_setprio 0
	s_barrier
; #define PG8_STAGE(bufoff, gbase, voff) do { _Pragma("unroll") for (int _i = 0; _i < 2; ++_i) \
;         __builtin_amdgcn_global_load_lds((const unsigned*)((const char*)(gbase) + (voff)[_i]), (PG8_LAS unsigned*)(lds + (bufoff) + ldsw + _i * 8192), 16, 0, 0); } while (0)
; #define PG8_LDA(dst, b, h) do { _Pragma("unroll") for (int m = 0; m < 4; ++m) _Pragma("unroll") for (int k = 0; k < 2; ++k) dst[m][k] = *(const PG8_LAS bf16x8*)(lds + PG8_SA(b, h) + aoff + m * 2048 + k * 1024); } while (0)
; #define PG8_MMA(ai, bj, At, Bt) do { __builtin_amdgcn_s_setprio(1); _Pragma("unroll") for (int m = 0; m < 4; ++m) _Pragma("unroll") for (int n = 0; n < 2; ++n) _Pragma("unroll") for (int k = 0; k < 2; ++k) \
;         acc[ai][bj][m][n] = __builtin_amdgcn_mfma_f32_16x16x32_bf16(Bt[n][k], At[m][k], acc[ai][bj][m][n], 0, 0, 0); __builtin_amdgcn_s_setprio(0); } while (0)
; #define PG8_WAIT_V(n) asm volatile("s_waitcnt vmcnt(" #n ")" ::: "memory")
; #define PG8_WAIT_L(n) asm volatile("s_waitcnt lgkmcnt(" #n ")" ::: "memory")
; #define PG8_BAR __builtin_amdgcn_s_barrier()
; #define PG8_SCHED __builtin_amdgcn_sched_barrier(0)
; template <class Epi, class Sched, bool ALIGN_EPI = false, bool SP2 = false>
; __device__ __forceinline__ void gemm_phase(PG8_LAS unsigned char* lds, const Gemm g, const Sched& S, const Epi& E) {
;     ...
;         for (int t = 0; t < nt; t += 2) {
;     ...
;             PG8_LDA(At, 1, 1); PG8_STAGE(PG8_SB(1, 0), b3, voffB); PG8_STAGE(PG8_SB(1, 1), b3 + hstep, voffB); PG8_STAGE(PG8_SA(1, 0), a3, voffA);
;             PG8_WAIT_V(8); PG8_WAIT_L(0); PG8_BAR; PG8_MMA(1, 0, At, B0); PG8_MMA(1, 1, At, B1); PG8_BAR; PG8_SCHED;
;     ...
;         if constexpr (ALIGN_EPI) { if (wr == 0) PG8_BAR; }
	s_add_i32 s26, s45, s2
	v_lshl_add_u64 v[216:217], v[216:217], 0, s[8:9]
	s_mov_b32 m0, s26
	ds_read_b128 v[184:187], v155 offset:49152
	ds_read_b128 v[188:191], v155 offset:50176
	ds_read_b128 v[192:195], v155 offset:51200
	ds_read_b128 v[196:199], v155 offset:52224
	ds_read_b128 v[200:203], v155 offset:53248
	ds_read_b128 v[204:207], v155 offset:54272
	ds_read_b128 v[208:211], v155 offset:55296
	ds_read_b128 v[212:215], v155 offset:56320
	global_load_lds_dwordx4 v[216:217], off
	s_add_i32 m0, s26, 0x2000
	s_add_u32 s24, s24, 0x80080
	v_lshl_add_u64 v[216:217], v[218:219], 0, s[8:9]
	s_addc_u32 s25, s25, 0
	s_add_i32 s26, s46, s2
	global_load_lds_dwordx4 v[216:217], off
	s_mov_b32 m0, s26
	s_nop 0
	global_load_lds_dwordx4 v134, s[24:25]
	s_add_i32 m0, s26, 0x2000
	s_nop 0
	global_load_lds_dwordx4 v130, s[24:25]
	v_lshl_add_u64 v[216:217], v[220:221], 0, s[8:9]
	s_mov_b32 m0, s34
	s_nop 0
	global_load_lds_dwordx4 v[216:217], off
	v_lshl_add_u64 v[216:217], v[222:223], 0, s[8:9]
	s_mov_b32 m0, s35
	s_nop 0
	global_load_lds_dwordx4 v[216:217], off
	s_waitcnt vmcnt(8)
	s_waitcnt lgkmcnt(0)
	s_barrier
	s_setprio 1
	s_waitcnt lgkmcnt(0)
	v_mfma_f32_16x16x32_bf16 v[62:65], v[146:149], v[184:187], v[62:65]
	v_mfma_f32_16x16x32_bf16 v[58:61], v[160:163], v[184:187], v[58:61]
	v_mfma_f32_16x16x32_bf16 v[46:49], v[146:149], v[192:195], v[46:49]
	v_mfma_f32_16x16x32_bf16 v[42:45], v[160:163], v[192:195], v[42:45]
	v_mfma_f32_16x16x32_bf16 v[30:33], v[146:149], v[200:203], v[30:33]
	v_mfma_f32_16x16x32_bf16 v[26:29], v[160:163], v[200:203], v[26:29]
	v_mfma_f32_16x16x32_bf16 v[14:17], v[146:149], v[208:211], v[14:17]
	v_mfma_f32_16x16x32_bf16 v[10:13], v[160:163], v[208:211], v[10:13]
	v_mfma_f32_16x16x32_bf16 v[62:65], v[156:159], v[188:191], v[62:65]
	v_mfma_f32_16x16x32_bf16 v[58:61], v[164:167], v[188:191], v[58:61]
	v_mfma_f32_16x16x32_bf16 v[46:49], v[156:159], v[196:199], v[46:49]
	v_mfma_f32_16x16x32_bf16 v[42:45], v[164:167], v[196:199], v[42:45]
	v_mfma_f32_16x16x32_bf16 v[30:33], v[156:159], v[204:207], v[30:33]
	v_mfma_f32_16x16x32_bf16 v[26:29], v[164:167], v[204:207], v[26:29]
	v_mfma_f32_16x16x32_bf16 v[14:17], v[156:159], v[212:215], v[14:17]
	v_mfma_f32_16x16x32_bf16 v[10:13], v[164:167], v[212:215], v[10:13]
	s_setprio 0
	s_setprio 1
	v_mfma_f32_16x16x32_bf16 v[54:57], v[168:171], v[184:187], v[54:57]
	v_mfma_f32_16x16x32_bf16 v[50:53], v[176:179], v[184:187], v[50:53]
	v_mfma_f32_16x16x32_bf16 v[38:41], v[168:171], v[192:195], v[38:41]
	v_mfma_f32_16x16x32_bf16 v[34:37], v[176:179], v[192:195], v[34:37]
	v_mfma_f32_16x16x32_bf16 v[22:25], v[168:171], v[200:203], v[22:25]
	v_mfma_f32_16x16x32_bf16 v[18:21], v[176:179], v[200:203], v[18:21]
	v_mfma_f32_16x16x32_bf16 v[6:9], v[168:171], v[208:211], v[6:9]
	v_mfma_f32_16x16x32_bf16 v[2:5], v[176:179], v[208:211], v[2:5]
	v_mfma_f32_16x16x32_bf16 v[54:57], v[172:175], v[188:191], v[54:57]
	v_mfma_f32_16x16x32_bf16 v[50:53], v[180:183], v[188:191], v[50:53]
	v_mfma_f32_16x16x32_bf16 v[38:41], v[172:175], v[196:199], v[38:41]
	v_mfma_f32_16x16x32_bf16 v[34:37], v[180:183], v[196:199], v[34:37]
	v_mfma_f32_16x16x32_bf16 v[22:25], v[172:175], v[204:207], v[22:25]
	v_mfma_f32_16x16x32_bf16 v[18:21], v[180:183], v[204:207], v[18:21]
	v_mfma_f32_16x16x32_bf16 v[6:9], v[172:175], v[212:215], v[6:9]
	v_mfma_f32_16x16x32_bf16 v[2:5], v[180:183], v[212:215], v[2:5]
	s_setprio 0
	s_barrier
	s_add_i32 s44, s44, 2
	s_add_u32 s22, s22, 0x100
	s_addc_u32 s23, s23, 0
	s_add_u32 s42, s42, 0x100
	s_addc_u32 s43, s43, 0
	s_cmp_gt_u32 s44, 29
	s_cbranch_scc0 .LBB0_2774
	s_and_b64 vcc, exec, s[10:11]
	s_cbranch_vccz .LBB0_2777
	s_barrier

; #define PG8_STAGE(bufoff, gbase, voff) do { _Pragma("unroll") for (int _i = 0; _i < 2; ++_i) \
;         __builtin_amdgcn_global_load_lds((const unsigned*)((const char*)(gbase) + (voff)[_i]), (PG8_LAS unsigned*)(lds + (bufoff) + ldsw + _i * 8192), 16, 0, 0); } while (0)
; #define PG8_WAIT_V(n) asm volatile("s_waitcnt vmcnt(" #n ")" ::: "memory")
; #define PG8_BAR __builtin_amdgcn_s_barrier()
; template <class Epi, class Sched, bool ALIGN_EPI = false, bool SP2 = false>
; __device__ __forceinline__ void gemm_phase(PG8_LAS unsigned char* lds, const Gemm g, const Sched& S, const Epi& E) {
;     ...
;     for (int i = 0; i < 2; ++i) { int R, C; stage_rc(tid * 16 + i * 8192, R, C); const int Rb = Epi::PERM ? ((R & ~31) + perm32(R & 31)) : R;
;         voffA[i] = (unsigned)(R * K + C) * 2u; voffB[i] = (unsigned)(Rb * K + C) * 2u; }
;     const size_t kstep = (size_t)(BK * 2);
;     const size_t hstep = (size_t)HALF * K * 2;
;     const size_t tstep = 2 * hstep;
;     const unsigned ldsw = (unsigned)wid * 1024u;
;     const int aoff = lds_byte(wr * 64 + fr, fq * 8), boff = lds_byte(wc * 32 + fr, fq * 8);
;     ...
;         PG8_STAGE(PG8_SB(1, 0), cB + kstep, voffB); PG8_STAGE(PG8_SA(1, 0), cA + kstep, voffA); PG8_STAGE(PG8_SB(1, 1), cB + hstep + kstep, voffB);
;         PG8_WAIT_V(6); PG8_BAR;
.LBB0_2857:
	s_lshl_b32 s8, s8, 5
	s_and_b32 s16, s8, 0x60
	s_mov_b64 s[8:9], 0x80
	s_add_i32 m0, s3, 0x18000
	v_lshl_add_u64 v[8:9], v[8:9], 0, s[8:9]
	s_lshl_b32 s13, s0, 13
	s_lshl_b32 s14, s16, 7
	s_waitcnt vmcnt(2)
	s_barrier
	global_load_lds_dwordx4 v[8:9], off
	v_lshl_add_u64 v[4:5], v[4:5], 0, s[8:9]
	s_add_i32 m0, s3, 0x1a000
	s_add_i32 s36, s3, 0x8000
	s_add_i32 s37, s3, 0xa000
	global_load_lds_dwordx4 v[4:5], off
	v_lshl_add_u64 v[2:3], v[2:3], 0, s[8:9]
	s_mov_b32 m0, s36
	s_add_u32 s10, s24, 0x160080
	global_load_lds_dwordx4 v[2:3], off
	v_lshl_add_u64 v[2:3], v[6:7], 0, s[8:9]
	s_mov_b32 m0, s37
	s_addc_u32 s11, s25, 0
	global_load_lds_dwordx4 v[2:3], off
	s_add_i32 m0, s3, 0x1c000
	s_nop 0
	global_load_lds_dwordx4 v132, s[10:11]
	v_lshl_add_u64 v[2:3], s[10:11], 0, v[136:137]
	s_add_i32 m0, s3, 0x1e000
	v_and_b32_e32 v1, 15, v10
	global_load_lds_dwordx4 v136, s[10:11]
	v_bfe_u32 v2, v10, 4, 2
	v_lshlrev_b32_e32 v3, 4, v2
	v_lshl_or_b32 v1, v1, 6, v3
	v_lshlrev_b32_e32 v3, 2, v10
	v_and_b32_e32 v3, 32, v3
	v_bitop3_b32 v4, v1, s13, v3 bitop3:0xde
	v_bitop3_b32 v1, v1, s14, v3 bitop3:0xde
	v_bfe_u32 v3, v10, 2, 2
	v_lshl_or_b32 v2, v2, 2, v3
	v_and_b32_e32 v3, 3, v10
	v_lshlrev_b32_e32 v5, 6, v3
	v_lshl_or_b32 v146, v2, 2, v5
	v_lshl_or_b32 v147, s0, 6, v2
	v_lshl_or_b32 v148, v3, 3, s16
	v_lshrrev_b32_e32 v3, 1, v11
	v_mul_lo_u32 v2, v12, s1
	s_sext_i32_i8 s47, s7
	s_cmpk_lt_u32 s6, 0x100
	v_mad_u64_u32 v[2:3], s[6:7], v3, s12, v[2:3]
	v_or_b32_e32 v2, v2, v13
	s_mov_b64 s[14:15], 0x160080
	v_add_lshl_u32 v2, v2, v14, 1
	v_mov_b32_e32 v3, v133
	v_lshl_add_u64 v[138:139], v[2:3], 0, s[14:15]
	v_lshrrev_b32_e32 v3, 1, v15
	v_mul_lo_u32 v2, v16, s1
	v_mad_u64_u32 v[2:3], s[0:1], v3, s12, v[2:3]
	s_waitcnt vmcnt(6)
	v_or_b32_e32 v2, v2, v17
	s_cselect_b64 s[10:11], -1, 0
	v_add_lshl_u32 v2, v2, v18, 1
	v_mov_b32_e32 v3, v133
	s_add_i32 s38, 0, 0x10000
	s_add_i32 s39, 0, 0x14000
	v_lshl_add_u64 v[140:141], v[2:3], 0, s[14:15]
	v_mov_b64_e32 v[142:143], 0x200
	v_mov_b64_e32 v[144:145], 0x1ff
	v_add_u32_e32 v149, s38, v1
	v_add_u32_e32 v150, s39, v1
	v_add_u32_e32 v151, 0, v4
	s_mov_b64 s[12:13], 0x80000
	s_mov_b32 s40, 0x80000
	s_mov_b64 s[14:15], 0x90000
	s_mov_b32 s41, 0x90000
	s_mov_b64 s[16:17], 0xa0000
	s_mov_b32 s42, 0xa0000
	s_mov_b64 s[18:19], 0xb0000
	s_mov_b32 s43, 0xb0000
	s_barrier
	s_waitcnt vmcnt(0)
	s_branch .LBB0_2860

; #define PG8_STAGE(bufoff, gbase, voff) do { _Pragma("unroll") for (int _i = 0; _i < 2; ++_i) \
;         __builtin_amdgcn_global_load_lds((const unsigned*)((const char*)(gbase) + (voff)[_i]), (PG8_LAS unsigned*)(lds + (bufoff) + ldsw + _i * 8192), 16, 0, 0); } while (0)
; #define PG8_LDA(dst, b, h) do { _Pragma("unroll") for (int m = 0; m < 4; ++m) _Pragma("unroll") for (int k = 0; k < 2; ++k) dst[m][k] = *(const PG8_LAS bf16x8*)(lds + PG8_SA(b, h) + aoff + m * 2048 + k * 1024); } while (0)
; #define PG8_LDB(dst, b, h) do { _Pragma("unroll") for (int n = 0; n < 2; ++n) _Pragma("unroll") for (int k = 0; k < 2; ++k) dst[n][k] = *(const PG8_LAS bf16x8*)(lds + PG8_SB(b, h) + boff + n * 2048 + k * 1024); } while (0)
; #define PG8_MMA(ai, bj, At, Bt) do { __builtin_amdgcn_s_setprio(1); _Pragma("unroll") for (int m = 0; m < 4; ++m) _Pragma("unroll") for (int n = 0; n < 2; ++n) _Pragma("unroll") for (int k = 0; k < 2; ++k) \
;         acc[ai][bj][m][n] = __builtin_amdgcn_mfma_f32_16x16x32_bf16(Bt[n][k], At[m][k], acc[ai][bj][m][n], 0, 0, 0); __builtin_amdgcn_s_setprio(0); } while (0)
; #define PG8_WAIT_V(n) asm volatile("s_waitcnt vmcnt(" #n ")" ::: "memory")
; #define PG8_WAIT_L(n) asm volatile("s_waitcnt lgkmcnt(" #n ")" ::: "memory")
; #define PG8_BAR __builtin_amdgcn_s_barrier()
; #define PG8_SCHED __builtin_amdgcn_sched_barrier(0)
; template <class Epi, class Sched, bool ALIGN_EPI = false, bool SP2 = false>
; __device__ __forceinline__ void gemm_phase(PG8_LAS unsigned char* lds, const Gemm g, const Sched& S, const Epi& E) {
;     ...
;             PG8_LDB(B0, 0, 0); PG8_LDB(B1, 0, 1); PG8_SCHED; PG8_LDA(At, 0, 0); PG8_STAGE(PG8_SA(1, 1), a1 + hstep, voffA);
;             PG8_WAIT_V(8); PG8_WAIT_L(0); PG8_BAR; PG8_MMA(0, 0, At, B0); PG8_MMA(0, 1, At, B1); PG8_BAR; PG8_SCHED;
;             PG8_LDA(At, 0, 1); PG8_STAGE(PG8_SB(0, 0), b2, voffB); PG8_STAGE(PG8_SB(0, 1), b2 + hstep, voffB); PG8_STAGE(PG8_SA(0, 0), a2, voffA);
.LBB0_2871:
	ds_read_b128 v[152:155], v149
	ds_read_b128 v[156:159], v149 offset:1024
	ds_read_b128 v[160:163], v149 offset:2048
	ds_read_b128 v[164:167], v149 offset:3072
	ds_read_b128 v[168:171], v150
	ds_read_b128 v[172:175], v150 offset:1024
	ds_read_b128 v[176:179], v150 offset:2048
	ds_read_b128 v[180:183], v150 offset:3072
	s_add_u32 s24, s22, 0x100
	s_addc_u32 s25, s23, 0
	s_cmpk_eq_i32 s51, 0x54
	s_cselect_b32 s29, s7, s25
	s_cselect_b32 s28, s6, s24
	s_cselect_b32 s27, s21, s49
	s_cselect_b32 s26, s20, s48
	s_add_i32 m0, s3, 0xc000
	ds_read_b128 v[184:187], v151
	ds_read_b128 v[188:191], v151 offset:1024
	ds_read_b128 v[192:195], v151 offset:2048
	ds_read_b128 v[196:199], v151 offset:3072
	ds_read_b128 v[200:203], v151 offset:4096
	ds_read_b128 v[204:207], v151 offset:5120
	ds_read_b128 v[208:211], v151 offset:6144
	ds_read_b128 v[212:215], v151 offset:7168
	global_load_lds_dwordx4 v138, s[22:23]
	s_add_i32 m0, s3, 0xe000
	s_nop 0
	global_load_lds_dwordx4 v140, s[22:23]
	s_waitcnt vmcnt(8)
	s_waitcnt lgkmcnt(0)
	s_barrier
	s_setprio 1
	s_waitcnt lgkmcnt(0)
	v_mfma_f32_16x16x32_bf16 v[126:129], v[152:155], v[184:187], v[126:129]
	v_mfma_f32_16x16x32_bf16 v[122:125], v[160:163], v[184:187], v[122:125]
	v_mfma_f32_16x16x32_bf16 v[118:121], v[152:155], v[192:195], v[118:121]
	v_mfma_f32_16x16x32_bf16 v[110:113], v[160:163], v[192:195], v[110:113]
	v_mfma_f32_16x16x32_bf16 v[102:105], v[152:155], v[200:203], v[102:105]
	v_mfma_f32_16x16x32_bf16 v[94:97], v[160:163], v[200:203], v[94:97]
	v_mfma_f32_16x16x32_bf16 v[86:89], v[152:155], v[208:211], v[86:89]
	v_mfma_f32_16x16x32_bf16 v[78:81], v[160:163], v[208:211], v[78:81]
	v_mfma_f32_16x16x32_bf16 v[126:129], v[156:159], v[188:191], v[126:129]
	v_mfma_f32_16x16x32_bf16 v[122:125], v[164:167], v[188:191], v[122:125]
	v_mfma_f32_16x16x32_bf16 v[118:121], v[156:159], v[196:199], v[118:121]
	v_mfma_f32_16x16x32_bf16 v[110:113], v[164:167], v[196:199], v[110:113]
	v_mfma_f32_16x16x32_bf16 v[102:105], v[156:159], v[204:207], v[102:105]
	v_mfma_f32_16x16x32_bf16 v[94:97], v[164:167], v[204:207], v[94:97]
	v_mfma_f32_16x16x32_bf16 v[86:89], v[156:159], v[212:215], v[86:89]
	v_mfma_f32_16x16x32_bf16 v[78:81], v[164:167], v[212:215], v[78:81]
	s_setprio 0
	s_setprio 1
	v_mfma_f32_16x16x32_bf16 v[114:117], v[168:171], v[184:187], v[114:117]
	v_mfma_f32_16x16x32_bf16 v[106:109], v[176:179], v[184:187], v[106:109]
	v_mfma_f32_16x16x32_bf16 v[98:101], v[168:171], v[192:195], v[98:101]
	v_mfma_f32_16x16x32_bf16 v[90:93], v[176:179], v[192:195], v[90:93]
	v_mfma_f32_16x16x32_bf16 v[82:85], v[168:171], v[200:203], v[82:85]
	v_mfma_f32_16x16x32_bf16 v[74:77], v[176:179], v[200:203], v[74:77]
	v_mfma_f32_16x16x32_bf16 v[70:73], v[168:171], v[208:211], v[70:73]
	v_mfma_f32_16x16x32_bf16 v[66:69], v[176:179], v[208:211], v[66:69]
	v_mfma_f32_16x16x32_bf16 v[114:117], v[172:175], v[188:191], v[114:117]
	v_mfma_f32_16x16x32_bf16 v[106:109], v[180:183], v[188:191], v[106:109]
	v_mfma_f32_16x16x32_bf16 v[98:101], v[172:175], v[196:199], v[98:101]
	v_mfma_f32_16x16x32_bf16 v[90:93], v[180:183], v[196:199], v[90:93]
	v_mfma_f32_16x16x32_bf16 v[82:85], v[172:175], v[204:207], v[82:85]
	v_mfma_f32_16x16x32_bf16 v[74:77], v[180:183], v[204:207], v[74:77]
	v_mfma_f32_16x16x32_bf16 v[70:73], v[172:175], v[212:215], v[70:73]
	v_mfma_f32_16x16x32_bf16 v[66:69], v[180:183], v[212:215], v[66:69]
	s_setprio 0
	s_barrier
	s_add_i32 s22, s38, s2
	v_lshl_add_u64 v[216:217], s[26:27], 0, v[132:133]
	s_mov_b32 m0, s22
	ds_read_b128 v[184:187], v151 offset:16384
	ds_read_b128 v[188:191], v151 offset:17408
	ds_read_b128 v[192:195], v151 offset:18432
	ds_read_b128 v[196:199], v151 offset:19456
	ds_read_b128 v[200:203], v151 offset:20480
	ds_read_b128 v[204:207], v151 offset:21504
	ds_read_b128 v[208:211], v151 offset:22528
	ds_read_b128 v[212:215], v151 offset:23552
	global_load_lds_dwordx4 v132, s[26:27]
	s_add_i32 m0, s22, 0x2000
	s_add_u32 s22, s26, 0x160000
	v_lshl_add_u64 v[218:219], s[26:27], 0, v[136:137]
	s_addc_u32 s23, s27, 0
	s_add_i32 s52, s39, s2
	global_load_lds_dwordx4 v136, s[26:27]
	s_mov_b32 m0, s52
	v_lshl_add_u64 v[222:223], s[28:29], 0, v[134:135]
	global_load_lds_dwordx4 v132, s[22:23]
	s_add_i32 m0, s52, 0x2000
	s_nop 0
	global_load_lds_dwordx4 v136, s[22:23]
	v_lshl_add_u64 v[220:221], s[28:29], 0, v[130:131]
	s_mov_b32 m0, s3
	s_nop 0
	global_load_lds_dwordx4 v130, s[28:29]
	s_mov_b32 m0, s30
	s_nop 0
	global_load_lds_dwordx4 v134, s[28:29]
	s_waitcnt vmcnt(8)
	s_waitcnt lgkmcnt(0)
	s_barrier
; #define PG8_STAGE(bufoff, gbase, voff) do { _Pragma("unroll") for (int _i = 0; _i < 2; ++_i) \
;         __builtin_amdgcn_global_load_lds((const unsigned*)((const char*)(gbase) + (voff)[_i]), (PG8_LAS unsigned*)(lds + (bufoff) + ldsw + _i * 8192), 16, 0, 0); } while (0)
; #define PG8_LDA(dst, b, h) do { _Pragma("unroll") for (int m = 0; m < 4; ++m) _Pragma("unroll") for (int k = 0; k < 2; ++k) dst[m][k] = *(const PG8_LAS bf16x8*)(lds + PG8_SA(b, h) + aoff + m * 2048 + k * 1024); } while (0)
; #define PG8_LDB(dst, b, h) do { _Pragma("unroll") for (int n = 0; n < 2; ++n) _Pragma("unroll") for (int k = 0; k < 2; ++k) dst[n][k] = *(const PG8_LAS bf16x8*)(lds + PG8_SB(b, h) + boff + n * 2048 + k * 1024); } while (0)
; #define PG8_MMA(ai, bj, At, Bt) do { __builtin_amdgcn_s_setprio(1); _Pragma("unroll") for (int m = 0; m < 4; ++m) _Pragma("unroll") for (int n = 0; n < 2; ++n) _Pragma("unroll") for (int k = 0; k < 2; ++k) \
;         acc[ai][bj][m][n] = __builtin_amdgcn_mfma_f32_16x16x32_bf16(Bt[n][k], At[m][k], acc[ai][bj][m][n], 0, 0, 0); __builtin_amdgcn_s_setprio(0); } while (0)
; #define PG8_WAIT_V(n) asm volatile("s_waitcnt vmcnt(" #n ")" ::: "memory")
; #define PG8_WAIT_L(n) asm volatile("s_waitcnt lgkmcnt(" #n ")" ::: "memory")
; #define PG8_BAR __builtin_amdgcn_s_barrier()
; #define PG8_SCHED __builtin_amdgcn_sched_barrier(0)
; template <class Epi, class Sched, bool ALIGN_EPI = false, bool SP2 = false>
; __device__ __forceinline__ void gemm_phase(PG8_LAS unsigned char* lds, const Gemm g, const Sched& S, const Epi& E) {
;     ...
;             PG8_WAIT_V(8); PG8_WAIT_L(0); PG8_BAR; PG8_MMA(1, 0, At, B0); PG8_MMA(1, 1, At, B1); PG8_BAR; PG8_SCHED;
;             PG8_LDB(B0, 1, 0); PG8_LDB(B1, 1, 1); PG8_SCHED; PG8_LDA(At, 1, 0); PG8_STAGE(PG8_SA(0, 1), a2 + hstep, voffA);
;             PG8_WAIT_V(8); PG8_WAIT_L(0); PG8_BAR; PG8_MMA(0, 0, At, B0); PG8_MMA(0, 1, At, B1); PG8_BAR; PG8_SCHED;
	s_setprio 1
	s_waitcnt lgkmcnt(0)
	v_mfma_f32_16x16x32_bf16 v[62:65], v[152:155], v[184:187], v[62:65]
	v_mfma_f32_16x16x32_bf16 v[58:61], v[160:163], v[184:187], v[58:61]
	v_mfma_f32_16x16x32_bf16 v[54:57], v[152:155], v[192:195], v[54:57]
	v_mfma_f32_16x16x32_bf16 v[50:53], v[160:163], v[192:195], v[50:53]
	v_mfma_f32_16x16x32_bf16 v[38:41], v[152:155], v[200:203], v[38:41]
	v_mfma_f32_16x16x32_bf16 v[34:37], v[160:163], v[200:203], v[34:37]
	v_mfma_f32_16x16x32_bf16 v[22:25], v[152:155], v[208:211], v[22:25]
	v_mfma_f32_16x16x32_bf16 v[18:21], v[160:163], v[208:211], v[18:21]
	v_mfma_f32_16x16x32_bf16 v[62:65], v[156:159], v[188:191], v[62:65]
	v_mfma_f32_16x16x32_bf16 v[58:61], v[164:167], v[188:191], v[58:61]
	v_mfma_f32_16x16x32_bf16 v[54:57], v[156:159], v[196:199], v[54:57]
	v_mfma_f32_16x16x32_bf16 v[50:53], v[164:167], v[196:199], v[50:53]
	v_mfma_f32_16x16x32_bf16 v[38:41], v[156:159], v[204:207], v[38:41]
	v_mfma_f32_16x16x32_bf16 v[34:37], v[164:167], v[204:207], v[34:37]
	v_mfma_f32_16x16x32_bf16 v[22:25], v[156:159], v[212:215], v[22:25]
	v_mfma_f32_16x16x32_bf16 v[18:21], v[164:167], v[212:215], v[18:21]
	s_setprio 0
	s_setprio 1
	v_mfma_f32_16x16x32_bf16 v[46:49], v[168:171], v[184:187], v[46:49]
	v_mfma_f32_16x16x32_bf16 v[42:45], v[176:179], v[184:187], v[42:45]
	v_mfma_f32_16x16x32_bf16 v[30:33], v[168:171], v[192:195], v[30:33]
	v_mfma_f32_16x16x32_bf16 v[26:29], v[176:179], v[192:195], v[26:29]
	v_mfma_f32_16x16x32_bf16 v[14:17], v[168:171], v[200:203], v[14:17]
	v_mfma_f32_16x16x32_bf16 v[10:13], v[176:179], v[200:203], v[10:13]
	v_mfma_f32_16x16x32_bf16 v[6:9], v[168:171], v[208:211], v[6:9]
	v_mfma_f32_16x16x32_bf16 v[2:5], v[176:179], v[208:211], v[2:5]
	v_mfma_f32_16x16x32_bf16 v[46:49], v[172:175], v[188:191], v[46:49]
	v_mfma_f32_16x16x32_bf16 v[42:45], v[180:183], v[188:191], v[42:45]
	v_mfma_f32_16x16x32_bf16 v[30:33], v[172:175], v[196:199], v[30:33]
	v_mfma_f32_16x16x32_bf16 v[26:29], v[180:183], v[196:199], v[26:29]
	v_mfma_f32_16x16x32_bf16 v[14:17], v[172:175], v[204:207], v[14:17]
	v_mfma_f32_16x16x32_bf16 v[10:13], v[180:183], v[204:207], v[10:13]
	v_mfma_f32_16x16x32_bf16 v[6:9], v[172:175], v[212:215], v[6:9]
	v_mfma_f32_16x16x32_bf16 v[2:5], v[180:183], v[212:215], v[2:5]
	s_setprio 0
	s_barrier
	s_add_i32 s52, 0, 0x18000
	s_add_i32 s53, 0, 0x1c000
	v_add_u32_e32 v164, s52, v1
	v_add_u32_e32 v180, s53, v1
	ds_read_b128 v[152:155], v164
	ds_read_b128 v[156:159], v164 offset:1024
	ds_read_b128 v[160:163], v164 offset:2048
	ds_read_b128 v[164:167], v164 offset:3072
	ds_read_b128 v[168:171], v180
	ds_read_b128 v[172:175], v180 offset:1024
	ds_read_b128 v[176:179], v180 offset:2048
	ds_read_b128 v[180:183], v180 offset:3072
	s_add_u32 s22, s28, 0x160000
	s_addc_u32 s23, s29, 0
	s_mov_b32 m0, s31
	ds_read_b128 v[184:187], v151 offset:32768
	ds_read_b128 v[188:191], v151 offset:33792
	ds_read_b128 v[192:195], v151 offset:34816
	ds_read_b128 v[196:199], v151 offset:35840
	ds_read_b128 v[200:203], v151 offset:36864
	ds_read_b128 v[204:207], v151 offset:37888
	ds_read_b128 v[208:211], v151 offset:38912
	ds_read_b128 v[212:215], v151 offset:39936
	global_load_lds_dwordx4 v130, s[22:23]
	v_lshl_add_u64 v[224:225], s[22:23], 0, v[134:135]
	s_mov_b32 m0, s34
	s_nop 0
	global_load_lds_dwordx4 v134, s[22:23]
	s_waitcnt vmcnt(8)
	s_waitcnt lgkmcnt(0)
	s_barrier
	s_setprio 1
	s_waitcnt lgkmcnt(0)
	v_mfma_f32_16x16x32_bf16 v[126:129], v[152:155], v[184:187], v[126:129]
	v_mfma_f32_16x16x32_bf16 v[122:125], v[160:163], v[184:187], v[122:125]
	v_mfma_f32_16x16x32_bf16 v[118:121], v[152:155], v[192:195], v[118:121]
	v_mfma_f32_16x16x32_bf16 v[110:113], v[160:163], v[192:195], v[110:113]
	v_mfma_f32_16x16x32_bf16 v[102:105], v[152:155], v[200:203], v[102:105]
	v_mfma_f32_16x16x32_bf16 v[94:97], v[160:163], v[200:203], v[94:97]
	v_mfma_f32_16x16x32_bf16 v[86:89], v[152:155], v[208:211], v[86:89]
	v_mfma_f32_16x16x32_bf16 v[78:81], v[160:163], v[208:211], v[78:81]
	v_mfma_f32_16x16x32_bf16 v[126:129], v[156:159], v[188:191], v[126:129]
	v_mfma_f32_16x16x32_bf16 v[122:125], v[164:167], v[188:191], v[122:125]
	v_mfma_f32_16x16x32_bf16 v[118:121], v[156:159], v[196:199], v[118:121]
	v_mfma_f32_16x16x32_bf16 v[110:113], v[164:167], v[196:199], v[110:113]
	v_mfma_f32_16x16x32_bf16 v[102:105], v[156:159], v[204:207], v[102:105]
	v_mfma_f32_16x16x32_bf16 v[94:97], v[164:167], v[204:207], v[94:97]
	v_mfma_f32_16x16x32_bf16 v[86:89], v[156:159], v[212:215], v[86:89]
	v_mfma_f32_16x16x32_bf16 v[78:81], v[164:167], v[212:215], v[78:81]
	s_setprio 0
	s_setprio 1
	v_mfma_f32_16x16x32_bf16 v[114:117], v[168:171], v[184:187], v[114:117]
	v_mfma_f32_16x16x32_bf16 v[106:109], v[176:179], v[184:187], v[106:109]
	v_mfma_f32_16x16x32_bf16 v[98:101], v[168:171], v[192:195], v[98:101]
	v_mfma_f32_16x16x32_bf16 v[90:93], v[176:179], v[192:195], v[90:93]
	v_mfma_f32_16x16x32_bf16 v[82:85], v[168:171], v[200:203], v[82:85]
	v_mfma_f32_16x16x32_bf16 v[74:77], v[176:179], v[200:203], v[74:77]
	v_mfma_f32_16x16x32_bf16 v[70:73], v[168:171], v[208:211], v[70:73]
	v_mfma_f32_16x16x32_bf16 v[66:69], v[176:179], v[208:211], v[66:69]
	v_mfma_f32_16x16x32_bf16 v[114:117], v[172:175], v[188:191], v[114:117]
	v_mfma_f32_16x16x32_bf16 v[106:109], v[180:183], v[188:191], v[106:109]
	v_mfma_f32_16x16x32_bf16 v[98:101], v[172:175], v[196:199], v[98:101]
	v_mfma_f32_16x16x32_bf16 v[90:93], v[180:183], v[196:199], v[90:93]
	v_mfma_f32_16x16x32_bf16 v[82:85], v[172:175], v[204:207], v[82:85]
	v_mfma_f32_16x16x32_bf16 v[74:77], v[180:183], v[204:207], v[74:77]
	v_mfma_f32_16x16x32_bf16 v[70:73], v[172:175], v[212:215], v[70:73]
	v_mfma_f32_16x16x32_bf16 v[66:69], v[180:183], v[212:215], v[66:69]
	s_setprio 0
	s_barrier
; #define PG8_STAGE(bufoff, gbase, voff) do { _Pragma("unroll") for (int _i = 0; _i < 2; ++_i) \
;         __builtin_amdgcn_global_load_lds((const unsigned*)((const char*)(gbase) + (voff)[_i]), (PG8_LAS unsigned*)(lds + (bufoff) + ldsw + _i * 8192), 16, 0, 0); } while (0)
; #define PG8_LDA(dst, b, h) do { _Pragma("unroll") for (int m = 0; m < 4; ++m) _Pragma("unroll") for (int k = 0; k < 2; ++k) dst[m][k] = *(const PG8_LAS bf16x8*)(lds + PG8_SA(b, h) + aoff + m * 2048 + k * 1024); } while (0)
; #define PG8_MMA(ai, bj, At, Bt) do { __builtin_amdgcn_s_setprio(1); _Pragma("unroll") for (int m = 0; m < 4; ++m) _Pragma("unroll") for (int n = 0; n < 2; ++n) _Pragma("unroll") for (int k = 0; k < 2; ++k) \
;         acc[ai][bj][m][n] = __builtin_amdgcn_mfma_f32_16x16x32_bf16(Bt[n][k], At[m][k], acc[ai][bj][m][n], 0, 0, 0); __builtin_amdgcn_s_setprio(0); } while (0)
; #define PG8_WAIT_V(n) asm volatile("s_waitcnt vmcnt(" #n ")" ::: "memory")
; #define PG8_WAIT_L(n) asm volatile("s_waitcnt lgkmcnt(" #n ")" ::: "memory")
; #define PG8_BAR __builtin_amdgcn_s_barrier()
; #define PG8_SCHED __builtin_amdgcn_sched_barrier(0)
; template <class Epi, class Sched, bool ALIGN_EPI = false, bool SP2 = false>
; __device__ __forceinline__ void gemm_phase(PG8_LAS unsigned char* lds, const Gemm g, const Sched& S, const Epi& E) {
;     ...
;         for (int t = 0; t < nt; t += 2) {
;     ...
;             PG8_LDA(At, 1, 1); PG8_STAGE(PG8_SB(1, 0), b3, voffB); PG8_STAGE(PG8_SB(1, 1), b3 + hstep, voffB); PG8_STAGE(PG8_SA(1, 0), a3, voffA);
;             PG8_WAIT_V(8); PG8_WAIT_L(0); PG8_BAR; PG8_MMA(1, 0, At, B0); PG8_MMA(1, 1, At, B1); PG8_BAR; PG8_SCHED;
;     ...
;         if constexpr (ALIGN_EPI) { if (wr == 0) PG8_BAR; }
	s_add_i32 s22, s52, s2
	v_lshl_add_u64 v[216:217], v[216:217], 0, s[8:9]
	s_mov_b32 m0, s22
	ds_read_b128 v[184:187], v151 offset:49152
	ds_read_b128 v[188:191], v151 offset:50176
	ds_read_b128 v[192:195], v151 offset:51200
	ds_read_b128 v[196:199], v151 offset:52224
	ds_read_b128 v[200:203], v151 offset:53248
	ds_read_b128 v[204:207], v151 offset:54272
	ds_read_b128 v[208:211], v151 offset:55296
	ds_read_b128 v[212:215], v151 offset:56320
	global_load_lds_dwordx4 v[216:217], off
	s_add_i32 m0, s22, 0x2000
	s_add_u32 s22, s26, 0x160080
	v_lshl_add_u64 v[216:217], v[218:219], 0, s[8:9]
	s_addc_u32 s23, s27, 0
	s_add_i32 s26, s53, s2
	global_load_lds_dwordx4 v[216:217], off
	s_mov_b32 m0, s26
	s_nop 0
	global_load_lds_dwordx4 v132, s[22:23]
	s_add_i32 m0, s26, 0x2000
	s_nop 0
	global_load_lds_dwordx4 v136, s[22:23]
	v_lshl_add_u64 v[216:217], v[220:221], 0, s[8:9]
	s_mov_b32 m0, s36
	s_nop 0
	global_load_lds_dwordx4 v[216:217], off
	v_lshl_add_u64 v[216:217], v[222:223], 0, s[8:9]
	s_mov_b32 m0, s37
	s_nop 0
	global_load_lds_dwordx4 v[216:217], off
	s_waitcnt vmcnt(8)
	s_waitcnt lgkmcnt(0)
	s_barrier
	s_setprio 1
	s_waitcnt lgkmcnt(0)
	v_mfma_f32_16x16x32_bf16 v[62:65], v[152:155], v[184:187], v[62:65]
	v_mfma_f32_16x16x32_bf16 v[58:61], v[160:163], v[184:187], v[58:61]
	v_mfma_f32_16x16x32_bf16 v[54:57], v[152:155], v[192:195], v[54:57]
	v_mfma_f32_16x16x32_bf16 v[50:53], v[160:163], v[192:195], v[50:53]
	v_mfma_f32_16x16x32_bf16 v[38:41], v[152:155], v[200:203], v[38:41]
	v_mfma_f32_16x16x32_bf16 v[34:37], v[160:163], v[200:203], v[34:37]
	v_mfma_f32_16x16x32_bf16 v[22:25], v[152:155], v[208:211], v[22:25]
	v_mfma_f32_16x16x32_bf16 v[18:21], v[160:163], v[208:211], v[18:21]
	v_mfma_f32_16x16x32_bf16 v[62:65], v[156:159], v[188:191], v[62:65]
	v_mfma_f32_16x16x32_bf16 v[58:61], v[164:167], v[188:191], v[58:61]
	v_mfma_f32_16x16x32_bf16 v[54:57], v[156:159], v[196:199], v[54:57]
	v_mfma_f32_16x16x32_bf16 v[50:53], v[164:167], v[196:199], v[50:53]
	v_mfma_f32_16x16x32_bf16 v[38:41], v[156:159], v[204:207], v[38:41]
	v_mfma_f32_16x16x32_bf16 v[34:37], v[164:167], v[204:207], v[34:37]
	v_mfma_f32_16x16x32_bf16 v[22:25], v[156:159], v[212:215], v[22:25]
	v_mfma_f32_16x16x32_bf16 v[18:21], v[164:167], v[212:215], v[18:21]
	s_setprio 0
	s_setprio 1
	v_mfma_f32_16x16x32_bf16 v[46:49], v[168:171], v[184:187], v[46:49]
	v_mfma_f32_16x16x32_bf16 v[42:45], v[176:179], v[184:187], v[42:45]
	v_mfma_f32_16x16x32_bf16 v[30:33], v[168:171], v[192:195], v[30:33]
	v_mfma_f32_16x16x32_bf16 v[26:29], v[176:179], v[192:195], v[26:29]
	v_mfma_f32_16x16x32_bf16 v[14:17], v[168:171], v[200:203], v[14:17]
	v_mfma_f32_16x16x32_bf16 v[10:13], v[176:179], v[200:203], v[10:13]
	v_mfma_f32_16x16x32_bf16 v[6:9], v[168:171], v[208:211], v[6:9]
	v_mfma_f32_16x16x32_bf16 v[2:5], v[176:179], v[208:211], v[2:5]
	v_mfma_f32_16x16x32_bf16 v[46:49], v[172:175], v[188:191], v[46:49]
	v_mfma_f32_16x16x32_bf16 v[42:45], v[180:183], v[188:191], v[42:45]
	v_mfma_f32_16x16x32_bf16 v[30:33], v[172:175], v[196:199], v[30:33]
	v_mfma_f32_16x16x32_bf16 v[26:29], v[180:183], v[196:199], v[26:29]
	v_mfma_f32_16x16x32_bf16 v[14:17], v[172:175], v[204:207], v[14:17]
	v_mfma_f32_16x16x32_bf16 v[10:13], v[180:183], v[204:207], v[10:13]
	v_mfma_f32_16x16x32_bf16 v[6:9], v[172:175], v[212:215], v[6:9]
	v_mfma_f32_16x16x32_bf16 v[2:5], v[180:183], v[212:215], v[2:5]
	s_setprio 0
	s_barrier
	s_add_i32 s51, s51, 2
	s_add_u32 s48, s48, 0x100
	s_addc_u32 s49, s49, 0
	s_cmpk_gt_u32 s51, 0x55
	s_mov_b64 s[22:23], s[24:25]
	s_cbranch_scc0 .LBB0_2871
	s_and_b64 vcc, exec, s[10:11]
	s_cbranch_vccz .LBB0_2874
	s_barrier
